# GLA prep: counted vmcnt keeps next-item prefetch in flight (was drained by vmcnt(0) right after issue)
# speedup vs baseline: 1.0104x; 1.0027x over previous
.LBB0_370:
	s_cmp_lg_u64 s[96:97], 0
	s_cbranch_scc0 .Lpw0_full
	s_waitcnt vmcnt(17)
	s_branch .Lpw0_done
.Lpw0_full:
	s_waitcnt vmcnt(0)
.Lpw0_done:
	s_and_saveexec_b64 s[58:59], s[0:1]
	ds_write_b128 v192, v[16:19] offset:34816
	s_or_b64 exec, exec, s[58:59]
	s_waitcnt lgkmcnt(0)
	s_barrier
	v_add_u32_e32 v218, 0, v193
	ds_read_b128 v[0:3], v218 offset:34816
	ds_read_b128 v[4:7], v218 offset:34832
	ds_read_b128 v[8:11], v218 offset:34848
	ds_read_b128 v[12:15], v218 offset:34864
	s_ashr_i32 s58, s23, 9
	s_waitcnt lgkmcnt(3)
	v_mov_b32_e32 v146, v0
	s_waitcnt lgkmcnt(2)
	v_mov_b32_e32 v147, v4
	v_mov_b32_e32 v4, v1
	v_pk_mul_f32 v[0:1], v[44:45], v[4:5]
	v_mov_b32_e32 v148, v2
	v_mov_b32_e32 v149, v6
	v_mov_b32_e32 v6, v3
	v_pk_mul_f32 v[2:3], v[130:131], v[4:5]
	v_pk_fma_f32 v[0:1], v[46:47], v[146:147], v[0:1]
	v_pk_fma_f32 v[2:3], v[132:133], v[146:147], v[2:3]
	v_pk_fma_f32 v[0:1], v[48:49], v[148:149], v[0:1]
	v_pk_fma_f32 v[2:3], v[136:137], v[148:149], v[2:3]
	s_waitcnt lgkmcnt(0)
	v_mov_b32_e32 v5, v12
	v_mov_b32_e32 v12, v9
	v_pk_fma_f32 v[0:1], v[54:55], v[6:7], v[0:1]
	v_pk_fma_f32 v[2:3], v[138:139], v[6:7], v[2:3]
	v_mov_b32_e32 v4, v8
	v_pk_mul_f32 v[6:7], v[70:71], v[12:13]
	v_mov_b32_e32 v8, v10
	v_pk_fma_f32 v[6:7], v[68:69], v[4:5], v[6:7]
	v_mov_b32_e32 v9, v14
	v_pk_fma_f32 v[6:7], v[98:99], v[8:9], v[6:7]
	v_mov_b32_e32 v14, v11
	v_add_f32_e32 v0, v128, v0
	v_pk_fma_f32 v[6:7], v[94:95], v[14:15], v[6:7]
	v_add_f32_e32 v0, v0, v1
	v_add_f32_e32 v0, v0, v6
	v_add_f32_e32 v6, v0, v7
	v_pk_mul_f32 v[0:1], v[140:141], v[12:13]
	v_add_f32_e32 v2, v129, v2
	v_pk_fma_f32 v[0:1], v[142:143], v[4:5], v[0:1]
	v_add_f32_e32 v2, v2, v3
	v_pk_fma_f32 v[0:1], v[144:145], v[8:9], v[0:1]
	s_ashr_i32 s59, s58, 31
	v_pk_fma_f32 v[0:1], v[134:135], v[14:15], v[0:1]
	s_bfe_u32 s25, s23, 0x20001
	v_add_f32_e32 v0, v2, v0
	v_add_f32_e32 v3, v0, v1
	v_mul_f32_e64 v1, |v6|, s77
	v_exp_f32_e32 v1, v1
	s_bfe_u32 s66, s23, 0x60003
	s_lshl_b64 s[62:63], s[58:59], 12
	s_lshl_b64 s[58:59], s[58:59], 2
	v_add_f32_e32 v1, 1.0, v1
	v_cmp_gt_f32_e32 vcc, s87, v1
	s_add_u32 s58, s58, s33
	s_addc_u32 s59, s59, 0
	v_cndmask_b32_e64 v2, 0, 32, vcc
	v_ldexp_f32 v1, v1, v2
	v_log_f32_e32 v1, v1
	s_or_b32 s58, s58, s25
	s_lshl_b64 s[64:65], s[58:59], 6
	v_min_f32_e32 v0, 0, v6
	v_mul_f32_e32 v2, 0x3f317217, v1
	v_fma_f32 v2, v1, s20, -v2
	v_fmac_f32_e32 v2, 0x3377d1cf, v1
	v_fmac_f32_e32 v2, 0x3f317217, v1
	v_cmp_lt_f32_e64 s[58:59], |v1|, s21
	v_add_u32_e32 v222, v191, v193
	s_or_b32 s64, s64, s66
	v_cndmask_b32_e64 v1, v1, v2, s[58:59]
	v_cndmask_b32_e32 v2, 0, v200, vcc
	v_sub_f32_e32 v2, v1, v2
	v_min_f32_e32 v1, 0, v3
	v_mul_f32_e64 v3, |v3|, s77
	v_exp_f32_e32 v3, v3
	v_add_u32_e32 v219, 0x4400, v194
	v_add_u32_e32 v220, 0x400, v194
	v_add_u32_e32 v221, 0x4800, v194
	v_add_f32_e32 v3, 1.0, v3
	v_cmp_gt_f32_e32 vcc, s87, v3
	s_nop 1
	v_cndmask_b32_e64 v4, 0, 32, vcc
	v_ldexp_f32 v3, v3, v4
	v_log_f32_e32 v3, v3
	s_nop 0
	v_mul_f32_e32 v4, 0x3f317217, v3
	v_fma_f32 v4, v3, s20, -v4
	v_fmac_f32_e32 v4, 0x3377d1cf, v3
	v_fmac_f32_e32 v4, 0x3f317217, v3
	v_cmp_lt_f32_e64 s[58:59], |v3|, s21
	s_nop 1
	v_cndmask_b32_e64 v3, v3, v4, s[58:59]
	v_cndmask_b32_e32 v4, 0, v200, vcc
	v_sub_f32_e32 v3, v3, v4
	ds_read_b128 v[4:7], v218 offset:34880
	ds_read_b128 v[8:11], v218 offset:34896
	v_pk_add_f32 v[0:1], v[0:1], v[2:3] neg_lo:[0,1] neg_hi:[0,1]
	s_waitcnt lgkmcnt(1)
	v_mov_b32_e32 v12, v4
	s_waitcnt lgkmcnt(0)
	v_mov_b32_e32 v13, v8
	v_mov_b32_e32 v8, v5
	v_pk_mul_f32 v[4:5], v[44:45], v[8:9]
	v_mov_b32_e32 v14, v6
	v_pk_fma_f32 v[4:5], v[46:47], v[12:13], v[4:5]
	v_mov_b32_e32 v15, v10
	v_pk_fma_f32 v[4:5], v[48:49], v[14:15], v[4:5]
	v_mov_b32_e32 v10, v7
	v_pk_fma_f32 v[146:147], v[54:55], v[10:11], v[4:5]
	v_pk_mul_f32 v[4:5], v[130:131], v[8:9]
	s_nop 0
	v_pk_fma_f32 v[4:5], v[132:133], v[12:13], v[4:5]
	s_nop 0
	v_pk_fma_f32 v[4:5], v[136:137], v[14:15], v[4:5]
	s_nop 0
	v_pk_fma_f32 v[12:13], v[138:139], v[10:11], v[4:5]
	ds_read_b128 v[4:7], v218 offset:34912
	ds_read_b128 v[8:11], v218 offset:34928
	s_waitcnt lgkmcnt(1)
	v_mov_b32_e32 v14, v4
	s_waitcnt lgkmcnt(0)
	v_mov_b32_e32 v15, v8
	v_mov_b32_e32 v8, v5
	v_pk_mul_f32 v[4:5], v[70:71], v[8:9]
	v_mov_b32_e32 v148, v6
	v_pk_fma_f32 v[4:5], v[68:69], v[14:15], v[4:5]
	v_mov_b32_e32 v149, v10
	v_pk_fma_f32 v[4:5], v[98:99], v[148:149], v[4:5]
	v_mov_b32_e32 v10, v7
	v_add_f32_e32 v6, v128, v146
	v_pk_fma_f32 v[4:5], v[94:95], v[10:11], v[4:5]
	v_add_f32_e32 v6, v6, v147
	v_add_f32_e32 v4, v6, v4
	v_add_f32_e32 v6, v4, v5
	v_pk_mul_f32 v[4:5], v[140:141], v[8:9]
	v_add_f32_e32 v7, v129, v12
	v_pk_fma_f32 v[4:5], v[142:143], v[14:15], v[4:5]
	v_add_f32_e32 v7, v7, v13
	v_pk_fma_f32 v[4:5], v[144:145], v[148:149], v[4:5]
	s_nop 0
	v_pk_fma_f32 v[4:5], v[134:135], v[10:11], v[4:5]
	s_nop 0
	v_add_f32_e32 v4, v7, v4
	v_add_f32_e32 v7, v4, v5
	v_mul_f32_e64 v5, |v6|, s77
	v_exp_f32_e32 v5, v5
	v_min_f32_e32 v4, 0, v6
	v_add_f32_e32 v5, 1.0, v5
	v_cmp_gt_f32_e32 vcc, s87, v5
	s_nop 1
	v_cndmask_b32_e64 v6, 0, 32, vcc
	v_ldexp_f32 v5, v5, v6
	v_log_f32_e32 v5, v5
	s_nop 0
	v_mul_f32_e32 v6, 0x3f317217, v5
	v_fma_f32 v6, v5, s20, -v6
	v_fmac_f32_e32 v6, 0x3377d1cf, v5
	v_fmac_f32_e32 v6, 0x3f317217, v5
	v_cmp_lt_f32_e64 s[58:59], |v5|, s21
	s_nop 1
	v_cndmask_b32_e64 v5, v5, v6, s[58:59]
	v_cndmask_b32_e32 v6, 0, v200, vcc
	v_sub_f32_e32 v6, v5, v6
	v_min_f32_e32 v5, 0, v7
	v_mul_f32_e64 v7, |v7|, s77
	v_exp_f32_e32 v7, v7
	s_nop 0
	v_add_f32_e32 v7, 1.0, v7
	v_cmp_gt_f32_e32 vcc, s87, v7
	s_nop 1
	v_cndmask_b32_e64 v8, 0, 32, vcc
	v_ldexp_f32 v7, v7, v8
	v_log_f32_e32 v7, v7
	s_nop 0
	v_mul_f32_e32 v8, 0x3f317217, v7
	v_fma_f32 v8, v7, s20, -v8
	v_fmac_f32_e32 v8, 0x3377d1cf, v7
	v_fmac_f32_e32 v8, 0x3f317217, v7
	v_cmp_lt_f32_e64 s[58:59], |v7|, s21
	s_nop 1
	v_cndmask_b32_e64 v7, v7, v8, s[58:59]
	v_cndmask_b32_e32 v8, 0, v200, vcc
	v_sub_f32_e32 v7, v7, v8
	ds_read_b128 v[8:11], v218 offset:34944
	ds_read_b128 v[12:15], v218 offset:34960
	s_waitcnt lgkmcnt(1)
	v_mov_b32_e32 v146, v8
	s_waitcnt lgkmcnt(0)
	v_mov_b32_e32 v147, v12
	v_mov_b32_e32 v12, v9
	v_pk_mul_f32 v[8:9], v[44:45], v[12:13]
	v_mov_b32_e32 v148, v10
	v_pk_fma_f32 v[8:9], v[46:47], v[146:147], v[8:9]
	v_mov_b32_e32 v149, v14
	v_pk_fma_f32 v[8:9], v[48:49], v[148:149], v[8:9]
	v_mov_b32_e32 v14, v11
	v_pk_fma_f32 v[150:151], v[54:55], v[14:15], v[8:9]
	v_pk_mul_f32 v[8:9], v[130:131], v[12:13]
	s_nop 0
	v_pk_fma_f32 v[8:9], v[132:133], v[146:147], v[8:9]
	s_nop 0
	v_pk_fma_f32 v[8:9], v[136:137], v[148:149], v[8:9]
	s_nop 0
	v_pk_fma_f32 v[146:147], v[138:139], v[14:15], v[8:9]
	ds_read_b128 v[8:11], v218 offset:34976
	ds_read_b128 v[12:15], v218 offset:34992
	s_waitcnt lgkmcnt(1)
	v_mov_b32_e32 v148, v8
	s_waitcnt lgkmcnt(0)
	v_mov_b32_e32 v149, v12
	v_mov_b32_e32 v12, v9
	v_pk_mul_f32 v[8:9], v[70:71], v[12:13]
	v_mov_b32_e32 v152, v10
	v_pk_fma_f32 v[8:9], v[68:69], v[148:149], v[8:9]
	v_mov_b32_e32 v153, v14
	v_pk_fma_f32 v[8:9], v[98:99], v[152:153], v[8:9]
	v_mov_b32_e32 v14, v11
	v_add_f32_e32 v10, v128, v150
	v_pk_fma_f32 v[8:9], v[94:95], v[14:15], v[8:9]
	v_add_f32_e32 v10, v10, v151
	v_add_f32_e32 v8, v10, v8
	v_add_f32_e32 v10, v8, v9
	v_pk_mul_f32 v[8:9], v[140:141], v[12:13]
	v_add_f32_e32 v11, v129, v146
	v_pk_fma_f32 v[8:9], v[142:143], v[148:149], v[8:9]
	v_add_f32_e32 v11, v11, v147
	v_pk_fma_f32 v[8:9], v[144:145], v[152:153], v[8:9]
	s_nop 0
	v_pk_fma_f32 v[8:9], v[134:135], v[14:15], v[8:9]
	s_nop 0
	v_add_f32_e32 v8, v11, v8
	v_add_f32_e32 v11, v8, v9
	v_mul_f32_e64 v9, |v10|, s77
	v_exp_f32_e32 v9, v9
	v_min_f32_e32 v8, 0, v10
	v_add_f32_e32 v9, 1.0, v9
	v_cmp_gt_f32_e32 vcc, s87, v9
	s_nop 1
	v_cndmask_b32_e64 v10, 0, 32, vcc
	v_ldexp_f32 v9, v9, v10
	v_log_f32_e32 v9, v9
	s_nop 0
	v_mul_f32_e32 v10, 0x3f317217, v9
	v_fma_f32 v10, v9, s20, -v10
	v_fmac_f32_e32 v10, 0x3377d1cf, v9
	v_fmac_f32_e32 v10, 0x3f317217, v9
	v_cmp_lt_f32_e64 s[58:59], |v9|, s21
	s_nop 1
	v_cndmask_b32_e64 v9, v9, v10, s[58:59]
	v_cndmask_b32_e32 v10, 0, v200, vcc
	v_sub_f32_e32 v10, v9, v10
	v_min_f32_e32 v9, 0, v11
	v_mul_f32_e64 v11, |v11|, s77
	v_exp_f32_e32 v11, v11
	s_nop 0
	v_add_f32_e32 v11, 1.0, v11
	v_cmp_gt_f32_e32 vcc, s87, v11
	s_nop 1
	v_cndmask_b32_e64 v12, 0, 32, vcc
	v_ldexp_f32 v11, v11, v12
	v_log_f32_e32 v11, v11
	s_nop 0
	v_mul_f32_e32 v12, 0x3f317217, v11
	v_fma_f32 v12, v11, s20, -v12
	v_fmac_f32_e32 v12, 0x3377d1cf, v11
	v_fmac_f32_e32 v12, 0x3f317217, v11
	v_cmp_lt_f32_e64 s[58:59], |v11|, s21
	s_nop 1
	v_cndmask_b32_e64 v11, v11, v12, s[58:59]
	v_cndmask_b32_e32 v12, 0, v200, vcc
	v_sub_f32_e32 v11, v11, v12
	ds_read_b128 v[12:15], v218 offset:35008
	ds_read_b128 v[146:149], v218 offset:35024
	s_waitcnt lgkmcnt(1)
	v_mov_b32_e32 v150, v12
	s_waitcnt lgkmcnt(0)
	v_mov_b32_e32 v151, v146
	v_mov_b32_e32 v146, v13
	v_pk_mul_f32 v[12:13], v[44:45], v[146:147]
	v_mov_b32_e32 v152, v14
	v_pk_fma_f32 v[12:13], v[46:47], v[150:151], v[12:13]
	v_mov_b32_e32 v153, v148
	v_pk_fma_f32 v[12:13], v[48:49], v[152:153], v[12:13]
	v_mov_b32_e32 v148, v15
	v_pk_fma_f32 v[154:155], v[54:55], v[148:149], v[12:13]
	v_pk_mul_f32 v[12:13], v[130:131], v[146:147]
	s_nop 0
	v_pk_fma_f32 v[12:13], v[132:133], v[150:151], v[12:13]
	s_nop 0
	v_pk_fma_f32 v[12:13], v[136:137], v[152:153], v[12:13]
	s_nop 0
	v_pk_fma_f32 v[150:151], v[138:139], v[148:149], v[12:13]
	ds_read_b128 v[12:15], v218 offset:35040
	ds_read_b128 v[146:149], v218 offset:35056
	s_waitcnt lgkmcnt(1)
	v_mov_b32_e32 v152, v12
	s_waitcnt lgkmcnt(0)
	v_mov_b32_e32 v153, v146
	v_mov_b32_e32 v146, v13
	v_pk_mul_f32 v[12:13], v[70:71], v[146:147]
	v_mov_b32_e32 v156, v14
	v_pk_fma_f32 v[12:13], v[68:69], v[152:153], v[12:13]
	v_mov_b32_e32 v157, v148
	v_pk_fma_f32 v[12:13], v[98:99], v[156:157], v[12:13]
	v_mov_b32_e32 v148, v15
	v_add_f32_e32 v14, v128, v154
	v_pk_fma_f32 v[12:13], v[94:95], v[148:149], v[12:13]
	v_add_f32_e32 v14, v14, v155
	v_add_f32_e32 v12, v14, v12
	v_add_f32_e32 v14, v12, v13
	v_pk_mul_f32 v[12:13], v[140:141], v[146:147]
	v_add_f32_e32 v15, v129, v150
	v_pk_fma_f32 v[12:13], v[142:143], v[152:153], v[12:13]
	v_add_f32_e32 v15, v15, v151
	v_pk_fma_f32 v[12:13], v[144:145], v[156:157], v[12:13]
	s_nop 0
	v_pk_fma_f32 v[12:13], v[134:135], v[148:149], v[12:13]
	s_nop 0
	v_add_f32_e32 v12, v15, v12
	v_add_f32_e32 v15, v12, v13
	v_mul_f32_e64 v13, |v14|, s77
	v_exp_f32_e32 v13, v13
	v_min_f32_e32 v12, 0, v14
	v_add_f32_e32 v13, 1.0, v13
	v_cmp_gt_f32_e32 vcc, s87, v13
	s_nop 1
	v_cndmask_b32_e64 v14, 0, 32, vcc
	v_ldexp_f32 v13, v13, v14
	v_log_f32_e32 v13, v13
	s_nop 0
	v_mul_f32_e32 v14, 0x3f317217, v13
	v_fma_f32 v14, v13, s20, -v14
	v_fmac_f32_e32 v14, 0x3377d1cf, v13
	v_fmac_f32_e32 v14, 0x3f317217, v13
	v_cmp_lt_f32_e64 s[58:59], |v13|, s21
	s_nop 1
	v_cndmask_b32_e64 v13, v13, v14, s[58:59]
	v_cndmask_b32_e32 v14, 0, v200, vcc
	v_sub_f32_e32 v14, v13, v14
	v_min_f32_e32 v13, 0, v15
	v_mul_f32_e64 v15, |v15|, s77
	v_exp_f32_e32 v15, v15
	s_nop 0
	v_add_f32_e32 v15, 1.0, v15
	v_cmp_gt_f32_e32 vcc, s87, v15
	s_nop 1
	v_cndmask_b32_e64 v146, 0, 32, vcc
	v_ldexp_f32 v15, v15, v146
	v_log_f32_e32 v15, v15
	s_nop 0
	v_mul_f32_e32 v146, 0x3f317217, v15
	v_fma_f32 v146, v15, s20, -v146
	v_fmac_f32_e32 v146, 0x3377d1cf, v15
	v_fmac_f32_e32 v146, 0x3f317217, v15
	v_cmp_lt_f32_e64 s[58:59], |v15|, s21
	s_nop 1
	v_cndmask_b32_e64 v15, v15, v146, s[58:59]
	v_cndmask_b32_e32 v146, 0, v200, vcc
	v_sub_f32_e32 v15, v15, v146
	ds_read_b128 v[146:149], v218 offset:35072
	ds_read_b128 v[150:153], v218 offset:35088
	s_waitcnt lgkmcnt(1)
	v_mov_b32_e32 v154, v146
	s_waitcnt lgkmcnt(0)
	v_mov_b32_e32 v155, v150
	v_mov_b32_e32 v150, v147
	v_pk_mul_f32 v[146:147], v[44:45], v[150:151]
	v_mov_b32_e32 v156, v148
	v_pk_fma_f32 v[146:147], v[46:47], v[154:155], v[146:147]
	v_mov_b32_e32 v157, v152
	v_pk_fma_f32 v[146:147], v[48:49], v[156:157], v[146:147]
	v_mov_b32_e32 v152, v149
	v_pk_fma_f32 v[158:159], v[54:55], v[152:153], v[146:147]
	v_pk_mul_f32 v[146:147], v[130:131], v[150:151]
	s_nop 0
	v_pk_fma_f32 v[146:147], v[132:133], v[154:155], v[146:147]
	s_nop 0
	v_pk_fma_f32 v[146:147], v[136:137], v[156:157], v[146:147]
	s_nop 0
	v_pk_fma_f32 v[154:155], v[138:139], v[152:153], v[146:147]
	ds_read_b128 v[146:149], v218 offset:35104
	ds_read_b128 v[150:153], v218 offset:35120
	s_waitcnt lgkmcnt(1)
	v_mov_b32_e32 v156, v146
	s_waitcnt lgkmcnt(0)
	v_mov_b32_e32 v157, v150
	v_mov_b32_e32 v150, v147
	v_pk_mul_f32 v[146:147], v[70:71], v[150:151]
	v_mov_b32_e32 v160, v148
	v_pk_fma_f32 v[146:147], v[68:69], v[156:157], v[146:147]
	v_mov_b32_e32 v161, v152
	v_pk_fma_f32 v[146:147], v[98:99], v[160:161], v[146:147]
	v_mov_b32_e32 v152, v149
	v_add_f32_e32 v148, v128, v158
	v_pk_fma_f32 v[146:147], v[94:95], v[152:153], v[146:147]
	v_add_f32_e32 v148, v148, v159
	v_add_f32_e32 v146, v148, v146
	v_add_f32_e32 v148, v146, v147
	v_pk_mul_f32 v[146:147], v[140:141], v[150:151]
	v_add_f32_e32 v149, v129, v154
	v_pk_fma_f32 v[146:147], v[142:143], v[156:157], v[146:147]
	v_add_f32_e32 v149, v149, v155
	v_pk_fma_f32 v[146:147], v[144:145], v[160:161], v[146:147]
	s_nop 0
	v_pk_fma_f32 v[146:147], v[134:135], v[152:153], v[146:147]
	s_nop 0
	v_add_f32_e32 v146, v149, v146
	v_add_f32_e32 v149, v146, v147
	v_mul_f32_e64 v147, |v148|, s77
	v_exp_f32_e32 v147, v147
	v_min_f32_e32 v146, 0, v148
	v_add_f32_e32 v147, 1.0, v147
	v_cmp_gt_f32_e32 vcc, s87, v147
	s_nop 1
	v_cndmask_b32_e64 v148, 0, 32, vcc
	v_ldexp_f32 v147, v147, v148
	v_log_f32_e32 v147, v147
	s_nop 0
	v_mul_f32_e32 v148, 0x3f317217, v147
	v_fma_f32 v148, v147, s20, -v148
	v_fmac_f32_e32 v148, 0x3377d1cf, v147
	v_fmac_f32_e32 v148, 0x3f317217, v147
	v_cmp_lt_f32_e64 s[58:59], |v147|, s21
	s_nop 1
	v_cndmask_b32_e64 v147, v147, v148, s[58:59]
	v_cndmask_b32_e32 v148, 0, v200, vcc
	v_sub_f32_e32 v148, v147, v148
	v_min_f32_e32 v147, 0, v149
	v_mul_f32_e64 v149, |v149|, s77
	v_exp_f32_e32 v149, v149
	s_nop 0
	v_add_f32_e32 v149, 1.0, v149
	v_cmp_gt_f32_e32 vcc, s87, v149
	s_nop 1
	v_cndmask_b32_e64 v150, 0, 32, vcc
	v_ldexp_f32 v149, v149, v150
	v_log_f32_e32 v149, v149
	s_nop 0
	v_mul_f32_e32 v150, 0x3f317217, v149
	v_fma_f32 v150, v149, s20, -v150
	v_fmac_f32_e32 v150, 0x3377d1cf, v149
	v_fmac_f32_e32 v150, 0x3f317217, v149
	v_cmp_lt_f32_e64 s[58:59], |v149|, s21
	s_nop 1
	v_cndmask_b32_e64 v149, v149, v150, s[58:59]
	v_cndmask_b32_e32 v150, 0, v200, vcc
	v_sub_f32_e32 v149, v149, v150
	ds_read_b128 v[150:153], v218 offset:35136
	ds_read_b128 v[154:157], v218 offset:35152
	s_waitcnt lgkmcnt(1)
	v_mov_b32_e32 v158, v150
	s_waitcnt lgkmcnt(0)
	v_mov_b32_e32 v159, v154
	v_mov_b32_e32 v154, v151
	v_pk_mul_f32 v[150:151], v[44:45], v[154:155]
	v_mov_b32_e32 v160, v152
	v_pk_fma_f32 v[150:151], v[46:47], v[158:159], v[150:151]
	v_mov_b32_e32 v161, v156
	v_pk_fma_f32 v[150:151], v[48:49], v[160:161], v[150:151]
	v_mov_b32_e32 v156, v153
	v_pk_fma_f32 v[162:163], v[54:55], v[156:157], v[150:151]
	v_pk_mul_f32 v[150:151], v[130:131], v[154:155]
	s_nop 0
	v_pk_fma_f32 v[150:151], v[132:133], v[158:159], v[150:151]
	s_nop 0
	v_pk_fma_f32 v[150:151], v[136:137], v[160:161], v[150:151]
	s_nop 0
	v_pk_fma_f32 v[158:159], v[138:139], v[156:157], v[150:151]
	ds_read_b128 v[150:153], v218 offset:35168
	ds_read_b128 v[154:157], v218 offset:35184
	s_waitcnt lgkmcnt(1)
	v_mov_b32_e32 v160, v150
	s_waitcnt lgkmcnt(0)
	v_mov_b32_e32 v161, v154
	v_mov_b32_e32 v154, v151
	v_pk_mul_f32 v[150:151], v[70:71], v[154:155]
	v_mov_b32_e32 v164, v152
	v_pk_fma_f32 v[150:151], v[68:69], v[160:161], v[150:151]
	v_mov_b32_e32 v165, v156
	v_pk_fma_f32 v[150:151], v[98:99], v[164:165], v[150:151]
	v_mov_b32_e32 v156, v153
	v_add_f32_e32 v152, v128, v162
	v_pk_fma_f32 v[150:151], v[94:95], v[156:157], v[150:151]
	v_add_f32_e32 v152, v152, v163
	v_add_f32_e32 v150, v152, v150
	v_add_f32_e32 v152, v150, v151
	v_pk_mul_f32 v[150:151], v[140:141], v[154:155]
	v_add_f32_e32 v153, v129, v158
	v_pk_fma_f32 v[150:151], v[142:143], v[160:161], v[150:151]
	v_add_f32_e32 v153, v153, v159
	v_pk_fma_f32 v[150:151], v[144:145], v[164:165], v[150:151]
	s_nop 0
	v_pk_fma_f32 v[150:151], v[134:135], v[156:157], v[150:151]
	s_nop 0
	v_add_f32_e32 v150, v153, v150
	v_add_f32_e32 v153, v150, v151
	v_mul_f32_e64 v151, |v152|, s77
	v_exp_f32_e32 v151, v151
	v_min_f32_e32 v150, 0, v152
	v_add_f32_e32 v151, 1.0, v151
	v_cmp_gt_f32_e32 vcc, s87, v151
	s_nop 1
	v_cndmask_b32_e64 v152, 0, 32, vcc
	v_ldexp_f32 v151, v151, v152
	v_log_f32_e32 v151, v151
	s_nop 0
	v_mul_f32_e32 v152, 0x3f317217, v151
	v_fma_f32 v152, v151, s20, -v152
	v_fmac_f32_e32 v152, 0x3377d1cf, v151
	v_fmac_f32_e32 v152, 0x3f317217, v151
	v_cmp_lt_f32_e64 s[58:59], |v151|, s21
	s_nop 1
	v_cndmask_b32_e64 v151, v151, v152, s[58:59]
	v_cndmask_b32_e32 v152, 0, v200, vcc
	v_sub_f32_e32 v152, v151, v152
	v_min_f32_e32 v151, 0, v153
	v_mul_f32_e64 v153, |v153|, s77
	v_exp_f32_e32 v153, v153
	s_nop 0
	v_add_f32_e32 v153, 1.0, v153
	v_cmp_gt_f32_e32 vcc, s87, v153
	s_nop 1
	v_cndmask_b32_e64 v154, 0, 32, vcc
	v_ldexp_f32 v153, v153, v154
	v_log_f32_e32 v153, v153
	s_nop 0
	v_mul_f32_e32 v154, 0x3f317217, v153
	v_fma_f32 v154, v153, s20, -v154
	v_fmac_f32_e32 v154, 0x3377d1cf, v153
	v_fmac_f32_e32 v154, 0x3f317217, v153
	v_cmp_lt_f32_e64 s[58:59], |v153|, s21
	s_nop 1
	v_cndmask_b32_e64 v153, v153, v154, s[58:59]
	v_cndmask_b32_e32 v154, 0, v200, vcc
	v_sub_f32_e32 v153, v153, v154
	ds_read_b128 v[154:157], v218 offset:35200
	ds_read_b128 v[158:161], v218 offset:35216
	s_waitcnt lgkmcnt(1)
	v_mov_b32_e32 v162, v154
	s_waitcnt lgkmcnt(0)
	v_mov_b32_e32 v163, v158
	v_mov_b32_e32 v158, v155
	v_pk_mul_f32 v[154:155], v[44:45], v[158:159]
	v_mov_b32_e32 v164, v156
	v_pk_fma_f32 v[154:155], v[46:47], v[162:163], v[154:155]
	v_mov_b32_e32 v165, v160
	v_pk_fma_f32 v[154:155], v[48:49], v[164:165], v[154:155]
	v_mov_b32_e32 v160, v157
	v_pk_fma_f32 v[166:167], v[54:55], v[160:161], v[154:155]
	v_pk_mul_f32 v[154:155], v[130:131], v[158:159]
	s_nop 0
	v_pk_fma_f32 v[154:155], v[132:133], v[162:163], v[154:155]
	s_nop 0
	v_pk_fma_f32 v[154:155], v[136:137], v[164:165], v[154:155]
	s_nop 0
	v_pk_fma_f32 v[162:163], v[138:139], v[160:161], v[154:155]
	ds_read_b128 v[154:157], v218 offset:35232
	ds_read_b128 v[158:161], v218 offset:35248
	s_waitcnt lgkmcnt(1)
	v_mov_b32_e32 v164, v154
	s_waitcnt lgkmcnt(0)
	v_mov_b32_e32 v165, v158
	v_mov_b32_e32 v158, v155
	v_pk_mul_f32 v[154:155], v[70:71], v[158:159]
	v_mov_b32_e32 v168, v156
	v_pk_fma_f32 v[154:155], v[68:69], v[164:165], v[154:155]
	v_mov_b32_e32 v169, v160
	v_pk_fma_f32 v[154:155], v[98:99], v[168:169], v[154:155]
	v_mov_b32_e32 v160, v157
	v_add_f32_e32 v156, v128, v166
	v_pk_fma_f32 v[154:155], v[94:95], v[160:161], v[154:155]
	v_add_f32_e32 v156, v156, v167
	v_add_f32_e32 v154, v156, v154
	v_add_f32_e32 v156, v154, v155
	v_pk_mul_f32 v[154:155], v[140:141], v[158:159]
	v_add_f32_e32 v157, v129, v162
	v_pk_fma_f32 v[154:155], v[142:143], v[164:165], v[154:155]
	v_add_f32_e32 v157, v157, v163
	v_pk_fma_f32 v[154:155], v[144:145], v[168:169], v[154:155]
	s_nop 0
	v_pk_fma_f32 v[154:155], v[134:135], v[160:161], v[154:155]
	s_nop 0
	v_add_f32_e32 v154, v157, v154
	v_add_f32_e32 v157, v154, v155
	v_mul_f32_e64 v155, |v156|, s77
	v_exp_f32_e32 v155, v155
	v_min_f32_e32 v154, 0, v156
	v_add_f32_e32 v155, 1.0, v155
	v_cmp_gt_f32_e32 vcc, s87, v155
	s_nop 1
	v_cndmask_b32_e64 v156, 0, 32, vcc
	v_ldexp_f32 v155, v155, v156
	v_log_f32_e32 v155, v155
	s_nop 0
	v_mul_f32_e32 v156, 0x3f317217, v155
	v_fma_f32 v156, v155, s20, -v156
	v_fmac_f32_e32 v156, 0x3377d1cf, v155
	v_fmac_f32_e32 v156, 0x3f317217, v155
	v_cmp_lt_f32_e64 s[58:59], |v155|, s21
	s_nop 1
	v_cndmask_b32_e64 v155, v155, v156, s[58:59]
	v_cndmask_b32_e32 v156, 0, v200, vcc
	v_sub_f32_e32 v160, v155, v156
	v_mul_f32_e64 v156, |v157|, s77
	v_exp_f32_e32 v156, v156
	v_min_f32_e32 v155, 0, v157
	v_add_f32_e32 v156, 1.0, v156
	v_cmp_gt_f32_e32 vcc, s87, v156
	s_nop 1
	v_cndmask_b32_e64 v157, 0, 32, vcc
	v_ldexp_f32 v156, v156, v157
	v_log_f32_e32 v156, v156
	s_nop 0
	v_mul_f32_e32 v157, 0x3f317217, v156
	v_fma_f32 v157, v156, s20, -v157
	v_fmac_f32_e32 v157, 0x3377d1cf, v156
	v_fmac_f32_e32 v157, 0x3f317217, v156
	v_cmp_lt_f32_e64 s[58:59], |v156|, s21
	s_nop 1
	v_cndmask_b32_e64 v156, v156, v157, s[58:59]
	v_cndmask_b32_e32 v157, 0, v200, vcc
	v_sub_f32_e32 v161, v156, v157
	ds_read_b128 v[156:159], v218 offset:35264
	ds_read_b128 v[162:165], v218 offset:35280
	s_waitcnt lgkmcnt(1)
	v_mov_b32_e32 v166, v156
	s_waitcnt lgkmcnt(0)
	v_mov_b32_e32 v167, v162
	v_mov_b32_e32 v162, v157
	v_pk_mul_f32 v[156:157], v[44:45], v[162:163]
	v_mov_b32_e32 v168, v158
	v_pk_fma_f32 v[156:157], v[46:47], v[166:167], v[156:157]
	v_mov_b32_e32 v169, v164
	v_pk_fma_f32 v[156:157], v[48:49], v[168:169], v[156:157]
	v_mov_b32_e32 v164, v159
	v_pk_fma_f32 v[170:171], v[54:55], v[164:165], v[156:157]
	v_pk_mul_f32 v[156:157], v[130:131], v[162:163]
	s_nop 0
	v_pk_fma_f32 v[156:157], v[132:133], v[166:167], v[156:157]
	s_nop 0
	v_pk_fma_f32 v[156:157], v[136:137], v[168:169], v[156:157]
	s_nop 0
	v_pk_fma_f32 v[166:167], v[138:139], v[164:165], v[156:157]
	ds_read_b128 v[156:159], v218 offset:35296
	ds_read_b128 v[162:165], v218 offset:35312
	s_waitcnt lgkmcnt(1)
	v_mov_b32_e32 v168, v156
	s_waitcnt lgkmcnt(0)
	v_mov_b32_e32 v169, v162
	v_mov_b32_e32 v162, v157
	v_pk_mul_f32 v[156:157], v[70:71], v[162:163]
	v_mov_b32_e32 v172, v158
	v_pk_fma_f32 v[156:157], v[68:69], v[168:169], v[156:157]
	v_mov_b32_e32 v173, v164
	v_pk_fma_f32 v[156:157], v[98:99], v[172:173], v[156:157]
	v_mov_b32_e32 v164, v159
	v_add_f32_e32 v158, v128, v170
	v_pk_fma_f32 v[156:157], v[94:95], v[164:165], v[156:157]
	v_add_f32_e32 v158, v158, v171
	v_add_f32_e32 v156, v158, v156
	v_add_f32_e32 v158, v156, v157
	v_pk_mul_f32 v[156:157], v[140:141], v[162:163]
	v_add_f32_e32 v159, v129, v166
	v_pk_fma_f32 v[156:157], v[142:143], v[168:169], v[156:157]
	v_add_f32_e32 v159, v159, v167
	v_pk_fma_f32 v[156:157], v[144:145], v[172:173], v[156:157]
	v_pk_fma_f32 v[162:163], v[0:1], s[84:85], 0 op_sel_hi:[1,0,0]
	v_pk_fma_f32 v[156:157], v[134:135], v[164:165], v[156:157]
	v_min_f32_e32 v164, 0, v158
	v_add_f32_e32 v156, v159, v156
	v_add_f32_e32 v156, v156, v157
	v_mul_f32_e64 v157, |v158|, s77
	v_exp_f32_e32 v157, v157
	v_min_f32_e32 v165, 0, v156
	v_mul_f32_e64 v156, |v156|, s77
	v_exp_f32_e32 v156, v156
	v_add_f32_e32 v157, 1.0, v157
	v_cmp_gt_f32_e32 vcc, s87, v157
	v_pk_add_f32 v[0:1], v[4:5], v[6:7] neg_lo:[0,1] neg_hi:[0,1]
	v_add_f32_e32 v156, 1.0, v156
	v_cndmask_b32_e64 v158, 0, 32, vcc
	v_ldexp_f32 v157, v157, v158
	v_log_f32_e32 v157, v157
	s_nop 0
	v_mul_f32_e32 v158, 0x3f317217, v157
	v_fma_f32 v158, v157, s20, -v158
	v_fmac_f32_e32 v158, 0x3377d1cf, v157
	v_fmac_f32_e32 v158, 0x3f317217, v157
	v_cmp_lt_f32_e64 s[58:59], |v157|, s21
	s_nop 1
	v_cndmask_b32_e64 v157, v157, v158, s[58:59]
	v_cndmask_b32_e32 v158, 0, v200, vcc
	v_cmp_gt_f32_e32 vcc, s87, v156
	v_sub_f32_e32 v166, v157, v158
	v_pk_fma_f32 v[158:159], v[0:1], s[84:85], v[162:163] op_sel_hi:[1,0,1]
	v_cndmask_b32_e64 v157, 0, 32, vcc
	v_ldexp_f32 v156, v156, v157
	v_log_f32_e32 v156, v156
	v_pk_add_f32 v[0:1], v[8:9], v[10:11] neg_lo:[0,1] neg_hi:[0,1]
	v_mul_f32_e32 v157, 0x3f317217, v156
	v_fma_f32 v157, v156, s20, -v157
	v_fmac_f32_e32 v157, 0x3377d1cf, v156
	v_fmac_f32_e32 v157, 0x3f317217, v156
	v_cmp_lt_f32_e64 s[58:59], |v156|, s21
	s_nop 1
	v_cndmask_b32_e64 v156, v156, v157, s[58:59]
	v_cndmask_b32_e32 v157, 0, v200, vcc
	v_sub_f32_e32 v167, v156, v157
	v_pk_fma_f32 v[156:157], v[0:1], s[84:85], v[158:159] op_sel_hi:[1,0,1]
	v_pk_add_f32 v[0:1], v[12:13], v[14:15] neg_lo:[0,1] neg_hi:[0,1]
	s_lshl_b32 s58, s66, 6
	v_pk_fma_f32 v[12:13], v[0:1], s[84:85], v[156:157] op_sel_hi:[1,0,1]
	v_pk_add_f32 v[0:1], v[146:147], v[148:149] neg_lo:[0,1] neg_hi:[0,1]
	s_or_b32 s62, s62, s58
	v_pk_fma_f32 v[6:7], v[0:1], s[84:85], v[12:13] op_sel_hi:[1,0,1]
	v_pk_add_f32 v[0:1], v[150:151], v[152:153] neg_lo:[0,1] neg_hi:[0,1]
	s_lshl_b32 s66, s25, 8
	v_pk_fma_f32 v[4:5], v[0:1], s[84:85], v[6:7] op_sel_hi:[1,0,1]
	v_pk_add_f32 v[0:1], v[154:155], v[160:161] neg_lo:[0,1] neg_hi:[0,1]
	v_lshlrev_b32_e32 v152, 16, v65
	v_pk_fma_f32 v[2:3], v[0:1], s[84:85], v[4:5] op_sel_hi:[1,0,1]
	v_pk_add_f32 v[0:1], v[164:165], v[166:167] neg_lo:[0,1] neg_hi:[0,1]
	v_and_b32_e32 v153, 0xffff0000, v65
	v_pk_fma_f32 v[0:1], v[0:1], s[84:85], v[2:3] op_sel_hi:[1,0,1]
	ds_write_b64 v222, v[0:1] offset:38912
	s_waitcnt lgkmcnt(0)
	s_barrier
	ds_read2st64_b64 v[8:11], v191 offset0:76 offset1:77
	s_movk_i32 s25, 0x1000
	s_lshl_b64 s[58:59], s[64:65], 14
	s_waitcnt lgkmcnt(0)
	v_add_f32_e32 v8, 0, v8
	v_add_f32_e32 v9, 0, v9
	v_cndmask_b32_e64 v14, 0, v9, s[56:57]
	v_cndmask_b32_e64 v15, 0, v8, s[56:57]
	v_add_f32_e32 v146, v8, v10
	v_add_f32_e32 v147, v9, v11
	v_add_f32_e32 v8, v10, v15
	v_add_f32_e32 v9, v11, v14
	v_cndmask_b32_e64 v14, v14, v9, s[4:5]
	v_cndmask_b32_e64 v15, v15, v8, s[4:5]
	ds_read2st64_b64 v[8:11], v191 offset0:78 offset1:79
	s_waitcnt lgkmcnt(0)
	v_add_f32_e32 v146, v146, v8
	v_add_f32_e32 v147, v147, v9
	v_add_f32_e32 v8, v8, v15
	v_add_f32_e32 v9, v9, v14
	v_cndmask_b32_e64 v9, v14, v9, s[6:7]
	v_cndmask_b32_e64 v8, v15, v8, s[6:7]
	v_add_f32_e32 v14, v146, v10
	v_add_f32_e32 v15, v147, v11
	v_add_f32_e32 v10, v10, v8
	v_add_f32_e32 v11, v11, v9
	v_cndmask_b32_e64 v146, v9, v11, s[8:9]
	v_cndmask_b32_e64 v147, v8, v10, s[8:9]
	ds_read2st64_b64 v[8:11], v191 offset0:80 offset1:81
	s_waitcnt lgkmcnt(0)
	v_add_f32_e32 v14, v14, v8
	v_add_f32_e32 v15, v15, v9
	v_add_f32_e32 v8, v8, v147
	v_add_f32_e32 v9, v9, v146
	v_cndmask_b32_e64 v9, v146, v9, s[10:11]
	v_cndmask_b32_e64 v8, v147, v8, s[10:11]
	v_add_f32_e32 v14, v14, v10
	v_add_f32_e32 v15, v15, v11
	v_add_f32_e32 v10, v10, v8
	v_add_f32_e32 v11, v11, v9
	v_cndmask_b32_e64 v146, v9, v11, s[12:13]
	v_cndmask_b32_e64 v147, v8, v10, s[12:13]
	ds_read2st64_b64 v[8:11], v191 offset0:82 offset1:83
	s_waitcnt lgkmcnt(0)
	v_add_f32_e32 v14, v14, v8
	v_add_f32_e32 v15, v15, v9
	v_add_f32_e32 v8, v8, v147
	v_add_f32_e32 v9, v9, v146
	v_cndmask_b32_e64 v9, v146, v9, s[14:15]
	v_cndmask_b32_e64 v8, v147, v8, s[14:15]
	v_add_f32_e32 v14, v14, v10
	v_add_f32_e32 v15, v15, v11
	v_add_f32_e32 v10, v10, v8
	v_add_f32_e32 v11, v11, v9
	v_cndmask_b32_e64 v9, v9, v11, s[16:17]
	v_cndmask_b32_e64 v11, v8, v10, s[16:17]
	v_mul_f32_e32 v8, 0x3fb8aa3b, v14
	v_mul_f32_e32 v10, 0x3fb8aa3b, v15
	v_lshl_add_u64 v[14:15], s[62:63], 0, v[122:123]
	v_lshlrev_b64 v[14:15], 10, v[14:15]
	v_lshl_add_u64 v[14:15], s[68:69], 0, v[14:15]
	v_lshl_add_u64 v[14:15], v[14:15], 0, s[66:67]
	v_lshl_add_u64 v[148:149], v[14:15], 0, v[42:43]
	v_add_f32_e32 v14, v162, v11
	v_add_f32_e32 v15, v163, v9
	v_mul_f32_e32 v14, 0x3fb8aa3b, v14
	v_mul_f32_e32 v15, 0x3fb8aa3b, v15
	v_exp_f32_e32 v14, v14
	v_exp_f32_e32 v15, v15
	v_lshlrev_b32_e32 v146, 16, v63
	v_and_b32_e32 v147, 0xffff0000, v63
	v_rcp_f32_e32 v150, v14
	v_rcp_f32_e32 v151, v15
	v_pk_mul_f32 v[146:147], v[146:147], s[86:87] op_sel_hi:[1,0]
	v_exp_f32_e32 v8, v8
	v_pk_mul_f32 v[14:15], v[146:147], v[14:15]
	v_lshlrev_b32_e32 v146, 16, v67
	v_cvt_pk_bf16_f32 v160, v14, v15
	v_pk_mul_f32 v[14:15], v[150:151], v[152:153]
	v_and_b32_e32 v147, 0xffff0000, v67
	v_cvt_pk_bf16_f32 v161, v14, v15
	v_add_f32_e32 v14, v158, v11
	v_add_f32_e32 v15, v159, v9
	v_mul_f32_e32 v14, 0x3fb8aa3b, v14
	v_mul_f32_e32 v15, 0x3fb8aa3b, v15
	v_exp_f32_e32 v14, v14
	v_exp_f32_e32 v15, v15
	v_pk_mul_f32 v[146:147], v[146:147], s[86:87] op_sel_hi:[1,0]
	v_lshlrev_b32_e32 v158, 16, v73
	v_rcp_f32_e32 v154, v14
	v_rcp_f32_e32 v155, v15
	v_and_b32_e32 v159, 0xffff0000, v73
	v_pk_mul_f32 v[14:15], v[146:147], v[14:15]
	v_mov_b32_e32 v146, v150
	v_cvt_pk_bf16_f32 v162, v14, v15
	v_pk_mul_f32 v[14:15], v[154:155], v[158:159]
	v_mov_b32_e32 v147, v154
	v_mov_b32_e32 v154, v151
	v_add_f32_e32 v150, v156, v11
	v_add_f32_e32 v151, v157, v9
	v_mul_f32_e32 v150, 0x3fb8aa3b, v150
	v_mul_f32_e32 v151, 0x3fb8aa3b, v151
	v_exp_f32_e32 v10, v10
	v_exp_f32_e32 v150, v150
	v_exp_f32_e32 v151, v151
	v_cvt_pk_bf16_f32 v163, v14, v15
	v_mov_b32_e32 v14, v152
	v_mov_b32_e32 v15, v158
	v_pk_mul_f32 v[14:15], v[8:9], v[14:15] op_sel_hi:[0,1]
	v_mov_b32_e32 v158, v153
	v_add_f32_e32 v12, v12, v11
	v_add_f32_e32 v13, v13, v9
	v_pk_mul_f32 v[146:147], v[14:15], v[146:147]
	v_pk_mul_f32 v[14:15], v[10:11], v[158:159] op_sel_hi:[0,1]
	v_rcp_f32_e32 v152, v150
	v_rcp_f32_e32 v153, v151
	v_mul_f32_e32 v12, 0x3fb8aa3b, v12
	v_mul_f32_e32 v13, 0x3fb8aa3b, v13
	v_pk_mul_f32 v[14:15], v[14:15], v[154:155]
	v_lshlrev_b32_e32 v154, 16, v75
	v_and_b32_e32 v155, 0xffff0000, v75
	v_exp_f32_e32 v12, v12
	v_exp_f32_e32 v13, v13
	v_pk_mul_f32 v[154:155], v[154:155], s[86:87] op_sel_hi:[1,0]
	v_lshlrev_b32_e32 v156, 16, v77
	v_and_b32_e32 v157, 0xffff0000, v77
	v_pk_mul_f32 v[150:151], v[154:155], v[150:151]
	global_store_dword v[148:149], v160, off
	ds_write2_b32 v194, v160, v162 offset1:68
	v_cvt_pk_bf16_f32 v160, v150, v151
	v_pk_mul_f32 v[150:151], v[152:153], v[156:157]
	ds_write2_b32 v219, v161, v163 offset1:68
	v_cvt_pk_bf16_f32 v161, v150, v151
	v_rcp_f32_e32 v150, v12
	v_rcp_f32_e32 v151, v13
	v_lshlrev_b32_e32 v154, 16, v79
	v_and_b32_e32 v155, 0xffff0000, v79
	v_add_f32_e32 v6, v6, v11
	v_add_f32_e32 v7, v7, v9
	v_pk_mul_f32 v[154:155], v[154:155], s[86:87] op_sel_hi:[1,0]
	v_mul_f32_e32 v6, 0x3fb8aa3b, v6
	v_mul_f32_e32 v7, 0x3fb8aa3b, v7
	v_lshlrev_b32_e32 v158, 16, v81
	v_and_b32_e32 v159, 0xffff0000, v81
	v_pk_mul_f32 v[12:13], v[154:155], v[12:13]
	v_exp_f32_e32 v6, v6
	v_exp_f32_e32 v7, v7
	global_store_dword v[148:149], v162, off offset:1024
	v_cvt_pk_bf16_f32 v162, v12, v13
	v_pk_mul_f32 v[12:13], v[150:151], v[158:159]
	v_mov_b32_e32 v154, v152
	v_cvt_pk_bf16_f32 v163, v12, v13
	v_mov_b32_e32 v12, v156
	v_mov_b32_e32 v13, v158
	v_pk_mul_f32 v[12:13], v[8:9], v[12:13] op_sel_hi:[0,1]
	v_mov_b32_e32 v155, v150
	v_mov_b32_e32 v158, v157
	v_pk_mul_f32 v[12:13], v[12:13], v[154:155]
	v_pk_mul_f32 v[154:155], v[10:11], v[158:159] op_sel_hi:[0,1]
	v_mov_b32_e32 v150, v153
	v_rcp_f32_e32 v152, v6
	v_rcp_f32_e32 v153, v7
	v_add_f32_e32 v4, v4, v11
	v_add_f32_e32 v5, v5, v9
	v_pk_mul_f32 v[150:151], v[154:155], v[150:151]
	v_lshlrev_b32_e32 v154, 16, v83
	v_and_b32_e32 v155, 0xffff0000, v83
	v_mul_f32_e32 v4, 0x3fb8aa3b, v4
	v_mul_f32_e32 v5, 0x3fb8aa3b, v5
	v_pk_mul_f32 v[154:155], v[154:155], s[86:87] op_sel_hi:[1,0]
	v_exp_f32_e32 v4, v4
	v_exp_f32_e32 v5, v5
	v_lshlrev_b32_e32 v156, 16, v85
	v_and_b32_e32 v157, 0xffff0000, v85
	v_pk_mul_f32 v[6:7], v[154:155], v[6:7]
	global_store_dword v[148:149], v160, off offset:2048
	ds_write2_b32 v194, v160, v162 offset0:136 offset1:204
	ds_write2_b32 v219, v161, v163 offset0:136 offset1:204
	v_cvt_pk_bf16_f32 v160, v6, v7
	v_pk_mul_f32 v[6:7], v[152:153], v[156:157]
	global_store_dword v[148:149], v162, off offset:3072
	v_cvt_pk_bf16_f32 v161, v6, v7
	v_add_co_u32_e32 v6, vcc, s25, v148
	v_rcp_f32_e32 v148, v4
	s_nop 0
	v_addc_co_u32_e32 v7, vcc, 0, v149, vcc
	v_rcp_f32_e32 v149, v5
	v_lshlrev_b32_e32 v154, 16, v87
	v_and_b32_e32 v155, 0xffff0000, v87
	v_add_f32_e32 v2, v2, v11
	v_add_f32_e32 v3, v3, v9
	v_pk_mul_f32 v[154:155], v[154:155], s[86:87] op_sel_hi:[1,0]
	v_mul_f32_e32 v2, 0x3fb8aa3b, v2
	v_mul_f32_e32 v3, 0x3fb8aa3b, v3
	v_lshlrev_b32_e32 v158, 16, v89
	v_and_b32_e32 v159, 0xffff0000, v89
	v_pk_mul_f32 v[4:5], v[154:155], v[4:5]
	v_exp_f32_e32 v2, v2
	v_exp_f32_e32 v3, v3
	v_cvt_pk_bf16_f32 v162, v4, v5
	v_pk_mul_f32 v[4:5], v[148:149], v[158:159]
	v_mov_b32_e32 v154, v152
	v_cvt_pk_bf16_f32 v163, v4, v5
	v_mov_b32_e32 v4, v156
	v_mov_b32_e32 v5, v158
	v_pk_mul_f32 v[4:5], v[8:9], v[4:5] op_sel_hi:[0,1]
	v_mov_b32_e32 v155, v148
	v_mov_b32_e32 v158, v157
	v_add_f32_e32 v0, v0, v11
	v_add_f32_e32 v1, v1, v9
	v_pk_mul_f32 v[4:5], v[4:5], v[154:155]
	v_pk_mul_f32 v[154:155], v[10:11], v[158:159] op_sel_hi:[0,1]
	v_mov_b32_e32 v148, v153
	v_rcp_f32_e32 v152, v2
	v_rcp_f32_e32 v153, v3
	v_mul_f32_e32 v0, 0x3fb8aa3b, v0
	v_mul_f32_e32 v1, 0x3fb8aa3b, v1
	v_pk_mul_f32 v[148:149], v[154:155], v[148:149]
	v_lshlrev_b32_e32 v154, 16, v91
	v_and_b32_e32 v155, 0xffff0000, v91
	v_exp_f32_e32 v0, v0
	v_exp_f32_e32 v1, v1
	v_pk_mul_f32 v[154:155], v[154:155], s[86:87] op_sel_hi:[1,0]
	v_lshlrev_b32_e32 v156, 16, v93
	v_and_b32_e32 v157, 0xffff0000, v93
	v_pk_mul_f32 v[2:3], v[154:155], v[2:3]
	global_store_dword v[6:7], v160, off
	ds_write2_b32 v220, v160, v162 offset0:16 offset1:84
	v_cvt_pk_bf16_f32 v160, v2, v3
	v_pk_mul_f32 v[2:3], v[152:153], v[156:157]
	ds_write2_b32 v221, v161, v163 offset0:16 offset1:84
	v_cvt_pk_bf16_f32 v161, v2, v3
	v_rcp_f32_e32 v2, v0
	v_rcp_f32_e32 v3, v1
	v_lshlrev_b32_e32 v154, 16, v97
	v_and_b32_e32 v155, 0xffff0000, v97
	v_pk_mul_f32 v[154:155], v[154:155], s[86:87] op_sel_hi:[1,0]
	v_lshlrev_b32_e32 v158, 16, v101
	v_and_b32_e32 v159, 0xffff0000, v101
	v_pk_mul_f32 v[0:1], v[154:155], v[0:1]
	v_mov_b32_e32 v154, v152
	v_cvt_pk_bf16_f32 v9, v0, v1
	v_pk_mul_f32 v[0:1], v[2:3], v[158:159]
	v_mov_b32_e32 v155, v2
	v_cvt_pk_bf16_f32 v11, v0, v1
	v_mov_b32_e32 v0, v156
	v_mov_b32_e32 v1, v158
	v_pk_mul_f32 v[0:1], v[8:9], v[0:1] op_sel_hi:[0,1]
	v_mov_b32_e32 v158, v157
	v_pk_mul_f32 v[154:155], v[0:1], v[154:155]
	v_pk_mul_f32 v[0:1], v[10:11], v[158:159] op_sel_hi:[0,1]
	v_mov_b32_e32 v2, v153
	global_store_dword v[6:7], v162, off offset:1024
	global_store_dword v[6:7], v160, off offset:2048
	v_pk_mul_f32 v[152:153], v[0:1], v[2:3]
	ds_write2_b32 v220, v160, v9 offset0:152 offset1:220
	ds_write2_b32 v221, v161, v11 offset0:152 offset1:220
	global_store_dword v[6:7], v9, off offset:3072
	v_lshl_add_u64 v[6:7], v[56:57], 0, s[58:59]
	v_cvt_pk_bf16_f32 v0, v146, v147
	v_cvt_pk_bf16_f32 v1, v12, v13
	v_cvt_pk_bf16_f32 v2, v4, v5
	v_cvt_pk_bf16_f32 v3, v154, v155
	global_store_dwordx4 v[6:7], v[0:3], off
	s_nop 1
	v_cvt_pk_bf16_f32 v0, v14, v15
	v_cvt_pk_bf16_f32 v1, v150, v151
	v_cvt_pk_bf16_f32 v2, v148, v149
	v_cvt_pk_bf16_f32 v3, v152, v153
	global_store_dwordx4 v[6:7], v[0:3], off offset:128
	s_and_saveexec_b64 s[58:59], s[18:19]
	s_cbranch_execz .LBB0_374
	s_lshl_b64 s[62:63], s[64:65], 9
	v_lshl_add_u64 v[0:1], v[58:59], 0, s[62:63]
	v_mov_b32_e32 v9, v10
	global_store_dwordx2 v[0:1], v[8:9], off

.Lpw1_done:
	s_and_saveexec_b64 s[58:59], s[0:1]
	s_cbranch_execz .LBB0_390
	s_nop 0
	ds_write_b128 v192, v[20:23] offset:34816
.LBB0_390:
	s_or_b64 exec, exec, s[58:59]
	s_waitcnt lgkmcnt(0)
	s_barrier
	ds_read_b128 v[162:165], v218 offset:34816
	ds_read_b128 v[166:169], v218 offset:34832
	ds_read_b128 v[170:173], v218 offset:34848
	ds_read_b128 v[174:177], v218 offset:34864
	s_ashr_i32 s58, s24, 9
	s_waitcnt lgkmcnt(3)
	v_mov_b32_e32 v178, v162
	s_waitcnt lgkmcnt(2)
	v_mov_b32_e32 v179, v166
	v_mov_b32_e32 v166, v163
	v_pk_mul_f32 v[162:163], v[160:161], v[166:167]
	v_mov_b32_e32 v180, v164
	v_mov_b32_e32 v181, v168
	v_mov_b32_e32 v168, v165
	v_pk_mul_f32 v[164:165], v[152:153], v[166:167]
	v_pk_fma_f32 v[162:163], v[158:159], v[178:179], v[162:163]
	v_pk_fma_f32 v[164:165], v[148:149], v[178:179], v[164:165]
	v_pk_fma_f32 v[162:163], v[156:157], v[180:181], v[162:163]
	v_pk_fma_f32 v[164:165], v[150:151], v[180:181], v[164:165]
	s_waitcnt lgkmcnt(0)
	v_mov_b32_e32 v167, v174
	v_mov_b32_e32 v174, v171
	v_pk_fma_f32 v[162:163], v[154:155], v[168:169], v[162:163]
	v_pk_fma_f32 v[164:165], v[146:147], v[168:169], v[164:165]
	v_mov_b32_e32 v166, v170
	v_pk_mul_f32 v[168:169], v[12:13], v[174:175]
	v_mov_b32_e32 v170, v172
	v_pk_fma_f32 v[168:169], v[10:11], v[166:167], v[168:169]
	v_mov_b32_e32 v171, v176
	v_pk_fma_f32 v[168:169], v[14:15], v[170:171], v[168:169]
	v_mov_b32_e32 v176, v173
	s_nop 0
	v_add_f32_e32 v162, v128, v162
	v_pk_fma_f32 v[168:169], v[8:9], v[176:177], v[168:169]
	v_add_f32_e32 v162, v162, v163
	v_add_f32_e32 v162, v162, v168
	v_add_f32_e32 v168, v162, v169
	v_pk_mul_f32 v[162:163], v[4:5], v[174:175]
	v_add_f32_e32 v164, v129, v164
	v_pk_fma_f32 v[162:163], v[2:3], v[166:167], v[162:163]
	v_add_f32_e32 v164, v164, v165
	v_pk_fma_f32 v[162:163], v[6:7], v[170:171], v[162:163]
	s_ashr_i32 s59, s58, 31
	v_pk_fma_f32 v[162:163], v[0:1], v[176:177], v[162:163]
	s_bfe_u32 s23, s24, 0x20001
	v_add_f32_e32 v162, v164, v162
	v_add_f32_e32 v165, v162, v163
	v_mul_f32_e64 v163, |v168|, s77
	v_exp_f32_e32 v163, v163
	s_bfe_u32 s66, s24, 0x60003
	s_lshl_b64 s[62:63], s[58:59], 12
	s_lshl_b64 s[58:59], s[58:59], 2
	v_add_f32_e32 v163, 1.0, v163
	v_cmp_gt_f32_e32 vcc, s87, v163
	v_readlane_b32 s64, v238, 18
	s_add_u32 s58, s58, s64
	v_cndmask_b32_e64 v164, 0, 32, vcc
	v_ldexp_f32 v163, v163, v164
	v_log_f32_e32 v163, v163
	s_addc_u32 s59, s59, 0
	s_or_b32 s58, s58, s23
	s_lshl_b64 s[64:65], s[58:59], 6
	v_mul_f32_e32 v164, 0x3f317217, v163
	v_fma_f32 v164, v163, s20, -v164
	v_fmac_f32_e32 v164, 0x3377d1cf, v163
	v_fmac_f32_e32 v164, 0x3f317217, v163
	v_cmp_lt_f32_e64 s[58:59], |v163|, s21
	v_min_f32_e32 v162, 0, v168
	s_or_b32 s64, s64, s66
	v_cndmask_b32_e64 v163, v163, v164, s[58:59]
	v_cndmask_b32_e32 v164, 0, v200, vcc
	v_sub_f32_e32 v164, v163, v164
	v_min_f32_e32 v163, 0, v165
	v_mul_f32_e64 v165, |v165|, s77
	v_exp_f32_e32 v165, v165
	s_nop 0
	v_add_f32_e32 v165, 1.0, v165
	v_cmp_gt_f32_e32 vcc, s87, v165
	s_nop 1
	v_cndmask_b32_e64 v166, 0, 32, vcc
	v_ldexp_f32 v165, v165, v166
	v_log_f32_e32 v165, v165
	s_nop 0
	v_mul_f32_e32 v166, 0x3f317217, v165
	v_fma_f32 v166, v165, s20, -v166
	v_fmac_f32_e32 v166, 0x3377d1cf, v165
	v_fmac_f32_e32 v166, 0x3f317217, v165
	v_cmp_lt_f32_e64 s[58:59], |v165|, s21
	s_nop 1
	v_cndmask_b32_e64 v165, v165, v166, s[58:59]
	v_cndmask_b32_e32 v166, 0, v200, vcc
	v_sub_f32_e32 v165, v165, v166
	ds_read_b128 v[166:169], v218 offset:34880
	ds_read_b128 v[170:173], v218 offset:34896
	s_waitcnt lgkmcnt(1)
	v_mov_b32_e32 v174, v166
	s_waitcnt lgkmcnt(0)
	v_mov_b32_e32 v175, v170
	v_mov_b32_e32 v170, v167
	v_pk_mul_f32 v[166:167], v[160:161], v[170:171]
	v_mov_b32_e32 v176, v168
	v_pk_fma_f32 v[166:167], v[158:159], v[174:175], v[166:167]
	v_mov_b32_e32 v177, v172
	v_pk_fma_f32 v[166:167], v[156:157], v[176:177], v[166:167]
	v_mov_b32_e32 v172, v169
	v_pk_fma_f32 v[178:179], v[154:155], v[172:173], v[166:167]
	v_pk_mul_f32 v[166:167], v[152:153], v[170:171]
	s_nop 0
	v_pk_fma_f32 v[166:167], v[148:149], v[174:175], v[166:167]
	s_nop 0
	v_pk_fma_f32 v[166:167], v[150:151], v[176:177], v[166:167]
	s_nop 0
	v_pk_fma_f32 v[174:175], v[146:147], v[172:173], v[166:167]
	ds_read_b128 v[166:169], v218 offset:34912
	ds_read_b128 v[170:173], v218 offset:34928
	s_waitcnt lgkmcnt(1)
	v_mov_b32_e32 v176, v166
	s_waitcnt lgkmcnt(0)
	v_mov_b32_e32 v177, v170
	v_mov_b32_e32 v170, v167
	v_pk_mul_f32 v[166:167], v[12:13], v[170:171]
	v_mov_b32_e32 v180, v168
	v_pk_fma_f32 v[166:167], v[10:11], v[176:177], v[166:167]
	v_mov_b32_e32 v181, v172
	v_pk_fma_f32 v[166:167], v[14:15], v[180:181], v[166:167]
	v_mov_b32_e32 v172, v169
	v_add_f32_e32 v168, v128, v178
	v_pk_fma_f32 v[166:167], v[8:9], v[172:173], v[166:167]
	v_add_f32_e32 v168, v168, v179
	v_add_f32_e32 v166, v168, v166
	v_add_f32_e32 v168, v166, v167
	v_pk_mul_f32 v[166:167], v[4:5], v[170:171]
	v_add_f32_e32 v169, v129, v174
	v_pk_fma_f32 v[166:167], v[2:3], v[176:177], v[166:167]
	v_add_f32_e32 v169, v169, v175
	v_pk_fma_f32 v[166:167], v[6:7], v[180:181], v[166:167]
	s_nop 0
	v_pk_fma_f32 v[166:167], v[0:1], v[172:173], v[166:167]
	s_nop 0
	v_add_f32_e32 v166, v169, v166
	v_add_f32_e32 v169, v166, v167
	v_mul_f32_e64 v167, |v168|, s77
	v_exp_f32_e32 v167, v167
	v_min_f32_e32 v166, 0, v168
	v_add_f32_e32 v167, 1.0, v167
	v_cmp_gt_f32_e32 vcc, s87, v167
	s_nop 1
	v_cndmask_b32_e64 v168, 0, 32, vcc
	v_ldexp_f32 v167, v167, v168
	v_log_f32_e32 v167, v167
	s_nop 0
	v_mul_f32_e32 v168, 0x3f317217, v167
	v_fma_f32 v168, v167, s20, -v168
	v_fmac_f32_e32 v168, 0x3377d1cf, v167
	v_fmac_f32_e32 v168, 0x3f317217, v167
	v_cmp_lt_f32_e64 s[58:59], |v167|, s21
	s_nop 1
	v_cndmask_b32_e64 v167, v167, v168, s[58:59]
	v_cndmask_b32_e32 v168, 0, v200, vcc
	v_sub_f32_e32 v168, v167, v168
	v_min_f32_e32 v167, 0, v169
	v_mul_f32_e64 v169, |v169|, s77
	v_exp_f32_e32 v169, v169
	s_nop 0
	v_add_f32_e32 v169, 1.0, v169
	v_cmp_gt_f32_e32 vcc, s87, v169
	s_nop 1
	v_cndmask_b32_e64 v170, 0, 32, vcc
	v_ldexp_f32 v169, v169, v170
	v_log_f32_e32 v169, v169
	s_nop 0
	v_mul_f32_e32 v170, 0x3f317217, v169
	v_fma_f32 v170, v169, s20, -v170
	v_fmac_f32_e32 v170, 0x3377d1cf, v169
	v_fmac_f32_e32 v170, 0x3f317217, v169
	v_cmp_lt_f32_e64 s[58:59], |v169|, s21
	s_nop 1
	v_cndmask_b32_e64 v169, v169, v170, s[58:59]
	v_cndmask_b32_e32 v170, 0, v200, vcc
	v_sub_f32_e32 v169, v169, v170
	ds_read_b128 v[170:173], v218 offset:34944
	ds_read_b128 v[174:177], v218 offset:34960
	s_waitcnt lgkmcnt(1)
	v_mov_b32_e32 v178, v170
	s_waitcnt lgkmcnt(0)
	v_mov_b32_e32 v179, v174
	v_mov_b32_e32 v174, v171
	v_pk_mul_f32 v[170:171], v[160:161], v[174:175]
	v_mov_b32_e32 v180, v172
	v_pk_fma_f32 v[170:171], v[158:159], v[178:179], v[170:171]
	v_mov_b32_e32 v181, v176
	v_pk_fma_f32 v[170:171], v[156:157], v[180:181], v[170:171]
	v_mov_b32_e32 v176, v173
	v_pk_fma_f32 v[182:183], v[154:155], v[176:177], v[170:171]
	v_pk_mul_f32 v[170:171], v[152:153], v[174:175]
	s_nop 0
	v_pk_fma_f32 v[170:171], v[148:149], v[178:179], v[170:171]
	s_nop 0
	v_pk_fma_f32 v[170:171], v[150:151], v[180:181], v[170:171]
	s_nop 0
	v_pk_fma_f32 v[178:179], v[146:147], v[176:177], v[170:171]
	ds_read_b128 v[170:173], v218 offset:34976
	ds_read_b128 v[174:177], v218 offset:34992
	s_waitcnt lgkmcnt(1)
	v_mov_b32_e32 v180, v170
	s_waitcnt lgkmcnt(0)
	v_mov_b32_e32 v181, v174
	v_mov_b32_e32 v174, v171
	v_pk_mul_f32 v[170:171], v[12:13], v[174:175]
	v_mov_b32_e32 v184, v172
	v_pk_fma_f32 v[170:171], v[10:11], v[180:181], v[170:171]
	v_mov_b32_e32 v185, v176
	v_pk_fma_f32 v[170:171], v[14:15], v[184:185], v[170:171]
	v_mov_b32_e32 v176, v173
	v_add_f32_e32 v172, v128, v182
	v_pk_fma_f32 v[170:171], v[8:9], v[176:177], v[170:171]
	v_add_f32_e32 v172, v172, v183
	v_add_f32_e32 v170, v172, v170
	v_add_f32_e32 v172, v170, v171
	v_pk_mul_f32 v[170:171], v[4:5], v[174:175]
	v_add_f32_e32 v173, v129, v178
	v_pk_fma_f32 v[170:171], v[2:3], v[180:181], v[170:171]
	v_add_f32_e32 v173, v173, v179
	v_pk_fma_f32 v[170:171], v[6:7], v[184:185], v[170:171]
	s_nop 0
	v_pk_fma_f32 v[170:171], v[0:1], v[176:177], v[170:171]
	s_nop 0
	v_add_f32_e32 v170, v173, v170
	v_add_f32_e32 v173, v170, v171
	v_mul_f32_e64 v171, |v172|, s77
	v_exp_f32_e32 v171, v171
	v_min_f32_e32 v170, 0, v172
	v_add_f32_e32 v171, 1.0, v171
	v_cmp_gt_f32_e32 vcc, s87, v171
	s_nop 1
	v_cndmask_b32_e64 v172, 0, 32, vcc
	v_ldexp_f32 v171, v171, v172
	v_log_f32_e32 v171, v171
	s_nop 0
	v_mul_f32_e32 v172, 0x3f317217, v171
	v_fma_f32 v172, v171, s20, -v172
	v_fmac_f32_e32 v172, 0x3377d1cf, v171
	v_fmac_f32_e32 v172, 0x3f317217, v171
	v_cmp_lt_f32_e64 s[58:59], |v171|, s21
	s_nop 1
	v_cndmask_b32_e64 v171, v171, v172, s[58:59]
	v_cndmask_b32_e32 v172, 0, v200, vcc
	v_sub_f32_e32 v172, v171, v172
	v_min_f32_e32 v171, 0, v173
	v_mul_f32_e64 v173, |v173|, s77
	v_exp_f32_e32 v173, v173
	s_nop 0
	v_add_f32_e32 v173, 1.0, v173
	v_cmp_gt_f32_e32 vcc, s87, v173
	s_nop 1
	v_cndmask_b32_e64 v174, 0, 32, vcc
	v_ldexp_f32 v173, v173, v174
	v_log_f32_e32 v173, v173
	s_nop 0
	v_mul_f32_e32 v174, 0x3f317217, v173
	v_fma_f32 v174, v173, s20, -v174
	v_fmac_f32_e32 v174, 0x3377d1cf, v173
	v_fmac_f32_e32 v174, 0x3f317217, v173
	v_cmp_lt_f32_e64 s[58:59], |v173|, s21
	s_nop 1
	v_cndmask_b32_e64 v173, v173, v174, s[58:59]
	v_cndmask_b32_e32 v174, 0, v200, vcc
	v_sub_f32_e32 v173, v173, v174
	ds_read_b128 v[174:177], v218 offset:35008
	ds_read_b128 v[178:181], v218 offset:35024
	s_waitcnt lgkmcnt(1)
	v_mov_b32_e32 v182, v174
	s_waitcnt lgkmcnt(0)
	v_mov_b32_e32 v183, v178
	v_mov_b32_e32 v178, v175
	v_pk_mul_f32 v[174:175], v[160:161], v[178:179]
	v_mov_b32_e32 v184, v176
	v_pk_fma_f32 v[174:175], v[158:159], v[182:183], v[174:175]
	v_mov_b32_e32 v185, v180
	v_pk_fma_f32 v[174:175], v[156:157], v[184:185], v[174:175]
	v_mov_b32_e32 v180, v177
	v_pk_fma_f32 v[186:187], v[154:155], v[180:181], v[174:175]
	v_pk_mul_f32 v[174:175], v[152:153], v[178:179]
	s_nop 0
	v_pk_fma_f32 v[174:175], v[148:149], v[182:183], v[174:175]
	s_nop 0
	v_pk_fma_f32 v[174:175], v[150:151], v[184:185], v[174:175]
	s_nop 0
	v_pk_fma_f32 v[182:183], v[146:147], v[180:181], v[174:175]
	ds_read_b128 v[174:177], v218 offset:35040
	ds_read_b128 v[178:181], v218 offset:35056
	s_waitcnt lgkmcnt(1)
	v_mov_b32_e32 v184, v174
	s_waitcnt lgkmcnt(0)
	v_mov_b32_e32 v185, v178
	v_mov_b32_e32 v178, v175
	v_pk_mul_f32 v[174:175], v[12:13], v[178:179]
	v_mov_b32_e32 v188, v176
	v_pk_fma_f32 v[174:175], v[10:11], v[184:185], v[174:175]
	v_mov_b32_e32 v189, v180
	v_pk_fma_f32 v[174:175], v[14:15], v[188:189], v[174:175]
	v_mov_b32_e32 v180, v177
	v_add_f32_e32 v176, v128, v186
	v_pk_fma_f32 v[174:175], v[8:9], v[180:181], v[174:175]
	v_add_f32_e32 v176, v176, v187
	v_add_f32_e32 v174, v176, v174
	v_add_f32_e32 v176, v174, v175
	v_pk_mul_f32 v[174:175], v[4:5], v[178:179]
	v_add_f32_e32 v177, v129, v182
	v_pk_fma_f32 v[174:175], v[2:3], v[184:185], v[174:175]
	v_add_f32_e32 v177, v177, v183
	v_pk_fma_f32 v[174:175], v[6:7], v[188:189], v[174:175]
	s_nop 0
	v_pk_fma_f32 v[174:175], v[0:1], v[180:181], v[174:175]
	s_nop 0
	v_add_f32_e32 v174, v177, v174
	v_add_f32_e32 v177, v174, v175
	v_mul_f32_e64 v175, |v176|, s77
	v_exp_f32_e32 v175, v175
	v_min_f32_e32 v174, 0, v176
	v_add_f32_e32 v175, 1.0, v175
	v_cmp_gt_f32_e32 vcc, s87, v175
	s_nop 1
	v_cndmask_b32_e64 v176, 0, 32, vcc
	v_ldexp_f32 v175, v175, v176
	v_log_f32_e32 v175, v175
	s_nop 0
	v_mul_f32_e32 v176, 0x3f317217, v175
	v_fma_f32 v176, v175, s20, -v176
	v_fmac_f32_e32 v176, 0x3377d1cf, v175
	v_fmac_f32_e32 v176, 0x3f317217, v175
	v_cmp_lt_f32_e64 s[58:59], |v175|, s21
	s_nop 1
	v_cndmask_b32_e64 v175, v175, v176, s[58:59]
	v_cndmask_b32_e32 v176, 0, v200, vcc
	v_sub_f32_e32 v176, v175, v176
	v_min_f32_e32 v175, 0, v177
	v_mul_f32_e64 v177, |v177|, s77
	v_exp_f32_e32 v177, v177
	s_nop 0
	v_add_f32_e32 v177, 1.0, v177
	v_cmp_gt_f32_e32 vcc, s87, v177
	s_nop 1
	v_cndmask_b32_e64 v178, 0, 32, vcc
	v_ldexp_f32 v177, v177, v178
	v_log_f32_e32 v177, v177
	s_nop 0
	v_mul_f32_e32 v178, 0x3f317217, v177
	v_fma_f32 v178, v177, s20, -v178
	v_fmac_f32_e32 v178, 0x3377d1cf, v177
	v_fmac_f32_e32 v178, 0x3f317217, v177
	v_cmp_lt_f32_e64 s[58:59], |v177|, s21
	s_nop 1
	v_cndmask_b32_e64 v177, v177, v178, s[58:59]
	v_cndmask_b32_e32 v178, 0, v200, vcc
	v_sub_f32_e32 v177, v177, v178
	ds_read_b128 v[178:181], v218 offset:35072
	ds_read_b128 v[182:185], v218 offset:35088
	s_waitcnt lgkmcnt(1)
	v_mov_b32_e32 v186, v178
	s_waitcnt lgkmcnt(0)
	v_mov_b32_e32 v187, v182
	v_mov_b32_e32 v182, v179
	v_pk_mul_f32 v[178:179], v[160:161], v[182:183]
	v_mov_b32_e32 v188, v180
	v_pk_fma_f32 v[178:179], v[158:159], v[186:187], v[178:179]
	v_mov_b32_e32 v189, v184
	v_pk_fma_f32 v[178:179], v[156:157], v[188:189], v[178:179]
	v_mov_b32_e32 v184, v181
	v_pk_fma_f32 v[224:225], v[154:155], v[184:185], v[178:179]
	v_pk_mul_f32 v[178:179], v[152:153], v[182:183]
	s_nop 0
	v_pk_fma_f32 v[178:179], v[148:149], v[186:187], v[178:179]
	s_nop 0
	v_pk_fma_f32 v[178:179], v[150:151], v[188:189], v[178:179]
	s_nop 0
	v_pk_fma_f32 v[186:187], v[146:147], v[184:185], v[178:179]
	ds_read_b128 v[178:181], v218 offset:35104
	ds_read_b128 v[182:185], v218 offset:35120
	s_waitcnt lgkmcnt(1)
	v_mov_b32_e32 v188, v178
	s_waitcnt lgkmcnt(0)
	v_mov_b32_e32 v189, v182
	v_mov_b32_e32 v182, v179
	v_pk_mul_f32 v[178:179], v[12:13], v[182:183]
	v_mov_b32_e32 v226, v180
	v_pk_fma_f32 v[178:179], v[10:11], v[188:189], v[178:179]
	v_mov_b32_e32 v227, v184
	v_pk_fma_f32 v[178:179], v[14:15], v[226:227], v[178:179]
	v_mov_b32_e32 v184, v181
	v_add_f32_e32 v180, v128, v224
	v_pk_fma_f32 v[178:179], v[8:9], v[184:185], v[178:179]
	v_add_f32_e32 v180, v180, v225
	v_add_f32_e32 v178, v180, v178
	v_add_f32_e32 v180, v178, v179
	v_pk_mul_f32 v[178:179], v[4:5], v[182:183]
	v_add_f32_e32 v181, v129, v186
	v_pk_fma_f32 v[178:179], v[2:3], v[188:189], v[178:179]
	v_add_f32_e32 v181, v181, v187
	v_pk_fma_f32 v[178:179], v[6:7], v[226:227], v[178:179]
	s_nop 0
	v_pk_fma_f32 v[178:179], v[0:1], v[184:185], v[178:179]
	s_nop 0
	v_add_f32_e32 v178, v181, v178
	v_add_f32_e32 v181, v178, v179
	v_mul_f32_e64 v179, |v180|, s77
	v_exp_f32_e32 v179, v179
	v_min_f32_e32 v178, 0, v180
	v_add_f32_e32 v179, 1.0, v179
	v_cmp_gt_f32_e32 vcc, s87, v179
	s_nop 1
	v_cndmask_b32_e64 v180, 0, 32, vcc
	v_ldexp_f32 v179, v179, v180
	v_log_f32_e32 v179, v179
	s_nop 0
	v_mul_f32_e32 v180, 0x3f317217, v179
	v_fma_f32 v180, v179, s20, -v180
	v_fmac_f32_e32 v180, 0x3377d1cf, v179
	v_fmac_f32_e32 v180, 0x3f317217, v179
	v_cmp_lt_f32_e64 s[58:59], |v179|, s21
	s_nop 1
	v_cndmask_b32_e64 v179, v179, v180, s[58:59]
	v_cndmask_b32_e32 v180, 0, v200, vcc
	v_sub_f32_e32 v180, v179, v180
	v_min_f32_e32 v179, 0, v181
	v_mul_f32_e64 v181, |v181|, s77
	v_exp_f32_e32 v181, v181
	s_nop 0
	v_add_f32_e32 v181, 1.0, v181
	v_cmp_gt_f32_e32 vcc, s87, v181
	s_nop 1
	v_cndmask_b32_e64 v182, 0, 32, vcc
	v_ldexp_f32 v181, v181, v182
	v_log_f32_e32 v181, v181
	s_nop 0
	v_mul_f32_e32 v182, 0x3f317217, v181
	v_fma_f32 v182, v181, s20, -v182
	v_fmac_f32_e32 v182, 0x3377d1cf, v181
	v_fmac_f32_e32 v182, 0x3f317217, v181
	v_cmp_lt_f32_e64 s[58:59], |v181|, s21
	s_nop 1
	v_cndmask_b32_e64 v181, v181, v182, s[58:59]
	v_cndmask_b32_e32 v182, 0, v200, vcc
	v_sub_f32_e32 v181, v181, v182
	ds_read_b128 v[182:185], v218 offset:35136
	ds_read_b128 v[186:189], v218 offset:35152
	s_waitcnt lgkmcnt(1)
	v_mov_b32_e32 v224, v182
	s_waitcnt lgkmcnt(0)
	v_mov_b32_e32 v225, v186
	v_mov_b32_e32 v186, v183
	v_pk_mul_f32 v[182:183], v[160:161], v[186:187]
	v_mov_b32_e32 v226, v184
	v_pk_fma_f32 v[182:183], v[158:159], v[224:225], v[182:183]
	v_mov_b32_e32 v227, v188
	v_pk_fma_f32 v[182:183], v[156:157], v[226:227], v[182:183]
	v_mov_b32_e32 v188, v185
	v_pk_fma_f32 v[228:229], v[154:155], v[188:189], v[182:183]
	v_pk_mul_f32 v[182:183], v[152:153], v[186:187]
	s_nop 0
	v_pk_fma_f32 v[182:183], v[148:149], v[224:225], v[182:183]
	s_nop 0
	v_pk_fma_f32 v[182:183], v[150:151], v[226:227], v[182:183]
	s_nop 0
	v_pk_fma_f32 v[224:225], v[146:147], v[188:189], v[182:183]
	ds_read_b128 v[182:185], v218 offset:35168
	ds_read_b128 v[186:189], v218 offset:35184
	s_waitcnt lgkmcnt(1)
	v_mov_b32_e32 v226, v182
	s_waitcnt lgkmcnt(0)
	v_mov_b32_e32 v227, v186
	v_mov_b32_e32 v186, v183
	v_pk_mul_f32 v[182:183], v[12:13], v[186:187]
	v_mov_b32_e32 v230, v184
	v_pk_fma_f32 v[182:183], v[10:11], v[226:227], v[182:183]
	v_mov_b32_e32 v231, v188
	v_pk_fma_f32 v[182:183], v[14:15], v[230:231], v[182:183]
	v_mov_b32_e32 v188, v185
	v_add_f32_e32 v184, v128, v228
	v_pk_fma_f32 v[182:183], v[8:9], v[188:189], v[182:183]
	v_add_f32_e32 v184, v184, v229
	v_add_f32_e32 v182, v184, v182
	v_add_f32_e32 v184, v182, v183
	v_pk_mul_f32 v[182:183], v[4:5], v[186:187]
	v_add_f32_e32 v185, v129, v224
	v_pk_fma_f32 v[182:183], v[2:3], v[226:227], v[182:183]
	v_add_f32_e32 v185, v185, v225
	v_pk_fma_f32 v[182:183], v[6:7], v[230:231], v[182:183]
	s_nop 0
	v_pk_fma_f32 v[182:183], v[0:1], v[188:189], v[182:183]
	s_nop 0
	v_add_f32_e32 v182, v185, v182
	v_add_f32_e32 v185, v182, v183
	v_mul_f32_e64 v183, |v184|, s77
	v_exp_f32_e32 v183, v183
	v_min_f32_e32 v182, 0, v184
	v_add_f32_e32 v183, 1.0, v183
	v_cmp_gt_f32_e32 vcc, s87, v183
	s_nop 1
	v_cndmask_b32_e64 v184, 0, 32, vcc
	v_ldexp_f32 v183, v183, v184
	v_log_f32_e32 v183, v183
	s_nop 0
	v_mul_f32_e32 v184, 0x3f317217, v183
	v_fma_f32 v184, v183, s20, -v184
	v_fmac_f32_e32 v184, 0x3377d1cf, v183
	v_fmac_f32_e32 v184, 0x3f317217, v183
	v_cmp_lt_f32_e64 s[58:59], |v183|, s21
	s_nop 1
	v_cndmask_b32_e64 v183, v183, v184, s[58:59]
	v_cndmask_b32_e32 v184, 0, v200, vcc
	v_sub_f32_e32 v184, v183, v184
	v_min_f32_e32 v183, 0, v185
	v_mul_f32_e64 v185, |v185|, s77
	v_exp_f32_e32 v185, v185
	s_nop 0
	v_add_f32_e32 v185, 1.0, v185
	v_cmp_gt_f32_e32 vcc, s87, v185
	s_nop 1
	v_cndmask_b32_e64 v186, 0, 32, vcc
	v_ldexp_f32 v185, v185, v186
	v_log_f32_e32 v185, v185
	s_nop 0
	v_mul_f32_e32 v186, 0x3f317217, v185
	v_fma_f32 v186, v185, s20, -v186
	v_fmac_f32_e32 v186, 0x3377d1cf, v185
	v_fmac_f32_e32 v186, 0x3f317217, v185
	v_cmp_lt_f32_e64 s[58:59], |v185|, s21
	s_nop 1
	v_cndmask_b32_e64 v185, v185, v186, s[58:59]
	v_cndmask_b32_e32 v186, 0, v200, vcc
	v_sub_f32_e32 v185, v185, v186
	ds_read_b128 v[186:189], v218 offset:35200
	ds_read_b128 v[224:227], v218 offset:35216
	s_waitcnt lgkmcnt(1)
	v_mov_b32_e32 v228, v186
	s_waitcnt lgkmcnt(0)
	v_mov_b32_e32 v229, v224
	v_mov_b32_e32 v224, v187
	v_pk_mul_f32 v[186:187], v[160:161], v[224:225]
	v_mov_b32_e32 v230, v188
	v_pk_fma_f32 v[186:187], v[158:159], v[228:229], v[186:187]
	v_mov_b32_e32 v231, v226
	v_pk_fma_f32 v[186:187], v[156:157], v[230:231], v[186:187]
	v_mov_b32_e32 v226, v189
	v_pk_fma_f32 v[232:233], v[154:155], v[226:227], v[186:187]
	v_pk_mul_f32 v[186:187], v[152:153], v[224:225]
	s_nop 0
	v_pk_fma_f32 v[186:187], v[148:149], v[228:229], v[186:187]
	s_nop 0
	v_pk_fma_f32 v[186:187], v[150:151], v[230:231], v[186:187]
	s_nop 0
	v_pk_fma_f32 v[228:229], v[146:147], v[226:227], v[186:187]
	ds_read_b128 v[186:189], v218 offset:35232
	ds_read_b128 v[224:227], v218 offset:35248
	s_waitcnt lgkmcnt(1)
	v_mov_b32_e32 v230, v186
	s_waitcnt lgkmcnt(0)
	v_mov_b32_e32 v231, v224
	v_mov_b32_e32 v224, v187
	v_pk_mul_f32 v[186:187], v[12:13], v[224:225]
	v_mov_b32_e32 v234, v188
	v_pk_fma_f32 v[186:187], v[10:11], v[230:231], v[186:187]
	v_mov_b32_e32 v235, v226
	v_pk_fma_f32 v[186:187], v[14:15], v[234:235], v[186:187]
	v_mov_b32_e32 v226, v189
	v_add_f32_e32 v188, v128, v232
	v_pk_fma_f32 v[186:187], v[8:9], v[226:227], v[186:187]
	v_add_f32_e32 v188, v188, v233
	v_add_f32_e32 v186, v188, v186
	v_add_f32_e32 v188, v186, v187
	v_pk_mul_f32 v[186:187], v[4:5], v[224:225]
	v_add_f32_e32 v189, v129, v228
	v_pk_fma_f32 v[186:187], v[2:3], v[230:231], v[186:187]
	v_add_f32_e32 v189, v189, v229
	v_pk_fma_f32 v[186:187], v[6:7], v[234:235], v[186:187]
	s_nop 0
	v_pk_fma_f32 v[186:187], v[0:1], v[226:227], v[186:187]
	ds_read_b128 v[224:227], v218 offset:35264
	ds_read_b128 v[228:231], v218 offset:35280
	v_add_f32_e32 v186, v189, v186
	v_add_f32_e32 v189, v186, v187
	v_mul_f32_e64 v187, |v188|, s77
	v_exp_f32_e32 v187, v187
	v_min_f32_e32 v186, 0, v188
	s_waitcnt lgkmcnt(0)
	v_mov_b32_e32 v233, v228
	v_mov_b32_e32 v228, v225
	v_add_f32_e32 v187, 1.0, v187
	v_cmp_gt_f32_e32 vcc, s87, v187
	v_mov_b32_e32 v232, v224
	v_pk_mul_f32 v[160:161], v[160:161], v[228:229]
	v_cndmask_b32_e64 v188, 0, 32, vcc
	v_ldexp_f32 v187, v187, v188
	v_log_f32_e32 v187, v187
	v_pk_mul_f32 v[152:153], v[152:153], v[228:229]
	v_pk_fma_f32 v[158:159], v[158:159], v[232:233], v[160:161]
	v_mov_b32_e32 v160, v226
	v_mul_f32_e32 v188, 0x3f317217, v187
	v_fma_f32 v188, v187, s20, -v188
	v_mov_b32_e32 v161, v230
	v_pk_fma_f32 v[148:149], v[148:149], v[232:233], v[152:153]
	v_fmac_f32_e32 v188, 0x3377d1cf, v187
	v_pk_fma_f32 v[156:157], v[156:157], v[160:161], v[158:159]
	v_mov_b32_e32 v230, v227
	v_pk_fma_f32 v[148:149], v[150:151], v[160:161], v[148:149]
	v_fmac_f32_e32 v188, 0x3f317217, v187
	v_cmp_lt_f32_e64 s[58:59], |v187|, s21
	v_pk_fma_f32 v[154:155], v[154:155], v[230:231], v[156:157]
	v_pk_fma_f32 v[156:157], v[146:147], v[230:231], v[148:149]
	ds_read_b128 v[146:149], v218 offset:35296
	ds_read_b128 v[150:153], v218 offset:35312
	v_cndmask_b32_e64 v187, v187, v188, s[58:59]
	v_cndmask_b32_e32 v188, 0, v200, vcc
	v_sub_f32_e32 v188, v187, v188
	v_min_f32_e32 v187, 0, v189
	v_mul_f32_e64 v189, |v189|, s77
	v_exp_f32_e32 v189, v189
	s_waitcnt lgkmcnt(0)
	v_mov_b32_e32 v159, v150
	v_mov_b32_e32 v150, v147
	v_mov_b32_e32 v158, v146
	v_pk_mul_f32 v[12:13], v[12:13], v[150:151]
	v_add_f32_e32 v189, 1.0, v189
	v_pk_fma_f32 v[10:11], v[10:11], v[158:159], v[12:13]
	v_mov_b32_e32 v12, v148
	v_mov_b32_e32 v13, v152
	v_pk_mul_f32 v[4:5], v[4:5], v[150:151]
	v_cmp_gt_f32_e32 vcc, s87, v189
	v_pk_fma_f32 v[10:11], v[14:15], v[12:13], v[10:11]
	v_mov_b32_e32 v152, v149
	v_pk_fma_f32 v[2:3], v[2:3], v[158:159], v[4:5]
	v_cndmask_b32_e64 v223, 0, 32, vcc
	v_pk_fma_f32 v[8:9], v[8:9], v[152:153], v[10:11]
	v_add_f32_e32 v10, v128, v154
	v_pk_fma_f32 v[2:3], v[6:7], v[12:13], v[2:3]
	v_ldexp_f32 v189, v189, v223
	v_add_f32_e32 v10, v10, v155
	v_pk_fma_f32 v[0:1], v[0:1], v[152:153], v[2:3]
	v_add_f32_e32 v2, v129, v156
	v_log_f32_e32 v189, v189
	v_add_f32_e32 v8, v10, v8
	v_add_f32_e32 v2, v2, v157
	v_add_f32_e32 v8, v8, v9
	v_add_f32_e32 v0, v2, v0
	v_add_f32_e32 v2, v0, v1
	v_mul_f32_e64 v1, |v8|, s77
	v_exp_f32_e32 v1, v1
	v_mul_f32_e32 v223, 0x3f317217, v189
	v_fma_f32 v223, v189, s20, -v223
	v_fmac_f32_e32 v223, 0x3377d1cf, v189
	v_fmac_f32_e32 v223, 0x3f317217, v189
	v_cmp_lt_f32_e64 s[58:59], |v189|, s21
	v_add_f32_e32 v1, 1.0, v1
	v_min_f32_e32 v0, 0, v8
	v_cndmask_b32_e64 v189, v189, v223, s[58:59]
	v_cndmask_b32_e32 v223, 0, v200, vcc
	v_cmp_gt_f32_e32 vcc, s87, v1
	v_sub_f32_e32 v189, v189, v223
	v_lshlrev_b32_e32 v154, 16, v202
	v_cndmask_b32_e64 v3, 0, 32, vcc
	v_ldexp_f32 v1, v1, v3
	v_log_f32_e32 v1, v1
	v_and_b32_e32 v155, 0xffff0000, v202
	v_pk_mul_f32 v[154:155], v[154:155], s[86:87] op_sel_hi:[1,0]
	v_lshlrev_b32_e32 v156, 16, v201
	v_mul_f32_e32 v3, 0x3f317217, v1
	v_fma_f32 v3, v1, s20, -v3
	v_fmac_f32_e32 v3, 0x3377d1cf, v1
	v_fmac_f32_e32 v3, 0x3f317217, v1
	v_cmp_lt_f32_e64 s[58:59], |v1|, s21
	v_and_b32_e32 v157, 0xffff0000, v201
	v_lshlrev_b32_e32 v158, 16, v203
	v_cndmask_b32_e64 v1, v1, v3, s[58:59]
	v_cndmask_b32_e32 v3, 0, v200, vcc
	v_sub_f32_e32 v8, v1, v3
	v_min_f32_e32 v1, 0, v2
	v_mul_f32_e64 v2, |v2|, s77
	v_exp_f32_e32 v2, v2
	v_and_b32_e32 v159, 0xffff0000, v203
	v_add_f32_e32 v2, 1.0, v2
	v_cmp_gt_f32_e32 vcc, s87, v2
	s_nop 1
	v_cndmask_b32_e64 v3, 0, 32, vcc
	v_ldexp_f32 v2, v2, v3
	v_log_f32_e32 v2, v2
	s_nop 0
	v_mul_f32_e32 v3, 0x3f317217, v2
	v_fma_f32 v3, v2, s20, -v3
	v_fmac_f32_e32 v3, 0x3377d1cf, v2
	v_fmac_f32_e32 v3, 0x3f317217, v2
	v_cmp_lt_f32_e64 s[58:59], |v2|, s21
	s_nop 1
	v_cndmask_b32_e64 v2, v2, v3, s[58:59]
	v_cndmask_b32_e32 v3, 0, v200, vcc
	v_sub_f32_e32 v9, v2, v3
	v_pk_add_f32 v[2:3], v[162:163], v[164:165] neg_lo:[0,1] neg_hi:[0,1]
	v_pk_add_f32 v[0:1], v[0:1], v[8:9] neg_lo:[0,1] neg_hi:[0,1]
	v_pk_fma_f32 v[148:149], v[2:3], s[84:85], 0 op_sel_hi:[1,0,0]
	v_pk_add_f32 v[2:3], v[166:167], v[168:169] neg_lo:[0,1] neg_hi:[0,1]
	s_lshl_b32 s58, s66, 6
	v_pk_fma_f32 v[146:147], v[2:3], s[84:85], v[148:149] op_sel_hi:[1,0,1]
	v_pk_add_f32 v[2:3], v[170:171], v[172:173] neg_lo:[0,1] neg_hi:[0,1]
	s_or_b32 s62, s62, s58
	v_pk_fma_f32 v[14:15], v[2:3], s[84:85], v[146:147] op_sel_hi:[1,0,1]
	v_pk_add_f32 v[2:3], v[174:175], v[176:177] neg_lo:[0,1] neg_hi:[0,1]
	s_lshl_b32 s66, s23, 8
	v_pk_fma_f32 v[12:13], v[2:3], s[84:85], v[14:15] op_sel_hi:[1,0,1]
	v_pk_add_f32 v[2:3], v[178:179], v[180:181] neg_lo:[0,1] neg_hi:[0,1]
	s_movk_i32 s23, 0x1000
	v_pk_fma_f32 v[6:7], v[2:3], s[84:85], v[12:13] op_sel_hi:[1,0,1]
	v_pk_add_f32 v[2:3], v[182:183], v[184:185] neg_lo:[0,1] neg_hi:[0,1]
	s_lshl_b64 s[58:59], s[64:65], 14
	v_pk_fma_f32 v[4:5], v[2:3], s[84:85], v[6:7] op_sel_hi:[1,0,1]
	v_pk_add_f32 v[2:3], v[186:187], v[188:189] neg_lo:[0,1] neg_hi:[0,1]
	s_nop 0
	v_pk_fma_f32 v[2:3], v[2:3], s[84:85], v[4:5] op_sel_hi:[1,0,1]
	s_nop 0
	v_pk_fma_f32 v[0:1], v[0:1], s[84:85], v[2:3] op_sel_hi:[1,0,1]
	ds_write_b64 v222, v[0:1] offset:38912
	s_waitcnt lgkmcnt(0)
	s_barrier
	ds_read2st64_b64 v[8:11], v191 offset0:76 offset1:77
	s_waitcnt lgkmcnt(0)
	v_add_f32_e32 v8, 0, v8
	v_add_f32_e32 v9, 0, v9
	v_cndmask_b32_e64 v150, 0, v9, s[56:57]
	v_cndmask_b32_e64 v151, 0, v8, s[56:57]
	v_add_f32_e32 v152, v8, v10
	v_add_f32_e32 v153, v9, v11
	v_add_f32_e32 v8, v10, v151
	v_add_f32_e32 v9, v11, v150
	v_cndmask_b32_e64 v150, v150, v9, s[4:5]
	v_cndmask_b32_e64 v151, v151, v8, s[4:5]
	ds_read2st64_b64 v[8:11], v191 offset0:78 offset1:79
	s_waitcnt lgkmcnt(0)
	v_add_f32_e32 v152, v152, v8
	v_add_f32_e32 v153, v153, v9
	v_add_f32_e32 v8, v8, v151
	v_add_f32_e32 v9, v9, v150
	v_cndmask_b32_e64 v9, v150, v9, s[6:7]
	v_cndmask_b32_e64 v8, v151, v8, s[6:7]
	v_add_f32_e32 v150, v152, v10
	v_add_f32_e32 v151, v153, v11
	v_add_f32_e32 v10, v10, v8
	v_add_f32_e32 v11, v11, v9
	v_cndmask_b32_e64 v152, v9, v11, s[8:9]
	v_cndmask_b32_e64 v153, v8, v10, s[8:9]
	ds_read2st64_b64 v[8:11], v191 offset0:80 offset1:81
	s_waitcnt lgkmcnt(0)
	v_add_f32_e32 v150, v150, v8
	v_add_f32_e32 v151, v151, v9
	v_add_f32_e32 v8, v8, v153
	v_add_f32_e32 v9, v9, v152
	v_cndmask_b32_e64 v9, v152, v9, s[10:11]
	v_cndmask_b32_e64 v8, v153, v8, s[10:11]
	v_add_f32_e32 v150, v150, v10
	v_add_f32_e32 v151, v151, v11
	v_add_f32_e32 v10, v10, v8
	v_add_f32_e32 v11, v11, v9
	v_cndmask_b32_e64 v152, v9, v11, s[12:13]
	v_cndmask_b32_e64 v153, v8, v10, s[12:13]
	ds_read2st64_b64 v[8:11], v191 offset0:82 offset1:83
	s_waitcnt lgkmcnt(0)
	v_add_f32_e32 v150, v150, v8
	v_add_f32_e32 v151, v151, v9
	v_add_f32_e32 v8, v8, v153
	v_add_f32_e32 v9, v9, v152
	v_cndmask_b32_e64 v9, v152, v9, s[14:15]
	v_cndmask_b32_e64 v8, v153, v8, s[14:15]
	v_add_f32_e32 v150, v150, v10
	v_add_f32_e32 v151, v151, v11
	v_add_f32_e32 v10, v10, v8
	v_add_f32_e32 v11, v11, v9
	v_cndmask_b32_e64 v9, v9, v11, s[16:17]
	v_cndmask_b32_e64 v11, v8, v10, s[16:17]
	v_add_f32_e32 v148, v148, v11
	v_add_f32_e32 v149, v149, v9
	v_mul_f32_e32 v148, 0x3fb8aa3b, v148
	v_mul_f32_e32 v149, 0x3fb8aa3b, v149
	v_exp_f32_e32 v148, v148
	v_exp_f32_e32 v149, v149
	v_add_f32_e32 v146, v146, v11
	v_add_f32_e32 v147, v147, v9
	v_mul_f32_e32 v146, 0x3fb8aa3b, v146
	v_mul_f32_e32 v147, 0x3fb8aa3b, v147
	v_rcp_f32_e32 v152, v148
	v_rcp_f32_e32 v153, v149
	v_exp_f32_e32 v146, v146
	v_exp_f32_e32 v147, v147
	v_pk_mul_f32 v[148:149], v[154:155], v[148:149]
	v_mul_f32_e32 v8, 0x3fb8aa3b, v150
	v_cvt_pk_bf16_f32 v160, v148, v149
	v_pk_mul_f32 v[148:149], v[152:153], v[156:157]
	v_rcp_f32_e32 v154, v146
	v_rcp_f32_e32 v155, v147
	v_cvt_pk_bf16_f32 v161, v148, v149
	v_lshlrev_b32_e32 v148, 16, v204
	v_and_b32_e32 v149, 0xffff0000, v204
	v_add_f32_e32 v14, v14, v11
	v_add_f32_e32 v15, v15, v9
	v_exp_f32_e32 v8, v8
	v_mul_f32_e32 v10, 0x3fb8aa3b, v151
	v_pk_mul_f32 v[148:149], v[148:149], s[86:87] op_sel_hi:[1,0]
	v_mul_f32_e32 v14, 0x3fb8aa3b, v14
	v_mul_f32_e32 v15, 0x3fb8aa3b, v15
	v_exp_f32_e32 v10, v10
	v_pk_mul_f32 v[146:147], v[148:149], v[146:147]
	v_exp_f32_e32 v14, v14
	v_exp_f32_e32 v15, v15
	v_cvt_pk_bf16_f32 v162, v146, v147
	v_pk_mul_f32 v[146:147], v[154:155], v[158:159]
	v_lshl_add_u64 v[150:151], s[62:63], 0, v[126:127]
	v_cvt_pk_bf16_f32 v163, v146, v147
	v_mov_b32_e32 v146, v156
	v_mov_b32_e32 v147, v158
	v_pk_mul_f32 v[146:147], v[8:9], v[146:147] op_sel_hi:[0,1]
	v_mov_b32_e32 v148, v152
	v_mov_b32_e32 v149, v154
	v_mov_b32_e32 v158, v157
	v_add_f32_e32 v12, v12, v11
	v_add_f32_e32 v13, v13, v9
	v_lshlrev_b64 v[150:151], 10, v[150:151]
	v_pk_mul_f32 v[148:149], v[146:147], v[148:149]
	v_pk_mul_f32 v[146:147], v[10:11], v[158:159] op_sel_hi:[0,1]
	v_mov_b32_e32 v154, v153
	v_rcp_f32_e32 v152, v14
	v_rcp_f32_e32 v153, v15
	v_mul_f32_e32 v12, 0x3fb8aa3b, v12
	v_mul_f32_e32 v13, 0x3fb8aa3b, v13
	v_lshl_add_u64 v[150:151], s[68:69], 0, v[150:151]
	v_pk_mul_f32 v[146:147], v[146:147], v[154:155]
	v_lshlrev_b32_e32 v154, 16, v206
	v_and_b32_e32 v155, 0xffff0000, v206
	v_exp_f32_e32 v12, v12
	v_exp_f32_e32 v13, v13
	v_lshl_add_u64 v[150:151], v[150:151], 0, s[66:67]
	v_pk_mul_f32 v[154:155], v[154:155], s[86:87] op_sel_hi:[1,0]
	v_lshl_add_u64 v[150:151], v[150:151], 0, v[42:43]
	v_lshlrev_b32_e32 v156, 16, v205
	v_and_b32_e32 v157, 0xffff0000, v205
	v_pk_mul_f32 v[14:15], v[154:155], v[14:15]
	global_store_dword v[150:151], v160, off
	ds_write2_b32 v194, v160, v162 offset1:68
	ds_write2_b32 v219, v161, v163 offset1:68
	v_cvt_pk_bf16_f32 v160, v14, v15
	v_pk_mul_f32 v[14:15], v[152:153], v[156:157]
	v_lshlrev_b32_e32 v154, 16, v207
	v_cvt_pk_bf16_f32 v161, v14, v15
	v_rcp_f32_e32 v14, v12
	v_rcp_f32_e32 v15, v13
	v_and_b32_e32 v155, 0xffff0000, v207
	v_add_f32_e32 v6, v6, v11
	v_add_f32_e32 v7, v7, v9
	v_pk_mul_f32 v[154:155], v[154:155], s[86:87] op_sel_hi:[1,0]
	v_mul_f32_e32 v6, 0x3fb8aa3b, v6
	v_mul_f32_e32 v7, 0x3fb8aa3b, v7
	v_lshlrev_b32_e32 v158, 16, v209
	v_and_b32_e32 v159, 0xffff0000, v209
	v_pk_mul_f32 v[12:13], v[154:155], v[12:13]
	v_exp_f32_e32 v6, v6
	v_exp_f32_e32 v7, v7
	global_store_dword v[150:151], v162, off offset:1024
	v_cvt_pk_bf16_f32 v162, v12, v13
	v_pk_mul_f32 v[12:13], v[14:15], v[158:159]
	v_mov_b32_e32 v154, v152
	v_cvt_pk_bf16_f32 v163, v12, v13
	v_mov_b32_e32 v12, v156
	v_mov_b32_e32 v13, v158
	v_pk_mul_f32 v[12:13], v[8:9], v[12:13] op_sel_hi:[0,1]
	v_mov_b32_e32 v155, v14
	v_mov_b32_e32 v158, v157
	v_pk_mul_f32 v[12:13], v[12:13], v[154:155]
	v_pk_mul_f32 v[154:155], v[10:11], v[158:159] op_sel_hi:[0,1]
	v_mov_b32_e32 v14, v153
	v_rcp_f32_e32 v152, v6
	v_rcp_f32_e32 v153, v7
	v_add_f32_e32 v4, v4, v11
	v_add_f32_e32 v5, v5, v9
	v_pk_mul_f32 v[14:15], v[154:155], v[14:15]
	v_lshlrev_b32_e32 v154, 16, v211
	v_and_b32_e32 v155, 0xffff0000, v211
	v_mul_f32_e32 v4, 0x3fb8aa3b, v4
	v_mul_f32_e32 v5, 0x3fb8aa3b, v5
	v_pk_mul_f32 v[154:155], v[154:155], s[86:87] op_sel_hi:[1,0]
	v_exp_f32_e32 v4, v4
	v_exp_f32_e32 v5, v5
	v_lshlrev_b32_e32 v156, 16, v210
	v_and_b32_e32 v157, 0xffff0000, v210
	v_pk_mul_f32 v[6:7], v[154:155], v[6:7]
	global_store_dword v[150:151], v160, off offset:2048
	ds_write2_b32 v194, v160, v162 offset0:136 offset1:204
	ds_write2_b32 v219, v161, v163 offset0:136 offset1:204
	v_cvt_pk_bf16_f32 v160, v6, v7
	v_pk_mul_f32 v[6:7], v[152:153], v[156:157]
	global_store_dword v[150:151], v162, off offset:3072
	v_cvt_pk_bf16_f32 v161, v6, v7
	v_add_co_u32_e32 v6, vcc, s23, v150
	v_rcp_f32_e32 v150, v4
	s_nop 0
	v_addc_co_u32_e32 v7, vcc, 0, v151, vcc
	v_rcp_f32_e32 v151, v5
	v_lshlrev_b32_e32 v154, 16, v213
	v_and_b32_e32 v155, 0xffff0000, v213
	v_add_f32_e32 v2, v2, v11
	v_add_f32_e32 v3, v3, v9
	v_pk_mul_f32 v[154:155], v[154:155], s[86:87] op_sel_hi:[1,0]
	v_mul_f32_e32 v2, 0x3fb8aa3b, v2
	v_mul_f32_e32 v3, 0x3fb8aa3b, v3
	v_lshlrev_b32_e32 v158, 16, v212
	v_and_b32_e32 v159, 0xffff0000, v212
	v_pk_mul_f32 v[4:5], v[154:155], v[4:5]
	v_exp_f32_e32 v2, v2
	v_exp_f32_e32 v3, v3
	v_cvt_pk_bf16_f32 v162, v4, v5
	v_pk_mul_f32 v[4:5], v[150:151], v[158:159]
	v_mov_b32_e32 v154, v152
	v_cvt_pk_bf16_f32 v163, v4, v5
	v_mov_b32_e32 v4, v156
	v_mov_b32_e32 v5, v158
	v_pk_mul_f32 v[4:5], v[8:9], v[4:5] op_sel_hi:[0,1]
	v_mov_b32_e32 v155, v150
	v_mov_b32_e32 v158, v157
	v_add_f32_e32 v0, v0, v11
	v_add_f32_e32 v1, v1, v9
	v_pk_mul_f32 v[4:5], v[4:5], v[154:155]
	v_pk_mul_f32 v[154:155], v[10:11], v[158:159] op_sel_hi:[0,1]
	v_mov_b32_e32 v150, v153
	v_rcp_f32_e32 v152, v2
	v_rcp_f32_e32 v153, v3
	v_mul_f32_e32 v0, 0x3fb8aa3b, v0
	v_mul_f32_e32 v1, 0x3fb8aa3b, v1
	v_pk_mul_f32 v[150:151], v[154:155], v[150:151]
	v_lshlrev_b32_e32 v154, 16, v215
	v_and_b32_e32 v155, 0xffff0000, v215
	v_exp_f32_e32 v0, v0
	v_exp_f32_e32 v1, v1
	v_pk_mul_f32 v[154:155], v[154:155], s[86:87] op_sel_hi:[1,0]
	v_lshlrev_b32_e32 v156, 16, v214
	v_and_b32_e32 v157, 0xffff0000, v214
	v_pk_mul_f32 v[2:3], v[154:155], v[2:3]
	global_store_dword v[6:7], v160, off
	ds_write2_b32 v220, v160, v162 offset0:16 offset1:84
	ds_write2_b32 v221, v161, v163 offset0:16 offset1:84
	v_cvt_pk_bf16_f32 v160, v2, v3
	v_pk_mul_f32 v[2:3], v[152:153], v[156:157]
	v_lshlrev_b32_e32 v154, 16, v216
	v_cvt_pk_bf16_f32 v161, v2, v3
	v_rcp_f32_e32 v2, v0
	v_rcp_f32_e32 v3, v1
	v_and_b32_e32 v155, 0xffff0000, v216
	v_pk_mul_f32 v[154:155], v[154:155], s[86:87] op_sel_hi:[1,0]
	v_lshlrev_b32_e32 v158, 16, v217
	v_and_b32_e32 v159, 0xffff0000, v217
	v_pk_mul_f32 v[0:1], v[154:155], v[0:1]
	v_mov_b32_e32 v154, v152
	v_cvt_pk_bf16_f32 v9, v0, v1
	v_pk_mul_f32 v[0:1], v[2:3], v[158:159]
	v_mov_b32_e32 v155, v2
	v_cvt_pk_bf16_f32 v11, v0, v1
	v_mov_b32_e32 v0, v156
	v_mov_b32_e32 v1, v158
	v_pk_mul_f32 v[0:1], v[8:9], v[0:1] op_sel_hi:[0,1]
	v_mov_b32_e32 v158, v157
	v_pk_mul_f32 v[154:155], v[0:1], v[154:155]
	v_pk_mul_f32 v[0:1], v[10:11], v[158:159] op_sel_hi:[0,1]
	v_mov_b32_e32 v2, v153
	global_store_dword v[6:7], v162, off offset:1024
	global_store_dword v[6:7], v160, off offset:2048
	v_pk_mul_f32 v[152:153], v[0:1], v[2:3]
	ds_write2_b32 v220, v160, v9 offset0:152 offset1:220
	ds_write2_b32 v221, v161, v11 offset0:152 offset1:220
	global_store_dword v[6:7], v9, off offset:3072
	v_lshl_add_u64 v[6:7], v[56:57], 0, s[58:59]
	v_cvt_pk_bf16_f32 v0, v148, v149
	v_cvt_pk_bf16_f32 v1, v12, v13
	v_cvt_pk_bf16_f32 v2, v4, v5
	v_cvt_pk_bf16_f32 v3, v154, v155
	global_store_dwordx4 v[6:7], v[0:3], off
	s_nop 1
	v_cvt_pk_bf16_f32 v0, v146, v147
	v_cvt_pk_bf16_f32 v1, v14, v15
	v_cvt_pk_bf16_f32 v2, v150, v151
	v_cvt_pk_bf16_f32 v3, v152, v153
	global_store_dwordx4 v[6:7], v[0:3], off offset:128
	s_and_saveexec_b64 s[58:59], s[18:19]
	s_cbranch_execz .LBB0_392
	s_lshl_b64 s[62:63], s[64:65], 9
	v_lshl_add_u64 v[0:1], v[58:59], 0, s[62:63]
	v_mov_b32_e32 v9, v10
	global_store_dwordx2 v[0:1], v[8:9], off

.Lpw2_done:
	s_and_saveexec_b64 s[58:59], s[0:1]
	ds_write_b128 v192, v[16:19] offset:34816
	s_or_b64 exec, exec, s[58:59]
	s_waitcnt lgkmcnt(0)
	s_barrier
	v_add_u32_e32 v218, 0, v193
	ds_read_b128 v[0:3], v218 offset:34816
	ds_read_b128 v[4:7], v218 offset:34832
	ds_read_b128 v[8:11], v218 offset:34848
	ds_read_b128 v[12:15], v218 offset:34864
	s_ashr_i32 s58, s23, 9
	s_waitcnt lgkmcnt(3)
	v_mov_b32_e32 v146, v0
	s_waitcnt lgkmcnt(2)
	v_mov_b32_e32 v147, v4
	v_mov_b32_e32 v4, v1
	v_pk_mul_f32 v[0:1], v[44:45], v[4:5]
	v_mov_b32_e32 v148, v2
	v_mov_b32_e32 v149, v6
	v_mov_b32_e32 v6, v3
	v_pk_mul_f32 v[2:3], v[130:131], v[4:5]
	v_pk_fma_f32 v[0:1], v[46:47], v[146:147], v[0:1]
	v_pk_fma_f32 v[2:3], v[132:133], v[146:147], v[2:3]
	v_pk_fma_f32 v[0:1], v[48:49], v[148:149], v[0:1]
	v_pk_fma_f32 v[2:3], v[136:137], v[148:149], v[2:3]
	s_waitcnt lgkmcnt(0)
	v_mov_b32_e32 v5, v12
	v_mov_b32_e32 v12, v9
	v_pk_fma_f32 v[0:1], v[54:55], v[6:7], v[0:1]
	v_pk_fma_f32 v[2:3], v[138:139], v[6:7], v[2:3]
	v_mov_b32_e32 v4, v8
	v_pk_mul_f32 v[6:7], v[70:71], v[12:13]
	v_mov_b32_e32 v8, v10
	v_pk_fma_f32 v[6:7], v[68:69], v[4:5], v[6:7]
	v_mov_b32_e32 v9, v14
	v_pk_fma_f32 v[6:7], v[98:99], v[8:9], v[6:7]
	v_mov_b32_e32 v14, v11
	s_nop 0
	v_add_f32_e32 v0, v128, v0
	v_pk_fma_f32 v[6:7], v[94:95], v[14:15], v[6:7]
	v_add_f32_e32 v0, v0, v1
	v_add_f32_e32 v0, v0, v6
	v_add_f32_e32 v6, v0, v7
	v_pk_mul_f32 v[0:1], v[140:141], v[12:13]
	v_add_f32_e32 v2, v129, v2
	v_pk_fma_f32 v[0:1], v[142:143], v[4:5], v[0:1]
	v_add_f32_e32 v2, v2, v3
	v_pk_fma_f32 v[0:1], v[144:145], v[8:9], v[0:1]
	s_ashr_i32 s59, s58, 31
	v_pk_fma_f32 v[0:1], v[134:135], v[14:15], v[0:1]
	s_bfe_u32 s25, s23, 0x20001
	v_add_f32_e32 v0, v2, v0
	v_add_f32_e32 v3, v0, v1
	v_mul_f32_e64 v1, |v6|, s77
	v_exp_f32_e32 v1, v1
	s_bfe_u32 s66, s23, 0x60003
	s_lshl_b64 s[62:63], s[58:59], 12
	s_lshl_b64 s[58:59], s[58:59], 2
	v_add_f32_e32 v1, 1.0, v1
	v_cmp_gt_f32_e32 vcc, s87, v1
	s_add_u32 s58, s58, s33
	s_addc_u32 s59, s59, 0
	v_cndmask_b32_e64 v2, 0, 32, vcc
	v_ldexp_f32 v1, v1, v2
	v_log_f32_e32 v1, v1
	s_or_b32 s58, s58, s25
	s_lshl_b64 s[64:65], s[58:59], 6
	v_min_f32_e32 v0, 0, v6
	v_mul_f32_e32 v2, 0x3f317217, v1
	v_fma_f32 v2, v1, s20, -v2
	v_fmac_f32_e32 v2, 0x3377d1cf, v1
	v_fmac_f32_e32 v2, 0x3f317217, v1
	v_cmp_lt_f32_e64 s[58:59], |v1|, s21
	v_add_u32_e32 v222, v191, v193
	s_or_b32 s64, s64, s66
	v_cndmask_b32_e64 v1, v1, v2, s[58:59]
	v_cndmask_b32_e32 v2, 0, v200, vcc
	v_sub_f32_e32 v2, v1, v2
	v_min_f32_e32 v1, 0, v3
	v_mul_f32_e64 v3, |v3|, s77
	v_exp_f32_e32 v3, v3
	v_add_u32_e32 v219, 0x4400, v194
	v_add_u32_e32 v220, 0x400, v194
	v_add_u32_e32 v221, 0x4800, v194
	v_add_f32_e32 v3, 1.0, v3
	v_cmp_gt_f32_e32 vcc, s87, v3
	s_nop 1
	v_cndmask_b32_e64 v4, 0, 32, vcc
	v_ldexp_f32 v3, v3, v4
	v_log_f32_e32 v3, v3
	s_nop 0
	v_mul_f32_e32 v4, 0x3f317217, v3
	v_fma_f32 v4, v3, s20, -v4
	v_fmac_f32_e32 v4, 0x3377d1cf, v3
	v_fmac_f32_e32 v4, 0x3f317217, v3
	v_cmp_lt_f32_e64 s[58:59], |v3|, s21
	s_nop 1
	v_cndmask_b32_e64 v3, v3, v4, s[58:59]
	v_cndmask_b32_e32 v4, 0, v200, vcc
	v_sub_f32_e32 v3, v3, v4
	ds_read_b128 v[4:7], v218 offset:34880
	ds_read_b128 v[8:11], v218 offset:34896
	v_pk_add_f32 v[0:1], v[0:1], v[2:3] neg_lo:[0,1] neg_hi:[0,1]
	s_waitcnt lgkmcnt(1)
	v_mov_b32_e32 v12, v4
	s_waitcnt lgkmcnt(0)
	v_mov_b32_e32 v13, v8
	v_mov_b32_e32 v8, v5
	v_pk_mul_f32 v[4:5], v[44:45], v[8:9]
	v_mov_b32_e32 v14, v6
	v_pk_fma_f32 v[4:5], v[46:47], v[12:13], v[4:5]
	v_mov_b32_e32 v15, v10
	v_pk_fma_f32 v[4:5], v[48:49], v[14:15], v[4:5]
	v_mov_b32_e32 v10, v7
	v_pk_fma_f32 v[146:147], v[54:55], v[10:11], v[4:5]
	v_pk_mul_f32 v[4:5], v[130:131], v[8:9]
	s_nop 0
	v_pk_fma_f32 v[4:5], v[132:133], v[12:13], v[4:5]
	s_nop 0
	v_pk_fma_f32 v[4:5], v[136:137], v[14:15], v[4:5]
	s_nop 0
	v_pk_fma_f32 v[12:13], v[138:139], v[10:11], v[4:5]
	ds_read_b128 v[4:7], v218 offset:34912
	ds_read_b128 v[8:11], v218 offset:34928
	s_waitcnt lgkmcnt(1)
	v_mov_b32_e32 v14, v4
	s_waitcnt lgkmcnt(0)
	v_mov_b32_e32 v15, v8
	v_mov_b32_e32 v8, v5
	v_pk_mul_f32 v[4:5], v[70:71], v[8:9]
	v_mov_b32_e32 v148, v6
	v_pk_fma_f32 v[4:5], v[68:69], v[14:15], v[4:5]
	v_mov_b32_e32 v149, v10
	v_pk_fma_f32 v[4:5], v[98:99], v[148:149], v[4:5]
	v_mov_b32_e32 v10, v7
	v_add_f32_e32 v6, v128, v146
	v_pk_fma_f32 v[4:5], v[94:95], v[10:11], v[4:5]
	v_add_f32_e32 v6, v6, v147
	v_add_f32_e32 v4, v6, v4
	v_add_f32_e32 v6, v4, v5
	v_pk_mul_f32 v[4:5], v[140:141], v[8:9]
	v_add_f32_e32 v7, v129, v12
	v_pk_fma_f32 v[4:5], v[142:143], v[14:15], v[4:5]
	v_add_f32_e32 v7, v7, v13
	v_pk_fma_f32 v[4:5], v[144:145], v[148:149], v[4:5]
	s_nop 0
	v_pk_fma_f32 v[4:5], v[134:135], v[10:11], v[4:5]
	s_nop 0
	v_add_f32_e32 v4, v7, v4
	v_add_f32_e32 v7, v4, v5
	v_mul_f32_e64 v5, |v6|, s77
	v_exp_f32_e32 v5, v5
	v_min_f32_e32 v4, 0, v6
	v_add_f32_e32 v5, 1.0, v5
	v_cmp_gt_f32_e32 vcc, s87, v5
	s_nop 1
	v_cndmask_b32_e64 v6, 0, 32, vcc
	v_ldexp_f32 v5, v5, v6
	v_log_f32_e32 v5, v5
	s_nop 0
	v_mul_f32_e32 v6, 0x3f317217, v5
	v_fma_f32 v6, v5, s20, -v6
	v_fmac_f32_e32 v6, 0x3377d1cf, v5
	v_fmac_f32_e32 v6, 0x3f317217, v5
	v_cmp_lt_f32_e64 s[58:59], |v5|, s21
	s_nop 1
	v_cndmask_b32_e64 v5, v5, v6, s[58:59]
	v_cndmask_b32_e32 v6, 0, v200, vcc
	v_sub_f32_e32 v6, v5, v6
	v_min_f32_e32 v5, 0, v7
	v_mul_f32_e64 v7, |v7|, s77
	v_exp_f32_e32 v7, v7
	s_nop 0
	v_add_f32_e32 v7, 1.0, v7
	v_cmp_gt_f32_e32 vcc, s87, v7
	s_nop 1
	v_cndmask_b32_e64 v8, 0, 32, vcc
	v_ldexp_f32 v7, v7, v8
	v_log_f32_e32 v7, v7
	s_nop 0
	v_mul_f32_e32 v8, 0x3f317217, v7
	v_fma_f32 v8, v7, s20, -v8
	v_fmac_f32_e32 v8, 0x3377d1cf, v7
	v_fmac_f32_e32 v8, 0x3f317217, v7
	v_cmp_lt_f32_e64 s[58:59], |v7|, s21
	s_nop 1
	v_cndmask_b32_e64 v7, v7, v8, s[58:59]
	v_cndmask_b32_e32 v8, 0, v200, vcc
	v_sub_f32_e32 v7, v7, v8
	ds_read_b128 v[8:11], v218 offset:34944
	ds_read_b128 v[12:15], v218 offset:34960
	s_waitcnt lgkmcnt(1)
	v_mov_b32_e32 v146, v8
	s_waitcnt lgkmcnt(0)
	v_mov_b32_e32 v147, v12
	v_mov_b32_e32 v12, v9
	v_pk_mul_f32 v[8:9], v[44:45], v[12:13]
	v_mov_b32_e32 v148, v10
	v_pk_fma_f32 v[8:9], v[46:47], v[146:147], v[8:9]
	v_mov_b32_e32 v149, v14
	v_pk_fma_f32 v[8:9], v[48:49], v[148:149], v[8:9]
	v_mov_b32_e32 v14, v11
	v_pk_fma_f32 v[150:151], v[54:55], v[14:15], v[8:9]
	v_pk_mul_f32 v[8:9], v[130:131], v[12:13]
	s_nop 0
	v_pk_fma_f32 v[8:9], v[132:133], v[146:147], v[8:9]
	s_nop 0
	v_pk_fma_f32 v[8:9], v[136:137], v[148:149], v[8:9]
	s_nop 0
	v_pk_fma_f32 v[146:147], v[138:139], v[14:15], v[8:9]
	ds_read_b128 v[8:11], v218 offset:34976
	ds_read_b128 v[12:15], v218 offset:34992
	s_waitcnt lgkmcnt(1)
	v_mov_b32_e32 v148, v8
	s_waitcnt lgkmcnt(0)
	v_mov_b32_e32 v149, v12
	v_mov_b32_e32 v12, v9
	v_pk_mul_f32 v[8:9], v[70:71], v[12:13]
	v_mov_b32_e32 v152, v10
	v_pk_fma_f32 v[8:9], v[68:69], v[148:149], v[8:9]
	v_mov_b32_e32 v153, v14
	v_pk_fma_f32 v[8:9], v[98:99], v[152:153], v[8:9]
	v_mov_b32_e32 v14, v11
	v_add_f32_e32 v10, v128, v150
	v_pk_fma_f32 v[8:9], v[94:95], v[14:15], v[8:9]
	v_add_f32_e32 v10, v10, v151
	v_add_f32_e32 v8, v10, v8
	v_add_f32_e32 v10, v8, v9
	v_pk_mul_f32 v[8:9], v[140:141], v[12:13]
	v_add_f32_e32 v11, v129, v146
	v_pk_fma_f32 v[8:9], v[142:143], v[148:149], v[8:9]
	v_add_f32_e32 v11, v11, v147
	v_pk_fma_f32 v[8:9], v[144:145], v[152:153], v[8:9]
	s_nop 0
	v_pk_fma_f32 v[8:9], v[134:135], v[14:15], v[8:9]
	s_nop 0
	v_add_f32_e32 v8, v11, v8
	v_add_f32_e32 v11, v8, v9
	v_mul_f32_e64 v9, |v10|, s77
	v_exp_f32_e32 v9, v9
	v_min_f32_e32 v8, 0, v10
	v_add_f32_e32 v9, 1.0, v9
	v_cmp_gt_f32_e32 vcc, s87, v9
	s_nop 1
	v_cndmask_b32_e64 v10, 0, 32, vcc
	v_ldexp_f32 v9, v9, v10
	v_log_f32_e32 v9, v9
	s_nop 0
	v_mul_f32_e32 v10, 0x3f317217, v9
	v_fma_f32 v10, v9, s20, -v10
	v_fmac_f32_e32 v10, 0x3377d1cf, v9
	v_fmac_f32_e32 v10, 0x3f317217, v9
	v_cmp_lt_f32_e64 s[58:59], |v9|, s21
	s_nop 1
	v_cndmask_b32_e64 v9, v9, v10, s[58:59]
	v_cndmask_b32_e32 v10, 0, v200, vcc
	v_sub_f32_e32 v10, v9, v10
	v_min_f32_e32 v9, 0, v11
	v_mul_f32_e64 v11, |v11|, s77
	v_exp_f32_e32 v11, v11
	s_nop 0
	v_add_f32_e32 v11, 1.0, v11
	v_cmp_gt_f32_e32 vcc, s87, v11
	s_nop 1
	v_cndmask_b32_e64 v12, 0, 32, vcc
	v_ldexp_f32 v11, v11, v12
	v_log_f32_e32 v11, v11
	s_nop 0
	v_mul_f32_e32 v12, 0x3f317217, v11
	v_fma_f32 v12, v11, s20, -v12
	v_fmac_f32_e32 v12, 0x3377d1cf, v11
	v_fmac_f32_e32 v12, 0x3f317217, v11
	v_cmp_lt_f32_e64 s[58:59], |v11|, s21
	s_nop 1
	v_cndmask_b32_e64 v11, v11, v12, s[58:59]
	v_cndmask_b32_e32 v12, 0, v200, vcc
	v_sub_f32_e32 v11, v11, v12
	ds_read_b128 v[12:15], v218 offset:35008
	ds_read_b128 v[146:149], v218 offset:35024
	s_waitcnt lgkmcnt(1)
	v_mov_b32_e32 v150, v12
	s_waitcnt lgkmcnt(0)
	v_mov_b32_e32 v151, v146
	v_mov_b32_e32 v146, v13
	v_pk_mul_f32 v[12:13], v[44:45], v[146:147]
	v_mov_b32_e32 v152, v14
	v_pk_fma_f32 v[12:13], v[46:47], v[150:151], v[12:13]
	v_mov_b32_e32 v153, v148
	v_pk_fma_f32 v[12:13], v[48:49], v[152:153], v[12:13]
	v_mov_b32_e32 v148, v15
	v_pk_fma_f32 v[154:155], v[54:55], v[148:149], v[12:13]
	v_pk_mul_f32 v[12:13], v[130:131], v[146:147]
	s_nop 0
	v_pk_fma_f32 v[12:13], v[132:133], v[150:151], v[12:13]
	s_nop 0
	v_pk_fma_f32 v[12:13], v[136:137], v[152:153], v[12:13]
	s_nop 0
	v_pk_fma_f32 v[150:151], v[138:139], v[148:149], v[12:13]
	ds_read_b128 v[12:15], v218 offset:35040
	ds_read_b128 v[146:149], v218 offset:35056
	s_waitcnt lgkmcnt(1)
	v_mov_b32_e32 v152, v12
	s_waitcnt lgkmcnt(0)
	v_mov_b32_e32 v153, v146
	v_mov_b32_e32 v146, v13
	v_pk_mul_f32 v[12:13], v[70:71], v[146:147]
	v_mov_b32_e32 v156, v14
	v_pk_fma_f32 v[12:13], v[68:69], v[152:153], v[12:13]
	v_mov_b32_e32 v157, v148
	v_pk_fma_f32 v[12:13], v[98:99], v[156:157], v[12:13]
	v_mov_b32_e32 v148, v15
	v_add_f32_e32 v14, v128, v154
	v_pk_fma_f32 v[12:13], v[94:95], v[148:149], v[12:13]
	v_add_f32_e32 v14, v14, v155
	v_add_f32_e32 v12, v14, v12
	v_add_f32_e32 v14, v12, v13
	v_pk_mul_f32 v[12:13], v[140:141], v[146:147]
	v_add_f32_e32 v15, v129, v150
	v_pk_fma_f32 v[12:13], v[142:143], v[152:153], v[12:13]
	v_add_f32_e32 v15, v15, v151
	v_pk_fma_f32 v[12:13], v[144:145], v[156:157], v[12:13]
	s_nop 0
	v_pk_fma_f32 v[12:13], v[134:135], v[148:149], v[12:13]
	s_nop 0
	v_add_f32_e32 v12, v15, v12
	v_add_f32_e32 v15, v12, v13
	v_mul_f32_e64 v13, |v14|, s77
	v_exp_f32_e32 v13, v13
	v_min_f32_e32 v12, 0, v14
	v_add_f32_e32 v13, 1.0, v13
	v_cmp_gt_f32_e32 vcc, s87, v13
	s_nop 1
	v_cndmask_b32_e64 v14, 0, 32, vcc
	v_ldexp_f32 v13, v13, v14
	v_log_f32_e32 v13, v13
	s_nop 0
	v_mul_f32_e32 v14, 0x3f317217, v13
	v_fma_f32 v14, v13, s20, -v14
	v_fmac_f32_e32 v14, 0x3377d1cf, v13
	v_fmac_f32_e32 v14, 0x3f317217, v13
	v_cmp_lt_f32_e64 s[58:59], |v13|, s21
	s_nop 1
	v_cndmask_b32_e64 v13, v13, v14, s[58:59]
	v_cndmask_b32_e32 v14, 0, v200, vcc
	v_sub_f32_e32 v14, v13, v14
	v_min_f32_e32 v13, 0, v15
	v_mul_f32_e64 v15, |v15|, s77
	v_exp_f32_e32 v15, v15
	s_nop 0
	v_add_f32_e32 v15, 1.0, v15
	v_cmp_gt_f32_e32 vcc, s87, v15
	s_nop 1
	v_cndmask_b32_e64 v146, 0, 32, vcc
	v_ldexp_f32 v15, v15, v146
	v_log_f32_e32 v15, v15
	s_nop 0
	v_mul_f32_e32 v146, 0x3f317217, v15
	v_fma_f32 v146, v15, s20, -v146
	v_fmac_f32_e32 v146, 0x3377d1cf, v15
	v_fmac_f32_e32 v146, 0x3f317217, v15
	v_cmp_lt_f32_e64 s[58:59], |v15|, s21
	s_nop 1
	v_cndmask_b32_e64 v15, v15, v146, s[58:59]
	v_cndmask_b32_e32 v146, 0, v200, vcc
	v_sub_f32_e32 v15, v15, v146
	ds_read_b128 v[146:149], v218 offset:35072
	ds_read_b128 v[150:153], v218 offset:35088
	s_waitcnt lgkmcnt(1)
	v_mov_b32_e32 v154, v146
	s_waitcnt lgkmcnt(0)
	v_mov_b32_e32 v155, v150
	v_mov_b32_e32 v150, v147
	v_pk_mul_f32 v[146:147], v[44:45], v[150:151]
	v_mov_b32_e32 v156, v148
	v_pk_fma_f32 v[146:147], v[46:47], v[154:155], v[146:147]
	v_mov_b32_e32 v157, v152
	v_pk_fma_f32 v[146:147], v[48:49], v[156:157], v[146:147]
	v_mov_b32_e32 v152, v149
	v_pk_fma_f32 v[158:159], v[54:55], v[152:153], v[146:147]
	v_pk_mul_f32 v[146:147], v[130:131], v[150:151]
	s_nop 0
	v_pk_fma_f32 v[146:147], v[132:133], v[154:155], v[146:147]
	s_nop 0
	v_pk_fma_f32 v[146:147], v[136:137], v[156:157], v[146:147]
	s_nop 0
	v_pk_fma_f32 v[154:155], v[138:139], v[152:153], v[146:147]
	ds_read_b128 v[146:149], v218 offset:35104
	ds_read_b128 v[150:153], v218 offset:35120
	s_waitcnt lgkmcnt(1)
	v_mov_b32_e32 v156, v146
	s_waitcnt lgkmcnt(0)
	v_mov_b32_e32 v157, v150
	v_mov_b32_e32 v150, v147
	v_pk_mul_f32 v[146:147], v[70:71], v[150:151]
	v_mov_b32_e32 v160, v148
	v_pk_fma_f32 v[146:147], v[68:69], v[156:157], v[146:147]
	v_mov_b32_e32 v161, v152
	v_pk_fma_f32 v[146:147], v[98:99], v[160:161], v[146:147]
	v_mov_b32_e32 v152, v149
	v_add_f32_e32 v148, v128, v158
	v_pk_fma_f32 v[146:147], v[94:95], v[152:153], v[146:147]
	v_add_f32_e32 v148, v148, v159
	v_add_f32_e32 v146, v148, v146
	v_add_f32_e32 v148, v146, v147
	v_pk_mul_f32 v[146:147], v[140:141], v[150:151]
	v_add_f32_e32 v149, v129, v154
	v_pk_fma_f32 v[146:147], v[142:143], v[156:157], v[146:147]
	v_add_f32_e32 v149, v149, v155
	v_pk_fma_f32 v[146:147], v[144:145], v[160:161], v[146:147]
	s_nop 0
	v_pk_fma_f32 v[146:147], v[134:135], v[152:153], v[146:147]
	s_nop 0
	v_add_f32_e32 v146, v149, v146
	v_add_f32_e32 v149, v146, v147
	v_mul_f32_e64 v147, |v148|, s77
	v_exp_f32_e32 v147, v147
	v_min_f32_e32 v146, 0, v148
	v_add_f32_e32 v147, 1.0, v147
	v_cmp_gt_f32_e32 vcc, s87, v147
	s_nop 1
	v_cndmask_b32_e64 v148, 0, 32, vcc
	v_ldexp_f32 v147, v147, v148
	v_log_f32_e32 v147, v147
	s_nop 0
	v_mul_f32_e32 v148, 0x3f317217, v147
	v_fma_f32 v148, v147, s20, -v148
	v_fmac_f32_e32 v148, 0x3377d1cf, v147
	v_fmac_f32_e32 v148, 0x3f317217, v147
	v_cmp_lt_f32_e64 s[58:59], |v147|, s21
	s_nop 1
	v_cndmask_b32_e64 v147, v147, v148, s[58:59]
	v_cndmask_b32_e32 v148, 0, v200, vcc
	v_sub_f32_e32 v148, v147, v148
	v_min_f32_e32 v147, 0, v149
	v_mul_f32_e64 v149, |v149|, s77
	v_exp_f32_e32 v149, v149
	s_nop 0
	v_add_f32_e32 v149, 1.0, v149
	v_cmp_gt_f32_e32 vcc, s87, v149
	s_nop 1
	v_cndmask_b32_e64 v150, 0, 32, vcc
	v_ldexp_f32 v149, v149, v150
	v_log_f32_e32 v149, v149
	s_nop 0
	v_mul_f32_e32 v150, 0x3f317217, v149
	v_fma_f32 v150, v149, s20, -v150
	v_fmac_f32_e32 v150, 0x3377d1cf, v149
	v_fmac_f32_e32 v150, 0x3f317217, v149
	v_cmp_lt_f32_e64 s[58:59], |v149|, s21
	s_nop 1
	v_cndmask_b32_e64 v149, v149, v150, s[58:59]
	v_cndmask_b32_e32 v150, 0, v200, vcc
	v_sub_f32_e32 v149, v149, v150
	ds_read_b128 v[150:153], v218 offset:35136
	ds_read_b128 v[154:157], v218 offset:35152
	s_waitcnt lgkmcnt(1)
	v_mov_b32_e32 v158, v150
	s_waitcnt lgkmcnt(0)
	v_mov_b32_e32 v159, v154
	v_mov_b32_e32 v154, v151
	v_pk_mul_f32 v[150:151], v[44:45], v[154:155]
	v_mov_b32_e32 v160, v152
	v_pk_fma_f32 v[150:151], v[46:47], v[158:159], v[150:151]
	v_mov_b32_e32 v161, v156
	v_pk_fma_f32 v[150:151], v[48:49], v[160:161], v[150:151]
	v_mov_b32_e32 v156, v153
	v_pk_fma_f32 v[162:163], v[54:55], v[156:157], v[150:151]
	v_pk_mul_f32 v[150:151], v[130:131], v[154:155]
	s_nop 0
	v_pk_fma_f32 v[150:151], v[132:133], v[158:159], v[150:151]
	s_nop 0
	v_pk_fma_f32 v[150:151], v[136:137], v[160:161], v[150:151]
	s_nop 0
	v_pk_fma_f32 v[158:159], v[138:139], v[156:157], v[150:151]
	ds_read_b128 v[150:153], v218 offset:35168
	ds_read_b128 v[154:157], v218 offset:35184
	s_waitcnt lgkmcnt(1)
	v_mov_b32_e32 v160, v150
	s_waitcnt lgkmcnt(0)
	v_mov_b32_e32 v161, v154
	v_mov_b32_e32 v154, v151
	v_pk_mul_f32 v[150:151], v[70:71], v[154:155]
	v_mov_b32_e32 v164, v152
	v_pk_fma_f32 v[150:151], v[68:69], v[160:161], v[150:151]
	v_mov_b32_e32 v165, v156
	v_pk_fma_f32 v[150:151], v[98:99], v[164:165], v[150:151]
	v_mov_b32_e32 v156, v153
	v_add_f32_e32 v152, v128, v162
	v_pk_fma_f32 v[150:151], v[94:95], v[156:157], v[150:151]
	v_add_f32_e32 v152, v152, v163
	v_add_f32_e32 v150, v152, v150
	v_add_f32_e32 v152, v150, v151
	v_pk_mul_f32 v[150:151], v[140:141], v[154:155]
	v_add_f32_e32 v153, v129, v158
	v_pk_fma_f32 v[150:151], v[142:143], v[160:161], v[150:151]
	v_add_f32_e32 v153, v153, v159
	v_pk_fma_f32 v[150:151], v[144:145], v[164:165], v[150:151]
	s_nop 0
	v_pk_fma_f32 v[150:151], v[134:135], v[156:157], v[150:151]
	s_nop 0
	v_add_f32_e32 v150, v153, v150
	v_add_f32_e32 v153, v150, v151
	v_mul_f32_e64 v151, |v152|, s77
	v_exp_f32_e32 v151, v151
	v_min_f32_e32 v150, 0, v152
	v_add_f32_e32 v151, 1.0, v151
	v_cmp_gt_f32_e32 vcc, s87, v151
	s_nop 1
	v_cndmask_b32_e64 v152, 0, 32, vcc
	v_ldexp_f32 v151, v151, v152
	v_log_f32_e32 v151, v151
	s_nop 0
	v_mul_f32_e32 v152, 0x3f317217, v151
	v_fma_f32 v152, v151, s20, -v152
	v_fmac_f32_e32 v152, 0x3377d1cf, v151
	v_fmac_f32_e32 v152, 0x3f317217, v151
	v_cmp_lt_f32_e64 s[58:59], |v151|, s21
	s_nop 1
	v_cndmask_b32_e64 v151, v151, v152, s[58:59]
	v_cndmask_b32_e32 v152, 0, v200, vcc
	v_sub_f32_e32 v152, v151, v152
	v_min_f32_e32 v151, 0, v153
	v_mul_f32_e64 v153, |v153|, s77
	v_exp_f32_e32 v153, v153
	s_nop 0
	v_add_f32_e32 v153, 1.0, v153
	v_cmp_gt_f32_e32 vcc, s87, v153
	s_nop 1
	v_cndmask_b32_e64 v154, 0, 32, vcc
	v_ldexp_f32 v153, v153, v154
	v_log_f32_e32 v153, v153
	s_nop 0
	v_mul_f32_e32 v154, 0x3f317217, v153
	v_fma_f32 v154, v153, s20, -v154
	v_fmac_f32_e32 v154, 0x3377d1cf, v153
	v_fmac_f32_e32 v154, 0x3f317217, v153
	v_cmp_lt_f32_e64 s[58:59], |v153|, s21
	s_nop 1
	v_cndmask_b32_e64 v153, v153, v154, s[58:59]
	v_cndmask_b32_e32 v154, 0, v200, vcc
	v_sub_f32_e32 v153, v153, v154
	ds_read_b128 v[154:157], v218 offset:35200
	ds_read_b128 v[158:161], v218 offset:35216
	s_waitcnt lgkmcnt(1)
	v_mov_b32_e32 v162, v154
	s_waitcnt lgkmcnt(0)
	v_mov_b32_e32 v163, v158
	v_mov_b32_e32 v158, v155
	v_pk_mul_f32 v[154:155], v[44:45], v[158:159]
	v_mov_b32_e32 v164, v156
	v_pk_fma_f32 v[154:155], v[46:47], v[162:163], v[154:155]
	v_mov_b32_e32 v165, v160
	v_pk_fma_f32 v[154:155], v[48:49], v[164:165], v[154:155]
	v_mov_b32_e32 v160, v157
	v_pk_fma_f32 v[166:167], v[54:55], v[160:161], v[154:155]
	v_pk_mul_f32 v[154:155], v[130:131], v[158:159]
	s_nop 0
	v_pk_fma_f32 v[154:155], v[132:133], v[162:163], v[154:155]
	s_nop 0
	v_pk_fma_f32 v[154:155], v[136:137], v[164:165], v[154:155]
	s_nop 0
	v_pk_fma_f32 v[162:163], v[138:139], v[160:161], v[154:155]
	ds_read_b128 v[154:157], v218 offset:35232
	ds_read_b128 v[158:161], v218 offset:35248
	s_waitcnt lgkmcnt(1)
	v_mov_b32_e32 v164, v154
	s_waitcnt lgkmcnt(0)
	v_mov_b32_e32 v165, v158
	v_mov_b32_e32 v158, v155
	v_pk_mul_f32 v[154:155], v[70:71], v[158:159]
	v_mov_b32_e32 v168, v156
	v_pk_fma_f32 v[154:155], v[68:69], v[164:165], v[154:155]
	v_mov_b32_e32 v169, v160
	v_pk_fma_f32 v[154:155], v[98:99], v[168:169], v[154:155]
	v_mov_b32_e32 v160, v157
	v_add_f32_e32 v156, v128, v166
	v_pk_fma_f32 v[154:155], v[94:95], v[160:161], v[154:155]
	v_add_f32_e32 v156, v156, v167
	v_add_f32_e32 v154, v156, v154
	v_add_f32_e32 v156, v154, v155
	v_pk_mul_f32 v[154:155], v[140:141], v[158:159]
	v_add_f32_e32 v157, v129, v162
	v_pk_fma_f32 v[154:155], v[142:143], v[164:165], v[154:155]
	v_add_f32_e32 v157, v157, v163
	v_pk_fma_f32 v[154:155], v[144:145], v[168:169], v[154:155]
	s_nop 0
	v_pk_fma_f32 v[154:155], v[134:135], v[160:161], v[154:155]
	s_nop 0
	v_add_f32_e32 v154, v157, v154
	v_add_f32_e32 v157, v154, v155
	v_mul_f32_e64 v155, |v156|, s77
	v_exp_f32_e32 v155, v155
	v_min_f32_e32 v154, 0, v156
	v_add_f32_e32 v155, 1.0, v155
	v_cmp_gt_f32_e32 vcc, s87, v155
	s_nop 1
	v_cndmask_b32_e64 v156, 0, 32, vcc
	v_ldexp_f32 v155, v155, v156
	v_log_f32_e32 v155, v155
	s_nop 0
	v_mul_f32_e32 v156, 0x3f317217, v155
	v_fma_f32 v156, v155, s20, -v156
	v_fmac_f32_e32 v156, 0x3377d1cf, v155
	v_fmac_f32_e32 v156, 0x3f317217, v155
	v_cmp_lt_f32_e64 s[58:59], |v155|, s21
	s_nop 1
	v_cndmask_b32_e64 v155, v155, v156, s[58:59]
	v_cndmask_b32_e32 v156, 0, v200, vcc
	v_sub_f32_e32 v160, v155, v156
	v_mul_f32_e64 v156, |v157|, s77
	v_exp_f32_e32 v156, v156
	v_min_f32_e32 v155, 0, v157
	v_add_f32_e32 v156, 1.0, v156
	v_cmp_gt_f32_e32 vcc, s87, v156
	s_nop 1
	v_cndmask_b32_e64 v157, 0, 32, vcc
	v_ldexp_f32 v156, v156, v157
	v_log_f32_e32 v156, v156
	s_nop 0
	v_mul_f32_e32 v157, 0x3f317217, v156
	v_fma_f32 v157, v156, s20, -v157
	v_fmac_f32_e32 v157, 0x3377d1cf, v156
	v_fmac_f32_e32 v157, 0x3f317217, v156
	v_cmp_lt_f32_e64 s[58:59], |v156|, s21
	s_nop 1
	v_cndmask_b32_e64 v156, v156, v157, s[58:59]
	v_cndmask_b32_e32 v157, 0, v200, vcc
	v_sub_f32_e32 v161, v156, v157
	ds_read_b128 v[156:159], v218 offset:35264
	ds_read_b128 v[162:165], v218 offset:35280
	s_waitcnt lgkmcnt(1)
	v_mov_b32_e32 v166, v156
	s_waitcnt lgkmcnt(0)
	v_mov_b32_e32 v167, v162
	v_mov_b32_e32 v162, v157
	v_pk_mul_f32 v[156:157], v[44:45], v[162:163]
	v_mov_b32_e32 v168, v158
	v_pk_fma_f32 v[156:157], v[46:47], v[166:167], v[156:157]
	v_mov_b32_e32 v169, v164
	v_pk_fma_f32 v[156:157], v[48:49], v[168:169], v[156:157]
	v_mov_b32_e32 v164, v159
	v_pk_fma_f32 v[170:171], v[54:55], v[164:165], v[156:157]
	v_pk_mul_f32 v[156:157], v[130:131], v[162:163]
	s_nop 0
	v_pk_fma_f32 v[156:157], v[132:133], v[166:167], v[156:157]
	s_nop 0
	v_pk_fma_f32 v[156:157], v[136:137], v[168:169], v[156:157]
	s_nop 0
	v_pk_fma_f32 v[166:167], v[138:139], v[164:165], v[156:157]
	ds_read_b128 v[156:159], v218 offset:35296
	ds_read_b128 v[162:165], v218 offset:35312
	s_waitcnt lgkmcnt(1)
	v_mov_b32_e32 v168, v156
	s_waitcnt lgkmcnt(0)
	v_mov_b32_e32 v169, v162
	v_mov_b32_e32 v162, v157
	v_pk_mul_f32 v[156:157], v[70:71], v[162:163]
	v_mov_b32_e32 v172, v158
	v_pk_fma_f32 v[156:157], v[68:69], v[168:169], v[156:157]
	v_mov_b32_e32 v173, v164
	v_pk_fma_f32 v[156:157], v[98:99], v[172:173], v[156:157]
	v_mov_b32_e32 v164, v159
	v_add_f32_e32 v158, v128, v170
	v_pk_fma_f32 v[156:157], v[94:95], v[164:165], v[156:157]
	v_add_f32_e32 v158, v158, v171
	v_add_f32_e32 v156, v158, v156
	v_add_f32_e32 v158, v156, v157
	v_pk_mul_f32 v[156:157], v[140:141], v[162:163]
	v_add_f32_e32 v159, v129, v166
	v_pk_fma_f32 v[156:157], v[142:143], v[168:169], v[156:157]
	v_add_f32_e32 v159, v159, v167
	v_pk_fma_f32 v[156:157], v[144:145], v[172:173], v[156:157]
	v_pk_fma_f32 v[162:163], v[0:1], s[84:85], 0 op_sel_hi:[1,0,0]
	v_pk_fma_f32 v[156:157], v[134:135], v[164:165], v[156:157]
	v_min_f32_e32 v164, 0, v158
	v_add_f32_e32 v156, v159, v156
	v_add_f32_e32 v156, v156, v157
	v_mul_f32_e64 v157, |v158|, s77
	v_exp_f32_e32 v157, v157
	v_min_f32_e32 v165, 0, v156
	v_mul_f32_e64 v156, |v156|, s77
	v_exp_f32_e32 v156, v156
	v_add_f32_e32 v157, 1.0, v157
	v_cmp_gt_f32_e32 vcc, s87, v157
	v_pk_add_f32 v[0:1], v[4:5], v[6:7] neg_lo:[0,1] neg_hi:[0,1]
	v_add_f32_e32 v156, 1.0, v156
	v_cndmask_b32_e64 v158, 0, 32, vcc
	v_ldexp_f32 v157, v157, v158
	v_log_f32_e32 v157, v157
	s_nop 0
	v_mul_f32_e32 v158, 0x3f317217, v157
	v_fma_f32 v158, v157, s20, -v158
	v_fmac_f32_e32 v158, 0x3377d1cf, v157
	v_fmac_f32_e32 v158, 0x3f317217, v157
	v_cmp_lt_f32_e64 s[58:59], |v157|, s21
	s_nop 1
	v_cndmask_b32_e64 v157, v157, v158, s[58:59]
	v_cndmask_b32_e32 v158, 0, v200, vcc
	v_cmp_gt_f32_e32 vcc, s87, v156
	v_sub_f32_e32 v166, v157, v158
	v_pk_fma_f32 v[158:159], v[0:1], s[84:85], v[162:163] op_sel_hi:[1,0,1]
	v_cndmask_b32_e64 v157, 0, 32, vcc
	v_ldexp_f32 v156, v156, v157
	v_log_f32_e32 v156, v156
	v_pk_add_f32 v[0:1], v[8:9], v[10:11] neg_lo:[0,1] neg_hi:[0,1]
	v_mul_f32_e32 v157, 0x3f317217, v156
	v_fma_f32 v157, v156, s20, -v157
	v_fmac_f32_e32 v157, 0x3377d1cf, v156
	v_fmac_f32_e32 v157, 0x3f317217, v156
	v_cmp_lt_f32_e64 s[58:59], |v156|, s21
	s_nop 1
	v_cndmask_b32_e64 v156, v156, v157, s[58:59]
	v_cndmask_b32_e32 v157, 0, v200, vcc
	v_sub_f32_e32 v167, v156, v157
	v_pk_fma_f32 v[156:157], v[0:1], s[84:85], v[158:159] op_sel_hi:[1,0,1]
	v_pk_add_f32 v[0:1], v[12:13], v[14:15] neg_lo:[0,1] neg_hi:[0,1]
	s_lshl_b32 s58, s66, 6
	v_pk_fma_f32 v[12:13], v[0:1], s[84:85], v[156:157] op_sel_hi:[1,0,1]
	v_pk_add_f32 v[0:1], v[146:147], v[148:149] neg_lo:[0,1] neg_hi:[0,1]
	s_or_b32 s62, s62, s58
	v_pk_fma_f32 v[6:7], v[0:1], s[84:85], v[12:13] op_sel_hi:[1,0,1]
	v_pk_add_f32 v[0:1], v[150:151], v[152:153] neg_lo:[0,1] neg_hi:[0,1]
	s_lshl_b32 s66, s25, 8
	v_pk_fma_f32 v[4:5], v[0:1], s[84:85], v[6:7] op_sel_hi:[1,0,1]
	v_pk_add_f32 v[0:1], v[154:155], v[160:161] neg_lo:[0,1] neg_hi:[0,1]
	v_lshlrev_b32_e32 v152, 16, v65
	v_pk_fma_f32 v[2:3], v[0:1], s[84:85], v[4:5] op_sel_hi:[1,0,1]
	v_pk_add_f32 v[0:1], v[164:165], v[166:167] neg_lo:[0,1] neg_hi:[0,1]
	v_and_b32_e32 v153, 0xffff0000, v65
	v_pk_fma_f32 v[0:1], v[0:1], s[84:85], v[2:3] op_sel_hi:[1,0,1]
	ds_write_b64 v222, v[0:1] offset:38912
	s_waitcnt lgkmcnt(0)
	s_barrier
	ds_read2st64_b64 v[8:11], v191 offset0:76 offset1:77
	s_movk_i32 s25, 0x1000
	s_lshl_b64 s[58:59], s[64:65], 14
	s_waitcnt lgkmcnt(0)
	v_add_f32_e32 v8, 0, v8
	v_add_f32_e32 v9, 0, v9
	v_cndmask_b32_e64 v14, 0, v9, s[56:57]
	v_cndmask_b32_e64 v15, 0, v8, s[56:57]
	v_add_f32_e32 v146, v8, v10
	v_add_f32_e32 v147, v9, v11
	v_add_f32_e32 v8, v10, v15
	v_add_f32_e32 v9, v11, v14
	v_cndmask_b32_e64 v14, v14, v9, s[4:5]
	v_cndmask_b32_e64 v15, v15, v8, s[4:5]
	ds_read2st64_b64 v[8:11], v191 offset0:78 offset1:79
	s_waitcnt lgkmcnt(0)
	v_add_f32_e32 v146, v146, v8
	v_add_f32_e32 v147, v147, v9
	v_add_f32_e32 v8, v8, v15
	v_add_f32_e32 v9, v9, v14
	v_cndmask_b32_e64 v9, v14, v9, s[6:7]
	v_cndmask_b32_e64 v8, v15, v8, s[6:7]
	v_add_f32_e32 v14, v146, v10
	v_add_f32_e32 v15, v147, v11
	v_add_f32_e32 v10, v10, v8
	v_add_f32_e32 v11, v11, v9
	v_cndmask_b32_e64 v146, v9, v11, s[8:9]
	v_cndmask_b32_e64 v147, v8, v10, s[8:9]
	ds_read2st64_b64 v[8:11], v191 offset0:80 offset1:81
	s_waitcnt lgkmcnt(0)
	v_add_f32_e32 v14, v14, v8
	v_add_f32_e32 v15, v15, v9
	v_add_f32_e32 v8, v8, v147
	v_add_f32_e32 v9, v9, v146
	v_cndmask_b32_e64 v9, v146, v9, s[10:11]
	v_cndmask_b32_e64 v8, v147, v8, s[10:11]
	v_add_f32_e32 v14, v14, v10
	v_add_f32_e32 v15, v15, v11
	v_add_f32_e32 v10, v10, v8
	v_add_f32_e32 v11, v11, v9
	v_cndmask_b32_e64 v146, v9, v11, s[12:13]
	v_cndmask_b32_e64 v147, v8, v10, s[12:13]
	ds_read2st64_b64 v[8:11], v191 offset0:82 offset1:83
	s_waitcnt lgkmcnt(0)
	v_add_f32_e32 v14, v14, v8
	v_add_f32_e32 v15, v15, v9
	v_add_f32_e32 v8, v8, v147
	v_add_f32_e32 v9, v9, v146
	v_cndmask_b32_e64 v9, v146, v9, s[14:15]
	v_cndmask_b32_e64 v8, v147, v8, s[14:15]
	v_add_f32_e32 v14, v14, v10
	v_add_f32_e32 v15, v15, v11
	v_add_f32_e32 v10, v10, v8
	v_add_f32_e32 v11, v11, v9
	v_cndmask_b32_e64 v9, v9, v11, s[16:17]
	v_cndmask_b32_e64 v11, v8, v10, s[16:17]
	v_mul_f32_e32 v8, 0x3fb8aa3b, v14
	v_mul_f32_e32 v10, 0x3fb8aa3b, v15
	v_lshl_add_u64 v[14:15], s[62:63], 0, v[122:123]
	v_lshlrev_b64 v[14:15], 10, v[14:15]
	v_lshl_add_u64 v[14:15], s[68:69], 0, v[14:15]
	v_lshl_add_u64 v[14:15], v[14:15], 0, s[66:67]
	v_lshl_add_u64 v[148:149], v[14:15], 0, v[42:43]
	v_add_f32_e32 v14, v162, v11
	v_add_f32_e32 v15, v163, v9
	v_mul_f32_e32 v14, 0x3fb8aa3b, v14
	v_mul_f32_e32 v15, 0x3fb8aa3b, v15
	v_exp_f32_e32 v14, v14
	v_exp_f32_e32 v15, v15
	v_lshlrev_b32_e32 v146, 16, v63
	v_and_b32_e32 v147, 0xffff0000, v63
	v_rcp_f32_e32 v150, v14
	v_rcp_f32_e32 v151, v15
	v_pk_mul_f32 v[146:147], v[146:147], s[86:87] op_sel_hi:[1,0]
	v_exp_f32_e32 v8, v8
	v_pk_mul_f32 v[14:15], v[146:147], v[14:15]
	v_lshlrev_b32_e32 v146, 16, v67
	v_cvt_pk_bf16_f32 v160, v14, v15
	v_pk_mul_f32 v[14:15], v[150:151], v[152:153]
	v_and_b32_e32 v147, 0xffff0000, v67
	v_cvt_pk_bf16_f32 v161, v14, v15
	v_add_f32_e32 v14, v158, v11
	v_add_f32_e32 v15, v159, v9
	v_mul_f32_e32 v14, 0x3fb8aa3b, v14
	v_mul_f32_e32 v15, 0x3fb8aa3b, v15
	v_exp_f32_e32 v14, v14
	v_exp_f32_e32 v15, v15
	v_pk_mul_f32 v[146:147], v[146:147], s[86:87] op_sel_hi:[1,0]
	v_lshlrev_b32_e32 v158, 16, v73
	v_rcp_f32_e32 v154, v14
	v_rcp_f32_e32 v155, v15
	v_and_b32_e32 v159, 0xffff0000, v73
	v_pk_mul_f32 v[14:15], v[146:147], v[14:15]
	v_mov_b32_e32 v146, v150
	v_cvt_pk_bf16_f32 v162, v14, v15
	v_pk_mul_f32 v[14:15], v[154:155], v[158:159]
	v_mov_b32_e32 v147, v154
	v_mov_b32_e32 v154, v151
	v_add_f32_e32 v150, v156, v11
	v_add_f32_e32 v151, v157, v9
	v_mul_f32_e32 v150, 0x3fb8aa3b, v150
	v_mul_f32_e32 v151, 0x3fb8aa3b, v151
	v_exp_f32_e32 v10, v10
	v_exp_f32_e32 v150, v150
	v_exp_f32_e32 v151, v151
	v_cvt_pk_bf16_f32 v163, v14, v15
	v_mov_b32_e32 v14, v152
	v_mov_b32_e32 v15, v158
	v_pk_mul_f32 v[14:15], v[8:9], v[14:15] op_sel_hi:[0,1]
	v_mov_b32_e32 v158, v153
	v_add_f32_e32 v12, v12, v11
	v_add_f32_e32 v13, v13, v9
	v_pk_mul_f32 v[146:147], v[14:15], v[146:147]
	v_pk_mul_f32 v[14:15], v[10:11], v[158:159] op_sel_hi:[0,1]
	v_rcp_f32_e32 v152, v150
	v_rcp_f32_e32 v153, v151
	v_mul_f32_e32 v12, 0x3fb8aa3b, v12
	v_mul_f32_e32 v13, 0x3fb8aa3b, v13
	v_pk_mul_f32 v[14:15], v[14:15], v[154:155]
	v_lshlrev_b32_e32 v154, 16, v75
	v_and_b32_e32 v155, 0xffff0000, v75
	v_exp_f32_e32 v12, v12
	v_exp_f32_e32 v13, v13
	v_pk_mul_f32 v[154:155], v[154:155], s[86:87] op_sel_hi:[1,0]
	v_lshlrev_b32_e32 v156, 16, v77
	v_and_b32_e32 v157, 0xffff0000, v77
	v_pk_mul_f32 v[150:151], v[154:155], v[150:151]
	global_store_dword v[148:149], v160, off
	ds_write2_b32 v194, v160, v162 offset1:68
	v_cvt_pk_bf16_f32 v160, v150, v151
	v_pk_mul_f32 v[150:151], v[152:153], v[156:157]
	ds_write2_b32 v219, v161, v163 offset1:68
	v_cvt_pk_bf16_f32 v161, v150, v151
	v_rcp_f32_e32 v150, v12
	v_rcp_f32_e32 v151, v13
	v_lshlrev_b32_e32 v154, 16, v79
	v_and_b32_e32 v155, 0xffff0000, v79
	v_add_f32_e32 v6, v6, v11
	v_add_f32_e32 v7, v7, v9
	v_pk_mul_f32 v[154:155], v[154:155], s[86:87] op_sel_hi:[1,0]
	v_mul_f32_e32 v6, 0x3fb8aa3b, v6
	v_mul_f32_e32 v7, 0x3fb8aa3b, v7
	v_lshlrev_b32_e32 v158, 16, v81
	v_and_b32_e32 v159, 0xffff0000, v81
	v_pk_mul_f32 v[12:13], v[154:155], v[12:13]
	v_exp_f32_e32 v6, v6
	v_exp_f32_e32 v7, v7
	global_store_dword v[148:149], v162, off offset:1024
	v_cvt_pk_bf16_f32 v162, v12, v13
	v_pk_mul_f32 v[12:13], v[150:151], v[158:159]
	v_mov_b32_e32 v154, v152
	v_cvt_pk_bf16_f32 v163, v12, v13
	v_mov_b32_e32 v12, v156
	v_mov_b32_e32 v13, v158
	v_pk_mul_f32 v[12:13], v[8:9], v[12:13] op_sel_hi:[0,1]
	v_mov_b32_e32 v155, v150
	v_mov_b32_e32 v158, v157
	v_pk_mul_f32 v[12:13], v[12:13], v[154:155]
	v_pk_mul_f32 v[154:155], v[10:11], v[158:159] op_sel_hi:[0,1]
	v_mov_b32_e32 v150, v153
	v_rcp_f32_e32 v152, v6
	v_rcp_f32_e32 v153, v7
	v_add_f32_e32 v4, v4, v11
	v_add_f32_e32 v5, v5, v9
	v_pk_mul_f32 v[150:151], v[154:155], v[150:151]
	v_lshlrev_b32_e32 v154, 16, v83
	v_and_b32_e32 v155, 0xffff0000, v83
	v_mul_f32_e32 v4, 0x3fb8aa3b, v4
	v_mul_f32_e32 v5, 0x3fb8aa3b, v5
	v_pk_mul_f32 v[154:155], v[154:155], s[86:87] op_sel_hi:[1,0]
	v_exp_f32_e32 v4, v4
	v_exp_f32_e32 v5, v5
	v_lshlrev_b32_e32 v156, 16, v85
	v_and_b32_e32 v157, 0xffff0000, v85
	v_pk_mul_f32 v[6:7], v[154:155], v[6:7]
	global_store_dword v[148:149], v160, off offset:2048
	ds_write2_b32 v194, v160, v162 offset0:136 offset1:204
	ds_write2_b32 v219, v161, v163 offset0:136 offset1:204
	v_cvt_pk_bf16_f32 v160, v6, v7
	v_pk_mul_f32 v[6:7], v[152:153], v[156:157]
	global_store_dword v[148:149], v162, off offset:3072
	v_cvt_pk_bf16_f32 v161, v6, v7
	v_add_co_u32_e32 v6, vcc, s25, v148
	v_rcp_f32_e32 v148, v4
	s_nop 0
	v_addc_co_u32_e32 v7, vcc, 0, v149, vcc
	v_rcp_f32_e32 v149, v5
	v_lshlrev_b32_e32 v154, 16, v87
	v_and_b32_e32 v155, 0xffff0000, v87
	v_add_f32_e32 v2, v2, v11
	v_add_f32_e32 v3, v3, v9
	v_pk_mul_f32 v[154:155], v[154:155], s[86:87] op_sel_hi:[1,0]
	v_mul_f32_e32 v2, 0x3fb8aa3b, v2
	v_mul_f32_e32 v3, 0x3fb8aa3b, v3
	v_lshlrev_b32_e32 v158, 16, v89
	v_and_b32_e32 v159, 0xffff0000, v89
	v_pk_mul_f32 v[4:5], v[154:155], v[4:5]
	v_exp_f32_e32 v2, v2
	v_exp_f32_e32 v3, v3
	v_cvt_pk_bf16_f32 v162, v4, v5
	v_pk_mul_f32 v[4:5], v[148:149], v[158:159]
	v_mov_b32_e32 v154, v152
	v_cvt_pk_bf16_f32 v163, v4, v5
	v_mov_b32_e32 v4, v156
	v_mov_b32_e32 v5, v158
	v_pk_mul_f32 v[4:5], v[8:9], v[4:5] op_sel_hi:[0,1]
	v_mov_b32_e32 v155, v148
	v_mov_b32_e32 v158, v157
	v_add_f32_e32 v0, v0, v11
	v_add_f32_e32 v1, v1, v9
	v_pk_mul_f32 v[4:5], v[4:5], v[154:155]
	v_pk_mul_f32 v[154:155], v[10:11], v[158:159] op_sel_hi:[0,1]
	v_mov_b32_e32 v148, v153
	v_rcp_f32_e32 v152, v2
	v_rcp_f32_e32 v153, v3
	v_mul_f32_e32 v0, 0x3fb8aa3b, v0
	v_mul_f32_e32 v1, 0x3fb8aa3b, v1
	v_pk_mul_f32 v[148:149], v[154:155], v[148:149]
	v_lshlrev_b32_e32 v154, 16, v91
	v_and_b32_e32 v155, 0xffff0000, v91
	v_exp_f32_e32 v0, v0
	v_exp_f32_e32 v1, v1
	v_pk_mul_f32 v[154:155], v[154:155], s[86:87] op_sel_hi:[1,0]
	v_lshlrev_b32_e32 v156, 16, v93
	v_and_b32_e32 v157, 0xffff0000, v93
	v_pk_mul_f32 v[2:3], v[154:155], v[2:3]
	global_store_dword v[6:7], v160, off
	ds_write2_b32 v220, v160, v162 offset0:16 offset1:84
	v_cvt_pk_bf16_f32 v160, v2, v3
	v_pk_mul_f32 v[2:3], v[152:153], v[156:157]
	ds_write2_b32 v221, v161, v163 offset0:16 offset1:84
	v_cvt_pk_bf16_f32 v161, v2, v3
	v_rcp_f32_e32 v2, v0
	v_rcp_f32_e32 v3, v1
	v_lshlrev_b32_e32 v154, 16, v97
	v_and_b32_e32 v155, 0xffff0000, v97
	v_pk_mul_f32 v[154:155], v[154:155], s[86:87] op_sel_hi:[1,0]
	v_lshlrev_b32_e32 v158, 16, v101
	v_and_b32_e32 v159, 0xffff0000, v101
	v_pk_mul_f32 v[0:1], v[154:155], v[0:1]
	v_mov_b32_e32 v154, v152
	v_cvt_pk_bf16_f32 v9, v0, v1
	v_pk_mul_f32 v[0:1], v[2:3], v[158:159]
	v_mov_b32_e32 v155, v2
	v_cvt_pk_bf16_f32 v11, v0, v1
	v_mov_b32_e32 v0, v156
	v_mov_b32_e32 v1, v158
	v_pk_mul_f32 v[0:1], v[8:9], v[0:1] op_sel_hi:[0,1]
	v_mov_b32_e32 v158, v157
	v_pk_mul_f32 v[154:155], v[0:1], v[154:155]
	v_pk_mul_f32 v[0:1], v[10:11], v[158:159] op_sel_hi:[0,1]
	v_mov_b32_e32 v2, v153
	global_store_dword v[6:7], v162, off offset:1024
	global_store_dword v[6:7], v160, off offset:2048
	v_pk_mul_f32 v[152:153], v[0:1], v[2:3]
	ds_write2_b32 v220, v160, v9 offset0:152 offset1:220
	ds_write2_b32 v221, v161, v11 offset0:152 offset1:220
	global_store_dword v[6:7], v9, off offset:3072
	v_lshl_add_u64 v[6:7], v[56:57], 0, s[58:59]
	v_cvt_pk_bf16_f32 v0, v146, v147
	v_cvt_pk_bf16_f32 v1, v12, v13
	v_cvt_pk_bf16_f32 v2, v4, v5
	v_cvt_pk_bf16_f32 v3, v154, v155
	global_store_dwordx4 v[6:7], v[0:3], off
	s_nop 1
	v_cvt_pk_bf16_f32 v0, v14, v15
	v_cvt_pk_bf16_f32 v1, v150, v151
	v_cvt_pk_bf16_f32 v2, v148, v149
	v_cvt_pk_bf16_f32 v3, v152, v153
	global_store_dwordx4 v[6:7], v[0:3], off offset:128
	s_and_saveexec_b64 s[58:59], s[18:19]
	s_cbranch_execz .LBB0_767
	s_lshl_b64 s[62:63], s[64:65], 9
	v_lshl_add_u64 v[0:1], v[58:59], 0, s[62:63]
	v_mov_b32_e32 v9, v10
	global_store_dwordx2 v[0:1], v[8:9], off

.Lpw3_done:
	s_and_saveexec_b64 s[58:59], s[0:1]
	ds_write_b128 v192, v[20:23] offset:34816
	s_or_b64 exec, exec, s[58:59]
	s_waitcnt lgkmcnt(0)
	s_barrier
	ds_read_b128 v[162:165], v218 offset:34816
	ds_read_b128 v[166:169], v218 offset:34832
	ds_read_b128 v[170:173], v218 offset:34848
	ds_read_b128 v[174:177], v218 offset:34864
	s_ashr_i32 s58, s24, 9
	s_waitcnt lgkmcnt(3)
	v_mov_b32_e32 v178, v162
	s_waitcnt lgkmcnt(2)
	v_mov_b32_e32 v179, v166
	v_mov_b32_e32 v166, v163
	v_pk_mul_f32 v[162:163], v[160:161], v[166:167]
	v_mov_b32_e32 v180, v164
	v_mov_b32_e32 v181, v168
	v_mov_b32_e32 v168, v165
	v_pk_mul_f32 v[164:165], v[152:153], v[166:167]
	v_pk_fma_f32 v[162:163], v[158:159], v[178:179], v[162:163]
	v_pk_fma_f32 v[164:165], v[148:149], v[178:179], v[164:165]
	v_pk_fma_f32 v[162:163], v[156:157], v[180:181], v[162:163]
	v_pk_fma_f32 v[164:165], v[150:151], v[180:181], v[164:165]
	s_waitcnt lgkmcnt(0)
	v_mov_b32_e32 v167, v174
	v_mov_b32_e32 v174, v171
	v_pk_fma_f32 v[162:163], v[154:155], v[168:169], v[162:163]
	v_pk_fma_f32 v[164:165], v[146:147], v[168:169], v[164:165]
	v_mov_b32_e32 v166, v170
	v_pk_mul_f32 v[168:169], v[12:13], v[174:175]
	v_mov_b32_e32 v170, v172
	v_pk_fma_f32 v[168:169], v[10:11], v[166:167], v[168:169]
	v_mov_b32_e32 v171, v176
	v_pk_fma_f32 v[168:169], v[14:15], v[170:171], v[168:169]
	v_mov_b32_e32 v176, v173
	s_nop 0
	v_add_f32_e32 v162, v128, v162
	v_pk_fma_f32 v[168:169], v[8:9], v[176:177], v[168:169]
	v_add_f32_e32 v162, v162, v163
	v_add_f32_e32 v162, v162, v168
	v_add_f32_e32 v168, v162, v169
	v_pk_mul_f32 v[162:163], v[4:5], v[174:175]
	v_add_f32_e32 v164, v129, v164
	v_pk_fma_f32 v[162:163], v[2:3], v[166:167], v[162:163]
	v_add_f32_e32 v164, v164, v165
	v_pk_fma_f32 v[162:163], v[6:7], v[170:171], v[162:163]
	s_ashr_i32 s59, s58, 31
	v_pk_fma_f32 v[162:163], v[0:1], v[176:177], v[162:163]
	s_bfe_u32 s23, s24, 0x20001
	v_add_f32_e32 v162, v164, v162
	v_add_f32_e32 v165, v162, v163
	v_mul_f32_e64 v163, |v168|, s77
	v_exp_f32_e32 v163, v163
	s_bfe_u32 s66, s24, 0x60003
	s_lshl_b64 s[62:63], s[58:59], 12
	s_lshl_b64 s[58:59], s[58:59], 2
	v_add_f32_e32 v163, 1.0, v163
	v_cmp_gt_f32_e32 vcc, s87, v163
	v_readlane_b32 s64, v238, 18
	s_add_u32 s58, s58, s64
	v_cndmask_b32_e64 v164, 0, 32, vcc
	v_ldexp_f32 v163, v163, v164
	v_log_f32_e32 v163, v163
	s_addc_u32 s59, s59, 0
	s_or_b32 s58, s58, s23
	s_lshl_b64 s[64:65], s[58:59], 6
	v_mul_f32_e32 v164, 0x3f317217, v163
	v_fma_f32 v164, v163, s20, -v164
	v_fmac_f32_e32 v164, 0x3377d1cf, v163
	v_fmac_f32_e32 v164, 0x3f317217, v163
	v_cmp_lt_f32_e64 s[58:59], |v163|, s21
	v_min_f32_e32 v162, 0, v168
	s_or_b32 s64, s64, s66
	v_cndmask_b32_e64 v163, v163, v164, s[58:59]
	v_cndmask_b32_e32 v164, 0, v200, vcc
	v_sub_f32_e32 v164, v163, v164
	v_min_f32_e32 v163, 0, v165
	v_mul_f32_e64 v165, |v165|, s77
	v_exp_f32_e32 v165, v165
	s_nop 0
	v_add_f32_e32 v165, 1.0, v165
	v_cmp_gt_f32_e32 vcc, s87, v165
	s_nop 1
	v_cndmask_b32_e64 v166, 0, 32, vcc
	v_ldexp_f32 v165, v165, v166
	v_log_f32_e32 v165, v165
	s_nop 0
	v_mul_f32_e32 v166, 0x3f317217, v165
	v_fma_f32 v166, v165, s20, -v166
	v_fmac_f32_e32 v166, 0x3377d1cf, v165
	v_fmac_f32_e32 v166, 0x3f317217, v165
	v_cmp_lt_f32_e64 s[58:59], |v165|, s21
	s_nop 1
	v_cndmask_b32_e64 v165, v165, v166, s[58:59]
	v_cndmask_b32_e32 v166, 0, v200, vcc
	v_sub_f32_e32 v165, v165, v166
	ds_read_b128 v[166:169], v218 offset:34880
	ds_read_b128 v[170:173], v218 offset:34896
	s_waitcnt lgkmcnt(1)
	v_mov_b32_e32 v174, v166
	s_waitcnt lgkmcnt(0)
	v_mov_b32_e32 v175, v170
	v_mov_b32_e32 v170, v167
	v_pk_mul_f32 v[166:167], v[160:161], v[170:171]
	v_mov_b32_e32 v176, v168
	v_pk_fma_f32 v[166:167], v[158:159], v[174:175], v[166:167]
	v_mov_b32_e32 v177, v172
	v_pk_fma_f32 v[166:167], v[156:157], v[176:177], v[166:167]
	v_mov_b32_e32 v172, v169
	v_pk_fma_f32 v[178:179], v[154:155], v[172:173], v[166:167]
	v_pk_mul_f32 v[166:167], v[152:153], v[170:171]
	s_nop 0
	v_pk_fma_f32 v[166:167], v[148:149], v[174:175], v[166:167]
	s_nop 0
	v_pk_fma_f32 v[166:167], v[150:151], v[176:177], v[166:167]
	s_nop 0
	v_pk_fma_f32 v[174:175], v[146:147], v[172:173], v[166:167]
	ds_read_b128 v[166:169], v218 offset:34912
	ds_read_b128 v[170:173], v218 offset:34928
	s_waitcnt lgkmcnt(1)
	v_mov_b32_e32 v176, v166
	s_waitcnt lgkmcnt(0)
	v_mov_b32_e32 v177, v170
	v_mov_b32_e32 v170, v167
	v_pk_mul_f32 v[166:167], v[12:13], v[170:171]
	v_mov_b32_e32 v180, v168
	v_pk_fma_f32 v[166:167], v[10:11], v[176:177], v[166:167]
	v_mov_b32_e32 v181, v172
	v_pk_fma_f32 v[166:167], v[14:15], v[180:181], v[166:167]
	v_mov_b32_e32 v172, v169
	v_add_f32_e32 v168, v128, v178
	v_pk_fma_f32 v[166:167], v[8:9], v[172:173], v[166:167]
	v_add_f32_e32 v168, v168, v179
	v_add_f32_e32 v166, v168, v166
	v_add_f32_e32 v168, v166, v167
	v_pk_mul_f32 v[166:167], v[4:5], v[170:171]
	v_add_f32_e32 v169, v129, v174
	v_pk_fma_f32 v[166:167], v[2:3], v[176:177], v[166:167]
	v_add_f32_e32 v169, v169, v175
	v_pk_fma_f32 v[166:167], v[6:7], v[180:181], v[166:167]
	s_nop 0
	v_pk_fma_f32 v[166:167], v[0:1], v[172:173], v[166:167]
	s_nop 0
	v_add_f32_e32 v166, v169, v166
	v_add_f32_e32 v169, v166, v167
	v_mul_f32_e64 v167, |v168|, s77
	v_exp_f32_e32 v167, v167
	v_min_f32_e32 v166, 0, v168
	v_add_f32_e32 v167, 1.0, v167
	v_cmp_gt_f32_e32 vcc, s87, v167
	s_nop 1
	v_cndmask_b32_e64 v168, 0, 32, vcc
	v_ldexp_f32 v167, v167, v168
	v_log_f32_e32 v167, v167
	s_nop 0
	v_mul_f32_e32 v168, 0x3f317217, v167
	v_fma_f32 v168, v167, s20, -v168
	v_fmac_f32_e32 v168, 0x3377d1cf, v167
	v_fmac_f32_e32 v168, 0x3f317217, v167
	v_cmp_lt_f32_e64 s[58:59], |v167|, s21
	s_nop 1
	v_cndmask_b32_e64 v167, v167, v168, s[58:59]
	v_cndmask_b32_e32 v168, 0, v200, vcc
	v_sub_f32_e32 v168, v167, v168
	v_min_f32_e32 v167, 0, v169
	v_mul_f32_e64 v169, |v169|, s77
	v_exp_f32_e32 v169, v169
	s_nop 0
	v_add_f32_e32 v169, 1.0, v169
	v_cmp_gt_f32_e32 vcc, s87, v169
	s_nop 1
	v_cndmask_b32_e64 v170, 0, 32, vcc
	v_ldexp_f32 v169, v169, v170
	v_log_f32_e32 v169, v169
	s_nop 0
	v_mul_f32_e32 v170, 0x3f317217, v169
	v_fma_f32 v170, v169, s20, -v170
	v_fmac_f32_e32 v170, 0x3377d1cf, v169
	v_fmac_f32_e32 v170, 0x3f317217, v169
	v_cmp_lt_f32_e64 s[58:59], |v169|, s21
	s_nop 1
	v_cndmask_b32_e64 v169, v169, v170, s[58:59]
	v_cndmask_b32_e32 v170, 0, v200, vcc
	v_sub_f32_e32 v169, v169, v170
	ds_read_b128 v[170:173], v218 offset:34944
	ds_read_b128 v[174:177], v218 offset:34960
	s_waitcnt lgkmcnt(1)
	v_mov_b32_e32 v178, v170
	s_waitcnt lgkmcnt(0)
	v_mov_b32_e32 v179, v174
	v_mov_b32_e32 v174, v171
	v_pk_mul_f32 v[170:171], v[160:161], v[174:175]
	v_mov_b32_e32 v180, v172
	v_pk_fma_f32 v[170:171], v[158:159], v[178:179], v[170:171]
	v_mov_b32_e32 v181, v176
	v_pk_fma_f32 v[170:171], v[156:157], v[180:181], v[170:171]
	v_mov_b32_e32 v176, v173
	v_pk_fma_f32 v[182:183], v[154:155], v[176:177], v[170:171]
	v_pk_mul_f32 v[170:171], v[152:153], v[174:175]
	s_nop 0
	v_pk_fma_f32 v[170:171], v[148:149], v[178:179], v[170:171]
	s_nop 0
	v_pk_fma_f32 v[170:171], v[150:151], v[180:181], v[170:171]
	s_nop 0
	v_pk_fma_f32 v[178:179], v[146:147], v[176:177], v[170:171]
	ds_read_b128 v[170:173], v218 offset:34976
	ds_read_b128 v[174:177], v218 offset:34992
	s_waitcnt lgkmcnt(1)
	v_mov_b32_e32 v180, v170
	s_waitcnt lgkmcnt(0)
	v_mov_b32_e32 v181, v174
	v_mov_b32_e32 v174, v171
	v_pk_mul_f32 v[170:171], v[12:13], v[174:175]
	v_mov_b32_e32 v184, v172
	v_pk_fma_f32 v[170:171], v[10:11], v[180:181], v[170:171]
	v_mov_b32_e32 v185, v176
	v_pk_fma_f32 v[170:171], v[14:15], v[184:185], v[170:171]
	v_mov_b32_e32 v176, v173
	v_add_f32_e32 v172, v128, v182
	v_pk_fma_f32 v[170:171], v[8:9], v[176:177], v[170:171]
	v_add_f32_e32 v172, v172, v183
	v_add_f32_e32 v170, v172, v170
	v_add_f32_e32 v172, v170, v171
	v_pk_mul_f32 v[170:171], v[4:5], v[174:175]
	v_add_f32_e32 v173, v129, v178
	v_pk_fma_f32 v[170:171], v[2:3], v[180:181], v[170:171]
	v_add_f32_e32 v173, v173, v179
	v_pk_fma_f32 v[170:171], v[6:7], v[184:185], v[170:171]
	s_nop 0
	v_pk_fma_f32 v[170:171], v[0:1], v[176:177], v[170:171]
	s_nop 0
	v_add_f32_e32 v170, v173, v170
	v_add_f32_e32 v173, v170, v171
	v_mul_f32_e64 v171, |v172|, s77
	v_exp_f32_e32 v171, v171
	v_min_f32_e32 v170, 0, v172
	v_add_f32_e32 v171, 1.0, v171
	v_cmp_gt_f32_e32 vcc, s87, v171
	s_nop 1
	v_cndmask_b32_e64 v172, 0, 32, vcc
	v_ldexp_f32 v171, v171, v172
	v_log_f32_e32 v171, v171
	s_nop 0
	v_mul_f32_e32 v172, 0x3f317217, v171
	v_fma_f32 v172, v171, s20, -v172
	v_fmac_f32_e32 v172, 0x3377d1cf, v171
	v_fmac_f32_e32 v172, 0x3f317217, v171
	v_cmp_lt_f32_e64 s[58:59], |v171|, s21
	s_nop 1
	v_cndmask_b32_e64 v171, v171, v172, s[58:59]
	v_cndmask_b32_e32 v172, 0, v200, vcc
	v_sub_f32_e32 v172, v171, v172
	v_min_f32_e32 v171, 0, v173
	v_mul_f32_e64 v173, |v173|, s77
	v_exp_f32_e32 v173, v173
	s_nop 0
	v_add_f32_e32 v173, 1.0, v173
	v_cmp_gt_f32_e32 vcc, s87, v173
	s_nop 1
	v_cndmask_b32_e64 v174, 0, 32, vcc
	v_ldexp_f32 v173, v173, v174
	v_log_f32_e32 v173, v173
	s_nop 0
	v_mul_f32_e32 v174, 0x3f317217, v173
	v_fma_f32 v174, v173, s20, -v174
	v_fmac_f32_e32 v174, 0x3377d1cf, v173
	v_fmac_f32_e32 v174, 0x3f317217, v173
	v_cmp_lt_f32_e64 s[58:59], |v173|, s21
	s_nop 1
	v_cndmask_b32_e64 v173, v173, v174, s[58:59]
	v_cndmask_b32_e32 v174, 0, v200, vcc
	v_sub_f32_e32 v173, v173, v174
	ds_read_b128 v[174:177], v218 offset:35008
	ds_read_b128 v[178:181], v218 offset:35024
	s_waitcnt lgkmcnt(1)
	v_mov_b32_e32 v182, v174
	s_waitcnt lgkmcnt(0)
	v_mov_b32_e32 v183, v178
	v_mov_b32_e32 v178, v175
	v_pk_mul_f32 v[174:175], v[160:161], v[178:179]
	v_mov_b32_e32 v184, v176
	v_pk_fma_f32 v[174:175], v[158:159], v[182:183], v[174:175]
	v_mov_b32_e32 v185, v180
	v_pk_fma_f32 v[174:175], v[156:157], v[184:185], v[174:175]
	v_mov_b32_e32 v180, v177
	v_pk_fma_f32 v[186:187], v[154:155], v[180:181], v[174:175]
	v_pk_mul_f32 v[174:175], v[152:153], v[178:179]
	s_nop 0
	v_pk_fma_f32 v[174:175], v[148:149], v[182:183], v[174:175]
	s_nop 0
	v_pk_fma_f32 v[174:175], v[150:151], v[184:185], v[174:175]
	s_nop 0
	v_pk_fma_f32 v[182:183], v[146:147], v[180:181], v[174:175]
	ds_read_b128 v[174:177], v218 offset:35040
	ds_read_b128 v[178:181], v218 offset:35056
	s_waitcnt lgkmcnt(1)
	v_mov_b32_e32 v184, v174
	s_waitcnt lgkmcnt(0)
	v_mov_b32_e32 v185, v178
	v_mov_b32_e32 v178, v175
	v_pk_mul_f32 v[174:175], v[12:13], v[178:179]
	v_mov_b32_e32 v188, v176
	v_pk_fma_f32 v[174:175], v[10:11], v[184:185], v[174:175]
	v_mov_b32_e32 v189, v180
	v_pk_fma_f32 v[174:175], v[14:15], v[188:189], v[174:175]
	v_mov_b32_e32 v180, v177
	v_add_f32_e32 v176, v128, v186
	v_pk_fma_f32 v[174:175], v[8:9], v[180:181], v[174:175]
	v_add_f32_e32 v176, v176, v187
	v_add_f32_e32 v174, v176, v174
	v_add_f32_e32 v176, v174, v175
	v_pk_mul_f32 v[174:175], v[4:5], v[178:179]
	v_add_f32_e32 v177, v129, v182
	v_pk_fma_f32 v[174:175], v[2:3], v[184:185], v[174:175]
	v_add_f32_e32 v177, v177, v183
	v_pk_fma_f32 v[174:175], v[6:7], v[188:189], v[174:175]
	s_nop 0
	v_pk_fma_f32 v[174:175], v[0:1], v[180:181], v[174:175]
	s_nop 0
	v_add_f32_e32 v174, v177, v174
	v_add_f32_e32 v177, v174, v175
	v_mul_f32_e64 v175, |v176|, s77
	v_exp_f32_e32 v175, v175
	v_min_f32_e32 v174, 0, v176
	v_add_f32_e32 v175, 1.0, v175
	v_cmp_gt_f32_e32 vcc, s87, v175
	s_nop 1
	v_cndmask_b32_e64 v176, 0, 32, vcc
	v_ldexp_f32 v175, v175, v176
	v_log_f32_e32 v175, v175
	s_nop 0
	v_mul_f32_e32 v176, 0x3f317217, v175
	v_fma_f32 v176, v175, s20, -v176
	v_fmac_f32_e32 v176, 0x3377d1cf, v175
	v_fmac_f32_e32 v176, 0x3f317217, v175
	v_cmp_lt_f32_e64 s[58:59], |v175|, s21
	s_nop 1
	v_cndmask_b32_e64 v175, v175, v176, s[58:59]
	v_cndmask_b32_e32 v176, 0, v200, vcc
	v_sub_f32_e32 v176, v175, v176
	v_min_f32_e32 v175, 0, v177
	v_mul_f32_e64 v177, |v177|, s77
	v_exp_f32_e32 v177, v177
	s_nop 0
	v_add_f32_e32 v177, 1.0, v177
	v_cmp_gt_f32_e32 vcc, s87, v177
	s_nop 1
	v_cndmask_b32_e64 v178, 0, 32, vcc
	v_ldexp_f32 v177, v177, v178
	v_log_f32_e32 v177, v177
	s_nop 0
	v_mul_f32_e32 v178, 0x3f317217, v177
	v_fma_f32 v178, v177, s20, -v178
	v_fmac_f32_e32 v178, 0x3377d1cf, v177
	v_fmac_f32_e32 v178, 0x3f317217, v177
	v_cmp_lt_f32_e64 s[58:59], |v177|, s21
	s_nop 1
	v_cndmask_b32_e64 v177, v177, v178, s[58:59]
	v_cndmask_b32_e32 v178, 0, v200, vcc
	v_sub_f32_e32 v177, v177, v178
	ds_read_b128 v[178:181], v218 offset:35072
	ds_read_b128 v[182:185], v218 offset:35088
	s_waitcnt lgkmcnt(1)
	v_mov_b32_e32 v186, v178
	s_waitcnt lgkmcnt(0)
	v_mov_b32_e32 v187, v182
	v_mov_b32_e32 v182, v179
	v_pk_mul_f32 v[178:179], v[160:161], v[182:183]
	v_mov_b32_e32 v188, v180
	v_pk_fma_f32 v[178:179], v[158:159], v[186:187], v[178:179]
	v_mov_b32_e32 v189, v184
	v_pk_fma_f32 v[178:179], v[156:157], v[188:189], v[178:179]
	v_mov_b32_e32 v184, v181
	v_pk_fma_f32 v[224:225], v[154:155], v[184:185], v[178:179]
	v_pk_mul_f32 v[178:179], v[152:153], v[182:183]
	s_nop 0
	v_pk_fma_f32 v[178:179], v[148:149], v[186:187], v[178:179]
	s_nop 0
	v_pk_fma_f32 v[178:179], v[150:151], v[188:189], v[178:179]
	s_nop 0
	v_pk_fma_f32 v[186:187], v[146:147], v[184:185], v[178:179]
	ds_read_b128 v[178:181], v218 offset:35104
	ds_read_b128 v[182:185], v218 offset:35120
	s_waitcnt lgkmcnt(1)
	v_mov_b32_e32 v188, v178
	s_waitcnt lgkmcnt(0)
	v_mov_b32_e32 v189, v182
	v_mov_b32_e32 v182, v179
	v_pk_mul_f32 v[178:179], v[12:13], v[182:183]
	v_mov_b32_e32 v226, v180
	v_pk_fma_f32 v[178:179], v[10:11], v[188:189], v[178:179]
	v_mov_b32_e32 v227, v184
	v_pk_fma_f32 v[178:179], v[14:15], v[226:227], v[178:179]
	v_mov_b32_e32 v184, v181
	v_add_f32_e32 v180, v128, v224
	v_pk_fma_f32 v[178:179], v[8:9], v[184:185], v[178:179]
	v_add_f32_e32 v180, v180, v225
	v_add_f32_e32 v178, v180, v178
	v_add_f32_e32 v180, v178, v179
	v_pk_mul_f32 v[178:179], v[4:5], v[182:183]
	v_add_f32_e32 v181, v129, v186
	v_pk_fma_f32 v[178:179], v[2:3], v[188:189], v[178:179]
	v_add_f32_e32 v181, v181, v187
	v_pk_fma_f32 v[178:179], v[6:7], v[226:227], v[178:179]
	s_nop 0
	v_pk_fma_f32 v[178:179], v[0:1], v[184:185], v[178:179]
	s_nop 0
	v_add_f32_e32 v178, v181, v178
	v_add_f32_e32 v181, v178, v179
	v_mul_f32_e64 v179, |v180|, s77
	v_exp_f32_e32 v179, v179
	v_min_f32_e32 v178, 0, v180
	v_add_f32_e32 v179, 1.0, v179
	v_cmp_gt_f32_e32 vcc, s87, v179
	s_nop 1
	v_cndmask_b32_e64 v180, 0, 32, vcc
	v_ldexp_f32 v179, v179, v180
	v_log_f32_e32 v179, v179
	s_nop 0
	v_mul_f32_e32 v180, 0x3f317217, v179
	v_fma_f32 v180, v179, s20, -v180
	v_fmac_f32_e32 v180, 0x3377d1cf, v179
	v_fmac_f32_e32 v180, 0x3f317217, v179
	v_cmp_lt_f32_e64 s[58:59], |v179|, s21
	s_nop 1
	v_cndmask_b32_e64 v179, v179, v180, s[58:59]
	v_cndmask_b32_e32 v180, 0, v200, vcc
	v_sub_f32_e32 v180, v179, v180
	v_min_f32_e32 v179, 0, v181
	v_mul_f32_e64 v181, |v181|, s77
	v_exp_f32_e32 v181, v181
	s_nop 0
	v_add_f32_e32 v181, 1.0, v181
	v_cmp_gt_f32_e32 vcc, s87, v181
	s_nop 1
	v_cndmask_b32_e64 v182, 0, 32, vcc
	v_ldexp_f32 v181, v181, v182
	v_log_f32_e32 v181, v181
	s_nop 0
	v_mul_f32_e32 v182, 0x3f317217, v181
	v_fma_f32 v182, v181, s20, -v182
	v_fmac_f32_e32 v182, 0x3377d1cf, v181
	v_fmac_f32_e32 v182, 0x3f317217, v181
	v_cmp_lt_f32_e64 s[58:59], |v181|, s21
	s_nop 1
	v_cndmask_b32_e64 v181, v181, v182, s[58:59]
	v_cndmask_b32_e32 v182, 0, v200, vcc
	v_sub_f32_e32 v181, v181, v182
	ds_read_b128 v[182:185], v218 offset:35136
	ds_read_b128 v[186:189], v218 offset:35152
	s_waitcnt lgkmcnt(1)
	v_mov_b32_e32 v224, v182
	s_waitcnt lgkmcnt(0)
	v_mov_b32_e32 v225, v186
	v_mov_b32_e32 v186, v183
	v_pk_mul_f32 v[182:183], v[160:161], v[186:187]
	v_mov_b32_e32 v226, v184
	v_pk_fma_f32 v[182:183], v[158:159], v[224:225], v[182:183]
	v_mov_b32_e32 v227, v188
	v_pk_fma_f32 v[182:183], v[156:157], v[226:227], v[182:183]
	v_mov_b32_e32 v188, v185
	v_pk_fma_f32 v[228:229], v[154:155], v[188:189], v[182:183]
	v_pk_mul_f32 v[182:183], v[152:153], v[186:187]
	s_nop 0
	v_pk_fma_f32 v[182:183], v[148:149], v[224:225], v[182:183]
	s_nop 0
	v_pk_fma_f32 v[182:183], v[150:151], v[226:227], v[182:183]
	s_nop 0
	v_pk_fma_f32 v[224:225], v[146:147], v[188:189], v[182:183]
	ds_read_b128 v[182:185], v218 offset:35168
	ds_read_b128 v[186:189], v218 offset:35184
	s_waitcnt lgkmcnt(1)
	v_mov_b32_e32 v226, v182
	s_waitcnt lgkmcnt(0)
	v_mov_b32_e32 v227, v186
	v_mov_b32_e32 v186, v183
	v_pk_mul_f32 v[182:183], v[12:13], v[186:187]
	v_mov_b32_e32 v230, v184
	v_pk_fma_f32 v[182:183], v[10:11], v[226:227], v[182:183]
	v_mov_b32_e32 v231, v188
	v_pk_fma_f32 v[182:183], v[14:15], v[230:231], v[182:183]
	v_mov_b32_e32 v188, v185
	v_add_f32_e32 v184, v128, v228
	v_pk_fma_f32 v[182:183], v[8:9], v[188:189], v[182:183]
	v_add_f32_e32 v184, v184, v229
	v_add_f32_e32 v182, v184, v182
	v_add_f32_e32 v184, v182, v183
	v_pk_mul_f32 v[182:183], v[4:5], v[186:187]
	v_add_f32_e32 v185, v129, v224
	v_pk_fma_f32 v[182:183], v[2:3], v[226:227], v[182:183]
	v_add_f32_e32 v185, v185, v225
	v_pk_fma_f32 v[182:183], v[6:7], v[230:231], v[182:183]
	s_nop 0
	v_pk_fma_f32 v[182:183], v[0:1], v[188:189], v[182:183]
	s_nop 0
	v_add_f32_e32 v182, v185, v182
	v_add_f32_e32 v185, v182, v183
	v_mul_f32_e64 v183, |v184|, s77
	v_exp_f32_e32 v183, v183
	v_min_f32_e32 v182, 0, v184
	v_add_f32_e32 v183, 1.0, v183
	v_cmp_gt_f32_e32 vcc, s87, v183
	s_nop 1
	v_cndmask_b32_e64 v184, 0, 32, vcc
	v_ldexp_f32 v183, v183, v184
	v_log_f32_e32 v183, v183
	s_nop 0
	v_mul_f32_e32 v184, 0x3f317217, v183
	v_fma_f32 v184, v183, s20, -v184
	v_fmac_f32_e32 v184, 0x3377d1cf, v183
	v_fmac_f32_e32 v184, 0x3f317217, v183
	v_cmp_lt_f32_e64 s[58:59], |v183|, s21
	s_nop 1
	v_cndmask_b32_e64 v183, v183, v184, s[58:59]
	v_cndmask_b32_e32 v184, 0, v200, vcc
	v_sub_f32_e32 v184, v183, v184
	v_min_f32_e32 v183, 0, v185
	v_mul_f32_e64 v185, |v185|, s77
	v_exp_f32_e32 v185, v185
	s_nop 0
	v_add_f32_e32 v185, 1.0, v185
	v_cmp_gt_f32_e32 vcc, s87, v185
	s_nop 1
	v_cndmask_b32_e64 v186, 0, 32, vcc
	v_ldexp_f32 v185, v185, v186
	v_log_f32_e32 v185, v185
	s_nop 0
	v_mul_f32_e32 v186, 0x3f317217, v185
	v_fma_f32 v186, v185, s20, -v186
	v_fmac_f32_e32 v186, 0x3377d1cf, v185
	v_fmac_f32_e32 v186, 0x3f317217, v185
	v_cmp_lt_f32_e64 s[58:59], |v185|, s21
	s_nop 1
	v_cndmask_b32_e64 v185, v185, v186, s[58:59]
	v_cndmask_b32_e32 v186, 0, v200, vcc
	v_sub_f32_e32 v185, v185, v186
	ds_read_b128 v[186:189], v218 offset:35200
	ds_read_b128 v[224:227], v218 offset:35216
	s_waitcnt lgkmcnt(1)
	v_mov_b32_e32 v228, v186
	s_waitcnt lgkmcnt(0)
	v_mov_b32_e32 v229, v224
	v_mov_b32_e32 v224, v187
	v_pk_mul_f32 v[186:187], v[160:161], v[224:225]
	v_mov_b32_e32 v230, v188
	v_pk_fma_f32 v[186:187], v[158:159], v[228:229], v[186:187]
	v_mov_b32_e32 v231, v226
	v_pk_fma_f32 v[186:187], v[156:157], v[230:231], v[186:187]
	v_mov_b32_e32 v226, v189
	v_pk_fma_f32 v[232:233], v[154:155], v[226:227], v[186:187]
	v_pk_mul_f32 v[186:187], v[152:153], v[224:225]
	s_nop 0
	v_pk_fma_f32 v[186:187], v[148:149], v[228:229], v[186:187]
	s_nop 0
	v_pk_fma_f32 v[186:187], v[150:151], v[230:231], v[186:187]
	s_nop 0
	v_pk_fma_f32 v[228:229], v[146:147], v[226:227], v[186:187]
	ds_read_b128 v[186:189], v218 offset:35232
	ds_read_b128 v[224:227], v218 offset:35248
	s_waitcnt lgkmcnt(1)
	v_mov_b32_e32 v230, v186
	s_waitcnt lgkmcnt(0)
	v_mov_b32_e32 v231, v224
	v_mov_b32_e32 v224, v187
	v_pk_mul_f32 v[186:187], v[12:13], v[224:225]
	v_mov_b32_e32 v234, v188
	v_pk_fma_f32 v[186:187], v[10:11], v[230:231], v[186:187]
	v_mov_b32_e32 v235, v226
	v_pk_fma_f32 v[186:187], v[14:15], v[234:235], v[186:187]
	v_mov_b32_e32 v226, v189
	v_add_f32_e32 v188, v128, v232
	v_pk_fma_f32 v[186:187], v[8:9], v[226:227], v[186:187]
	v_add_f32_e32 v188, v188, v233
	v_add_f32_e32 v186, v188, v186
	v_add_f32_e32 v188, v186, v187
	v_pk_mul_f32 v[186:187], v[4:5], v[224:225]
	v_add_f32_e32 v189, v129, v228
	v_pk_fma_f32 v[186:187], v[2:3], v[230:231], v[186:187]
	v_add_f32_e32 v189, v189, v229
	v_pk_fma_f32 v[186:187], v[6:7], v[234:235], v[186:187]
	s_nop 0
	v_pk_fma_f32 v[186:187], v[0:1], v[226:227], v[186:187]
	ds_read_b128 v[224:227], v218 offset:35264
	ds_read_b128 v[228:231], v218 offset:35280
	v_add_f32_e32 v186, v189, v186
	v_add_f32_e32 v189, v186, v187
	v_mul_f32_e64 v187, |v188|, s77
	v_exp_f32_e32 v187, v187
	v_min_f32_e32 v186, 0, v188
	s_waitcnt lgkmcnt(0)
	v_mov_b32_e32 v233, v228
	v_mov_b32_e32 v228, v225
	v_add_f32_e32 v187, 1.0, v187
	v_cmp_gt_f32_e32 vcc, s87, v187
	v_mov_b32_e32 v232, v224
	v_pk_mul_f32 v[160:161], v[160:161], v[228:229]
	v_cndmask_b32_e64 v188, 0, 32, vcc
	v_ldexp_f32 v187, v187, v188
	v_log_f32_e32 v187, v187
	v_pk_mul_f32 v[152:153], v[152:153], v[228:229]
	v_pk_fma_f32 v[158:159], v[158:159], v[232:233], v[160:161]
	v_mov_b32_e32 v160, v226
	v_mul_f32_e32 v188, 0x3f317217, v187
	v_fma_f32 v188, v187, s20, -v188
	v_mov_b32_e32 v161, v230
	v_pk_fma_f32 v[148:149], v[148:149], v[232:233], v[152:153]
	v_fmac_f32_e32 v188, 0x3377d1cf, v187
	v_pk_fma_f32 v[156:157], v[156:157], v[160:161], v[158:159]
	v_mov_b32_e32 v230, v227
	v_pk_fma_f32 v[148:149], v[150:151], v[160:161], v[148:149]
	v_fmac_f32_e32 v188, 0x3f317217, v187
	v_cmp_lt_f32_e64 s[58:59], |v187|, s21
	v_pk_fma_f32 v[154:155], v[154:155], v[230:231], v[156:157]
	v_pk_fma_f32 v[156:157], v[146:147], v[230:231], v[148:149]
	ds_read_b128 v[146:149], v218 offset:35296
	ds_read_b128 v[150:153], v218 offset:35312
	v_cndmask_b32_e64 v187, v187, v188, s[58:59]
	v_cndmask_b32_e32 v188, 0, v200, vcc
	v_sub_f32_e32 v188, v187, v188
	v_min_f32_e32 v187, 0, v189
	v_mul_f32_e64 v189, |v189|, s77
	v_exp_f32_e32 v189, v189
	s_waitcnt lgkmcnt(0)
	v_mov_b32_e32 v159, v150
	v_mov_b32_e32 v150, v147
	v_mov_b32_e32 v158, v146
	v_pk_mul_f32 v[12:13], v[12:13], v[150:151]
	v_add_f32_e32 v189, 1.0, v189
	v_pk_fma_f32 v[10:11], v[10:11], v[158:159], v[12:13]
	v_mov_b32_e32 v12, v148
	v_mov_b32_e32 v13, v152
	v_pk_mul_f32 v[4:5], v[4:5], v[150:151]
	v_cmp_gt_f32_e32 vcc, s87, v189
	v_pk_fma_f32 v[10:11], v[14:15], v[12:13], v[10:11]
	v_mov_b32_e32 v152, v149
	v_pk_fma_f32 v[2:3], v[2:3], v[158:159], v[4:5]
	v_cndmask_b32_e64 v223, 0, 32, vcc
	v_pk_fma_f32 v[8:9], v[8:9], v[152:153], v[10:11]
	v_add_f32_e32 v10, v128, v154
	v_pk_fma_f32 v[2:3], v[6:7], v[12:13], v[2:3]
	v_ldexp_f32 v189, v189, v223
	v_add_f32_e32 v10, v10, v155
	v_pk_fma_f32 v[0:1], v[0:1], v[152:153], v[2:3]
	v_add_f32_e32 v2, v129, v156
	v_log_f32_e32 v189, v189
	v_add_f32_e32 v8, v10, v8
	v_add_f32_e32 v2, v2, v157
	v_add_f32_e32 v8, v8, v9
	v_add_f32_e32 v0, v2, v0
	v_add_f32_e32 v2, v0, v1
	v_mul_f32_e64 v1, |v8|, s77
	v_exp_f32_e32 v1, v1
	v_mul_f32_e32 v223, 0x3f317217, v189
	v_fma_f32 v223, v189, s20, -v223
	v_fmac_f32_e32 v223, 0x3377d1cf, v189
	v_fmac_f32_e32 v223, 0x3f317217, v189
	v_cmp_lt_f32_e64 s[58:59], |v189|, s21
	v_add_f32_e32 v1, 1.0, v1
	v_min_f32_e32 v0, 0, v8
	v_cndmask_b32_e64 v189, v189, v223, s[58:59]
	v_cndmask_b32_e32 v223, 0, v200, vcc
	v_cmp_gt_f32_e32 vcc, s87, v1
	v_sub_f32_e32 v189, v189, v223
	v_lshlrev_b32_e32 v154, 16, v202
	v_cndmask_b32_e64 v3, 0, 32, vcc
	v_ldexp_f32 v1, v1, v3
	v_log_f32_e32 v1, v1
	v_and_b32_e32 v155, 0xffff0000, v202
	v_pk_mul_f32 v[154:155], v[154:155], s[86:87] op_sel_hi:[1,0]
	v_lshlrev_b32_e32 v156, 16, v201
	v_mul_f32_e32 v3, 0x3f317217, v1
	v_fma_f32 v3, v1, s20, -v3
	v_fmac_f32_e32 v3, 0x3377d1cf, v1
	v_fmac_f32_e32 v3, 0x3f317217, v1
	v_cmp_lt_f32_e64 s[58:59], |v1|, s21
	v_and_b32_e32 v157, 0xffff0000, v201
	v_lshlrev_b32_e32 v158, 16, v203
	v_cndmask_b32_e64 v1, v1, v3, s[58:59]
	v_cndmask_b32_e32 v3, 0, v200, vcc
	v_sub_f32_e32 v8, v1, v3
	v_min_f32_e32 v1, 0, v2
	v_mul_f32_e64 v2, |v2|, s77
	v_exp_f32_e32 v2, v2
	v_and_b32_e32 v159, 0xffff0000, v203
	v_add_f32_e32 v2, 1.0, v2
	v_cmp_gt_f32_e32 vcc, s87, v2
	s_nop 1
	v_cndmask_b32_e64 v3, 0, 32, vcc
	v_ldexp_f32 v2, v2, v3
	v_log_f32_e32 v2, v2
	s_nop 0
	v_mul_f32_e32 v3, 0x3f317217, v2
	v_fma_f32 v3, v2, s20, -v3
	v_fmac_f32_e32 v3, 0x3377d1cf, v2
	v_fmac_f32_e32 v3, 0x3f317217, v2
	v_cmp_lt_f32_e64 s[58:59], |v2|, s21
	s_nop 1
	v_cndmask_b32_e64 v2, v2, v3, s[58:59]
	v_cndmask_b32_e32 v3, 0, v200, vcc
	v_sub_f32_e32 v9, v2, v3
	v_pk_add_f32 v[2:3], v[162:163], v[164:165] neg_lo:[0,1] neg_hi:[0,1]
	v_pk_add_f32 v[0:1], v[0:1], v[8:9] neg_lo:[0,1] neg_hi:[0,1]
	v_pk_fma_f32 v[148:149], v[2:3], s[84:85], 0 op_sel_hi:[1,0,0]
	v_pk_add_f32 v[2:3], v[166:167], v[168:169] neg_lo:[0,1] neg_hi:[0,1]
	s_lshl_b32 s58, s66, 6
	v_pk_fma_f32 v[146:147], v[2:3], s[84:85], v[148:149] op_sel_hi:[1,0,1]
	v_pk_add_f32 v[2:3], v[170:171], v[172:173] neg_lo:[0,1] neg_hi:[0,1]
	s_or_b32 s62, s62, s58
	v_pk_fma_f32 v[14:15], v[2:3], s[84:85], v[146:147] op_sel_hi:[1,0,1]
	v_pk_add_f32 v[2:3], v[174:175], v[176:177] neg_lo:[0,1] neg_hi:[0,1]
	s_lshl_b32 s66, s23, 8
	v_pk_fma_f32 v[12:13], v[2:3], s[84:85], v[14:15] op_sel_hi:[1,0,1]
	v_pk_add_f32 v[2:3], v[178:179], v[180:181] neg_lo:[0,1] neg_hi:[0,1]
	s_movk_i32 s23, 0x1000
	v_pk_fma_f32 v[6:7], v[2:3], s[84:85], v[12:13] op_sel_hi:[1,0,1]
	v_pk_add_f32 v[2:3], v[182:183], v[184:185] neg_lo:[0,1] neg_hi:[0,1]
	s_lshl_b64 s[58:59], s[64:65], 14
	v_pk_fma_f32 v[4:5], v[2:3], s[84:85], v[6:7] op_sel_hi:[1,0,1]
	v_pk_add_f32 v[2:3], v[186:187], v[188:189] neg_lo:[0,1] neg_hi:[0,1]
	s_nop 0
	v_pk_fma_f32 v[2:3], v[2:3], s[84:85], v[4:5] op_sel_hi:[1,0,1]
	s_nop 0
	v_pk_fma_f32 v[0:1], v[0:1], s[84:85], v[2:3] op_sel_hi:[1,0,1]
	ds_write_b64 v222, v[0:1] offset:38912
	s_waitcnt lgkmcnt(0)
	s_barrier
	ds_read2st64_b64 v[8:11], v191 offset0:76 offset1:77
	s_waitcnt lgkmcnt(0)
	v_add_f32_e32 v8, 0, v8
	v_add_f32_e32 v9, 0, v9
	v_cndmask_b32_e64 v150, 0, v9, s[56:57]
	v_cndmask_b32_e64 v151, 0, v8, s[56:57]
	v_add_f32_e32 v152, v8, v10
	v_add_f32_e32 v153, v9, v11
	v_add_f32_e32 v8, v10, v151
	v_add_f32_e32 v9, v11, v150
	v_cndmask_b32_e64 v150, v150, v9, s[4:5]
	v_cndmask_b32_e64 v151, v151, v8, s[4:5]
	ds_read2st64_b64 v[8:11], v191 offset0:78 offset1:79
	s_waitcnt lgkmcnt(0)
	v_add_f32_e32 v152, v152, v8
	v_add_f32_e32 v153, v153, v9
	v_add_f32_e32 v8, v8, v151
	v_add_f32_e32 v9, v9, v150
	v_cndmask_b32_e64 v9, v150, v9, s[6:7]
	v_cndmask_b32_e64 v8, v151, v8, s[6:7]
	v_add_f32_e32 v150, v152, v10
	v_add_f32_e32 v151, v153, v11
	v_add_f32_e32 v10, v10, v8
	v_add_f32_e32 v11, v11, v9
	v_cndmask_b32_e64 v152, v9, v11, s[8:9]
	v_cndmask_b32_e64 v153, v8, v10, s[8:9]
	ds_read2st64_b64 v[8:11], v191 offset0:80 offset1:81
	s_waitcnt lgkmcnt(0)
	v_add_f32_e32 v150, v150, v8
	v_add_f32_e32 v151, v151, v9
	v_add_f32_e32 v8, v8, v153
	v_add_f32_e32 v9, v9, v152
	v_cndmask_b32_e64 v9, v152, v9, s[10:11]
	v_cndmask_b32_e64 v8, v153, v8, s[10:11]
	v_add_f32_e32 v150, v150, v10
	v_add_f32_e32 v151, v151, v11
	v_add_f32_e32 v10, v10, v8
	v_add_f32_e32 v11, v11, v9
	v_cndmask_b32_e64 v152, v9, v11, s[12:13]
	v_cndmask_b32_e64 v153, v8, v10, s[12:13]
	ds_read2st64_b64 v[8:11], v191 offset0:82 offset1:83
	s_waitcnt lgkmcnt(0)
	v_add_f32_e32 v150, v150, v8
	v_add_f32_e32 v151, v151, v9
	v_add_f32_e32 v8, v8, v153
	v_add_f32_e32 v9, v9, v152
	v_cndmask_b32_e64 v9, v152, v9, s[14:15]
	v_cndmask_b32_e64 v8, v153, v8, s[14:15]
	v_add_f32_e32 v150, v150, v10
	v_add_f32_e32 v151, v151, v11
	v_add_f32_e32 v10, v10, v8
	v_add_f32_e32 v11, v11, v9
	v_cndmask_b32_e64 v9, v9, v11, s[16:17]
	v_cndmask_b32_e64 v11, v8, v10, s[16:17]
	v_add_f32_e32 v148, v148, v11
	v_add_f32_e32 v149, v149, v9
	v_mul_f32_e32 v148, 0x3fb8aa3b, v148
	v_mul_f32_e32 v149, 0x3fb8aa3b, v149
	v_exp_f32_e32 v148, v148
	v_exp_f32_e32 v149, v149
	v_add_f32_e32 v146, v146, v11
	v_add_f32_e32 v147, v147, v9
	v_mul_f32_e32 v146, 0x3fb8aa3b, v146
	v_mul_f32_e32 v147, 0x3fb8aa3b, v147
	v_rcp_f32_e32 v152, v148
	v_rcp_f32_e32 v153, v149
	v_exp_f32_e32 v146, v146
	v_exp_f32_e32 v147, v147
	v_pk_mul_f32 v[148:149], v[154:155], v[148:149]
	v_mul_f32_e32 v8, 0x3fb8aa3b, v150
	v_cvt_pk_bf16_f32 v160, v148, v149
	v_pk_mul_f32 v[148:149], v[152:153], v[156:157]
	v_rcp_f32_e32 v154, v146
	v_rcp_f32_e32 v155, v147
	v_cvt_pk_bf16_f32 v161, v148, v149
	v_lshlrev_b32_e32 v148, 16, v204
	v_and_b32_e32 v149, 0xffff0000, v204
	v_add_f32_e32 v14, v14, v11
	v_add_f32_e32 v15, v15, v9
	v_exp_f32_e32 v8, v8
	v_mul_f32_e32 v10, 0x3fb8aa3b, v151
	v_pk_mul_f32 v[148:149], v[148:149], s[86:87] op_sel_hi:[1,0]
	v_mul_f32_e32 v14, 0x3fb8aa3b, v14
	v_mul_f32_e32 v15, 0x3fb8aa3b, v15
	v_exp_f32_e32 v10, v10
	v_pk_mul_f32 v[146:147], v[148:149], v[146:147]
	v_exp_f32_e32 v14, v14
	v_exp_f32_e32 v15, v15
	v_cvt_pk_bf16_f32 v162, v146, v147
	v_pk_mul_f32 v[146:147], v[154:155], v[158:159]
	v_lshl_add_u64 v[150:151], s[62:63], 0, v[126:127]
	v_cvt_pk_bf16_f32 v163, v146, v147
	v_mov_b32_e32 v146, v156
	v_mov_b32_e32 v147, v158
	v_pk_mul_f32 v[146:147], v[8:9], v[146:147] op_sel_hi:[0,1]
	v_mov_b32_e32 v148, v152
	v_mov_b32_e32 v149, v154
	v_mov_b32_e32 v158, v157
	v_add_f32_e32 v12, v12, v11
	v_add_f32_e32 v13, v13, v9
	v_lshlrev_b64 v[150:151], 10, v[150:151]
	v_pk_mul_f32 v[148:149], v[146:147], v[148:149]
	v_pk_mul_f32 v[146:147], v[10:11], v[158:159] op_sel_hi:[0,1]
	v_mov_b32_e32 v154, v153
	v_rcp_f32_e32 v152, v14
	v_rcp_f32_e32 v153, v15
	v_mul_f32_e32 v12, 0x3fb8aa3b, v12
	v_mul_f32_e32 v13, 0x3fb8aa3b, v13
	v_lshl_add_u64 v[150:151], s[68:69], 0, v[150:151]
	v_pk_mul_f32 v[146:147], v[146:147], v[154:155]
	v_lshlrev_b32_e32 v154, 16, v206
	v_and_b32_e32 v155, 0xffff0000, v206
	v_exp_f32_e32 v12, v12
	v_exp_f32_e32 v13, v13
	v_lshl_add_u64 v[150:151], v[150:151], 0, s[66:67]
	v_pk_mul_f32 v[154:155], v[154:155], s[86:87] op_sel_hi:[1,0]
	v_lshl_add_u64 v[150:151], v[150:151], 0, v[42:43]
	v_lshlrev_b32_e32 v156, 16, v205
	v_and_b32_e32 v157, 0xffff0000, v205
	v_pk_mul_f32 v[14:15], v[154:155], v[14:15]
	global_store_dword v[150:151], v160, off
	ds_write2_b32 v194, v160, v162 offset1:68
	ds_write2_b32 v219, v161, v163 offset1:68
	v_cvt_pk_bf16_f32 v160, v14, v15
	v_pk_mul_f32 v[14:15], v[152:153], v[156:157]
	v_lshlrev_b32_e32 v154, 16, v207
	v_cvt_pk_bf16_f32 v161, v14, v15
	v_rcp_f32_e32 v14, v12
	v_rcp_f32_e32 v15, v13
	v_and_b32_e32 v155, 0xffff0000, v207
	v_add_f32_e32 v6, v6, v11
	v_add_f32_e32 v7, v7, v9
	v_pk_mul_f32 v[154:155], v[154:155], s[86:87] op_sel_hi:[1,0]
	v_mul_f32_e32 v6, 0x3fb8aa3b, v6
	v_mul_f32_e32 v7, 0x3fb8aa3b, v7
	v_lshlrev_b32_e32 v158, 16, v209
	v_and_b32_e32 v159, 0xffff0000, v209
	v_pk_mul_f32 v[12:13], v[154:155], v[12:13]
	v_exp_f32_e32 v6, v6
	v_exp_f32_e32 v7, v7
	global_store_dword v[150:151], v162, off offset:1024
	v_cvt_pk_bf16_f32 v162, v12, v13
	v_pk_mul_f32 v[12:13], v[14:15], v[158:159]
	v_mov_b32_e32 v154, v152
	v_cvt_pk_bf16_f32 v163, v12, v13
	v_mov_b32_e32 v12, v156
	v_mov_b32_e32 v13, v158
	v_pk_mul_f32 v[12:13], v[8:9], v[12:13] op_sel_hi:[0,1]
	v_mov_b32_e32 v155, v14
	v_mov_b32_e32 v158, v157
	v_pk_mul_f32 v[12:13], v[12:13], v[154:155]
	v_pk_mul_f32 v[154:155], v[10:11], v[158:159] op_sel_hi:[0,1]
	v_mov_b32_e32 v14, v153
	v_rcp_f32_e32 v152, v6
	v_rcp_f32_e32 v153, v7
	v_add_f32_e32 v4, v4, v11
	v_add_f32_e32 v5, v5, v9
	v_pk_mul_f32 v[14:15], v[154:155], v[14:15]
	v_lshlrev_b32_e32 v154, 16, v211
	v_and_b32_e32 v155, 0xffff0000, v211
	v_mul_f32_e32 v4, 0x3fb8aa3b, v4
	v_mul_f32_e32 v5, 0x3fb8aa3b, v5
	v_pk_mul_f32 v[154:155], v[154:155], s[86:87] op_sel_hi:[1,0]
	v_exp_f32_e32 v4, v4
	v_exp_f32_e32 v5, v5
	v_lshlrev_b32_e32 v156, 16, v210
	v_and_b32_e32 v157, 0xffff0000, v210
	v_pk_mul_f32 v[6:7], v[154:155], v[6:7]
	global_store_dword v[150:151], v160, off offset:2048
	ds_write2_b32 v194, v160, v162 offset0:136 offset1:204
	ds_write2_b32 v219, v161, v163 offset0:136 offset1:204
	v_cvt_pk_bf16_f32 v160, v6, v7
	v_pk_mul_f32 v[6:7], v[152:153], v[156:157]
	global_store_dword v[150:151], v162, off offset:3072
	v_cvt_pk_bf16_f32 v161, v6, v7
	v_add_co_u32_e32 v6, vcc, s23, v150
	v_rcp_f32_e32 v150, v4
	s_nop 0
	v_addc_co_u32_e32 v7, vcc, 0, v151, vcc
	v_rcp_f32_e32 v151, v5
	v_lshlrev_b32_e32 v154, 16, v213
	v_and_b32_e32 v155, 0xffff0000, v213
	v_add_f32_e32 v2, v2, v11
	v_add_f32_e32 v3, v3, v9
	v_pk_mul_f32 v[154:155], v[154:155], s[86:87] op_sel_hi:[1,0]
	v_mul_f32_e32 v2, 0x3fb8aa3b, v2
	v_mul_f32_e32 v3, 0x3fb8aa3b, v3
	v_lshlrev_b32_e32 v158, 16, v212
	v_and_b32_e32 v159, 0xffff0000, v212
	v_pk_mul_f32 v[4:5], v[154:155], v[4:5]
	v_exp_f32_e32 v2, v2
	v_exp_f32_e32 v3, v3
	v_cvt_pk_bf16_f32 v162, v4, v5
	v_pk_mul_f32 v[4:5], v[150:151], v[158:159]
	v_mov_b32_e32 v154, v152
	v_cvt_pk_bf16_f32 v163, v4, v5
	v_mov_b32_e32 v4, v156
	v_mov_b32_e32 v5, v158
	v_pk_mul_f32 v[4:5], v[8:9], v[4:5] op_sel_hi:[0,1]
	v_mov_b32_e32 v155, v150
	v_mov_b32_e32 v158, v157
	v_add_f32_e32 v0, v0, v11
	v_add_f32_e32 v1, v1, v9
	v_pk_mul_f32 v[4:5], v[4:5], v[154:155]
	v_pk_mul_f32 v[154:155], v[10:11], v[158:159] op_sel_hi:[0,1]
	v_mov_b32_e32 v150, v153
	v_rcp_f32_e32 v152, v2
	v_rcp_f32_e32 v153, v3
	v_mul_f32_e32 v0, 0x3fb8aa3b, v0
	v_mul_f32_e32 v1, 0x3fb8aa3b, v1
	v_pk_mul_f32 v[150:151], v[154:155], v[150:151]
	v_lshlrev_b32_e32 v154, 16, v215
	v_and_b32_e32 v155, 0xffff0000, v215
	v_exp_f32_e32 v0, v0
	v_exp_f32_e32 v1, v1
	v_pk_mul_f32 v[154:155], v[154:155], s[86:87] op_sel_hi:[1,0]
	v_lshlrev_b32_e32 v156, 16, v214
	v_and_b32_e32 v157, 0xffff0000, v214
	v_pk_mul_f32 v[2:3], v[154:155], v[2:3]
	global_store_dword v[6:7], v160, off
	ds_write2_b32 v220, v160, v162 offset0:16 offset1:84
	ds_write2_b32 v221, v161, v163 offset0:16 offset1:84
	v_cvt_pk_bf16_f32 v160, v2, v3
	v_pk_mul_f32 v[2:3], v[152:153], v[156:157]
	v_lshlrev_b32_e32 v154, 16, v216
	v_cvt_pk_bf16_f32 v161, v2, v3
	v_rcp_f32_e32 v2, v0
	v_rcp_f32_e32 v3, v1
	v_and_b32_e32 v155, 0xffff0000, v216
	v_pk_mul_f32 v[154:155], v[154:155], s[86:87] op_sel_hi:[1,0]
	v_lshlrev_b32_e32 v158, 16, v217
	v_and_b32_e32 v159, 0xffff0000, v217
	v_pk_mul_f32 v[0:1], v[154:155], v[0:1]
	v_mov_b32_e32 v154, v152
	v_cvt_pk_bf16_f32 v9, v0, v1
	v_pk_mul_f32 v[0:1], v[2:3], v[158:159]
	v_mov_b32_e32 v155, v2
	v_cvt_pk_bf16_f32 v11, v0, v1
	v_mov_b32_e32 v0, v156
	v_mov_b32_e32 v1, v158
	v_pk_mul_f32 v[0:1], v[8:9], v[0:1] op_sel_hi:[0,1]
	v_mov_b32_e32 v158, v157
	v_pk_mul_f32 v[154:155], v[0:1], v[154:155]
	v_pk_mul_f32 v[0:1], v[10:11], v[158:159] op_sel_hi:[0,1]
	v_mov_b32_e32 v2, v153
	global_store_dword v[6:7], v162, off offset:1024
	global_store_dword v[6:7], v160, off offset:2048
	v_pk_mul_f32 v[152:153], v[0:1], v[2:3]
	ds_write2_b32 v220, v160, v9 offset0:152 offset1:220
	ds_write2_b32 v221, v161, v11 offset0:152 offset1:220
	global_store_dword v[6:7], v9, off offset:3072
	v_lshl_add_u64 v[6:7], v[56:57], 0, s[58:59]
	v_cvt_pk_bf16_f32 v0, v148, v149
	v_cvt_pk_bf16_f32 v1, v12, v13
	v_cvt_pk_bf16_f32 v2, v4, v5
	v_cvt_pk_bf16_f32 v3, v154, v155
	global_store_dwordx4 v[6:7], v[0:3], off
	s_nop 1
	v_cvt_pk_bf16_f32 v0, v146, v147
	v_cvt_pk_bf16_f32 v1, v14, v15
	v_cvt_pk_bf16_f32 v2, v150, v151
	v_cvt_pk_bf16_f32 v3, v152, v153
	global_store_dwordx4 v[6:7], v[0:3], off offset:128
	s_and_saveexec_b64 s[58:59], s[18:19]
	s_cbranch_execz .LBB0_785
	s_lshl_b64 s[62:63], s[64:65], 9
	v_lshl_add_u64 v[0:1], v[58:59], 0, s[62:63]
	v_mov_b32_e32 v9, v10
	global_store_dwordx2 v[0:1], v[8:9], off
